# K loop: waves 0-3 raised; unit epilogue: waves 4-7 raised instead (alternating halves)
# baseline (speedup 1.0000x reference)
; template <class Epi>
; __device__ __forceinline__ void gemm_phase(LAS unsigned char* lds, const Gemm g, const StaticOrder& S, const Epi& E) {
;     ...
;     for (;;) {
;         const bool has_next = S.next(ui + 1, nxt);
;         const char* nA = has_next ? (const char*)g.A + (size_t)nxt.pm * tstepA : cA; const char* nB = has_next ? (const char*)g.Bt + (size_t)nxt.pn * tstepB : cB;
;         for (int t = 0; t < nt; t += 2) {
.LBB0_202:
	s_setprio 0
	v_readfirstlane_b32 s98, v152
	s_nop 3
	s_cmp_lt_u32 s98, 0x100
	s_cbranch_scc0 .Lknf0_skip
	s_setprio 1

; #define PG8_STAGE(bufoff, gbase, voff) do { _Pragma("unroll") for (int _i = 0; _i < 2; ++_i) \
;         __builtin_amdgcn_global_load_lds((const unsigned*)((const char*)(gbase) + (voff)[_i]), (LAS unsigned*)(lds + (bufoff) + ldsw + _i * 8192), 16, 0, 0); } while (0)
; #define PG8_LDA(dst, b, h) do { _Pragma("unroll") for (int m = 0; m < 4; ++m) _Pragma("unroll") for (int k = 0; k < 2; ++k) dst[m][k] = *(const LAS bf16x8*)(lds + PG8_SA(b, h) + aoff + m * 2048 + k * 1024); } while (0)
; #define PG8_LDB(dst, b, h) do { _Pragma("unroll") for (int n = 0; n < 2; ++n) _Pragma("unroll") for (int k = 0; k < 2; ++k) dst[n][k] = *(const LAS bf16x8*)(lds + PG8_SB(b, h) + boff + n * 2048 + k * 1024); } while (0)
; #define PG8_MMA(ai, bj, At, Bt) do { __builtin_amdgcn_s_setprio(1); _Pragma("unroll") for (int m = 0; m < 4; ++m) _Pragma("unroll") for (int n = 0; n < 2; ++n) _Pragma("unroll") for (int k = 0; k < 2; ++k) \
;         acc[ai][bj][m][n] = __builtin_amdgcn_mfma_f32_16x16x32_bf16(Bt[n][k], At[m][k], acc[ai][bj][m][n], 0, 0, 0); __builtin_amdgcn_s_setprio(0); } while (0)
; #define PG8_WAIT_V(n) asm volatile("s_waitcnt vmcnt(" #n ")" ::: "memory")
; #define PG8_WAIT_L(n) asm volatile("s_waitcnt lgkmcnt(" #n ")" ::: "memory")
; #define PG8_BAR __builtin_amdgcn_s_barrier()
; #define PG8_SCHED __builtin_amdgcn_sched_barrier(0)
; template <class Epi>
; __device__ __forceinline__ void gemm_phase(LAS unsigned char* lds, const Gemm g, const StaticOrder& S, const Epi& E) {
;     ...
;             PG8_LDB(B0, 0, 0); PG8_SCHED; PG8_LDA(At, 0, 0); PG8_STAGE(PG8_SA(1, 1), a1 + hstepA, voffA);
;             PG8_WAIT_L(8); PG8_BAR; PG8_WAIT_L(0); PG8_MMA(0, 0, At, B0); PG8_BAR; PG8_SCHED;
;             PG8_LDB(B1, 0, 1); PG8_STAGE(PG8_SB(0, 0), b2, voffB);
;             PG8_BAR; PG8_WAIT_L(0); PG8_MMA(0, 1, At, B1); PG8_BAR;
;             PG8_LDA(At, 0, 1); PG8_STAGE(PG8_SA(0, 0), a2, voffA);
;             PG8_BAR; PG8_WAIT_L(0); PG8_MMA(1, 0, At, B0); PG8_BAR; PG8_SCHED;
;             PG8_STAGE(PG8_SB(0, 1), b2 + hstepB, voffB);
;             PG8_WAIT_V(6); PG8_BAR; PG8_MMA(1, 1, At, B1); PG8_BAR;
.LBB0_205:
	ds_read_b128 v[146:149], v170
	ds_read_b128 v[154:157], v170 offset:1024
	ds_read_b128 v[158:161], v170 offset:2048
	ds_read_b128 v[162:165], v170 offset:3072
	s_add_u32 s22, s20, 0xfffc0080
	s_addc_u32 s23, s21, -1
	s_cmp_eq_u32 s47, 12
	s_cselect_b32 s25, s13, s23
	s_cselect_b32 s24, s19, s22
	s_cselect_b32 s23, s11, s46
	s_cselect_b32 s22, s44, s45
	v_lshl_add_u64 v[150:151], s[20:21], 0, v[138:139]
	s_add_i32 m0, s30, 0xc000
	ds_read_b128 v[174:177], v171
	ds_read_b128 v[178:181], v171 offset:1024
	ds_read_b128 v[182:185], v171 offset:2048
	ds_read_b128 v[186:189], v171 offset:3072
	ds_read_b128 v[190:193], v171 offset:4096
	ds_read_b128 v[194:197], v171 offset:5120
	ds_read_b128 v[198:201], v171 offset:6144
	ds_read_b128 v[202:205], v171 offset:7168
	global_load_lds_dwordx4 v[150:151], off
	v_lshl_add_u64 v[150:151], s[20:21], 0, v[140:141]
	s_add_i32 m0, s30, 0xe000
	s_nop 0
	global_load_lds_dwordx4 v[150:151], off
	s_waitcnt lgkmcnt(8)
	s_barrier
	s_waitcnt lgkmcnt(0)
	v_mfma_f32_16x16x32_bf16 v[76:79], v[146:149], v[174:177], v[76:79]
	v_mfma_f32_16x16x32_bf16 v[64:67], v[158:161], v[174:177], v[64:67]
	v_mfma_f32_16x16x32_bf16 v[60:63], v[146:149], v[182:185], v[60:63]
	v_mfma_f32_16x16x32_bf16 v[56:59], v[158:161], v[182:185], v[56:59]
	v_mfma_f32_16x16x32_bf16 v[48:51], v[146:149], v[190:193], v[48:51]
	v_mfma_f32_16x16x32_bf16 v[40:43], v[158:161], v[190:193], v[40:43]
	v_mfma_f32_16x16x32_bf16 v[36:39], v[146:149], v[198:201], v[36:39]
	v_mfma_f32_16x16x32_bf16 v[32:35], v[158:161], v[198:201], v[32:35]
	v_mfma_f32_16x16x32_bf16 v[76:79], v[154:157], v[178:181], v[76:79]
	v_mfma_f32_16x16x32_bf16 v[64:67], v[162:165], v[178:181], v[64:67]
	v_mfma_f32_16x16x32_bf16 v[60:63], v[154:157], v[186:189], v[60:63]
	v_mfma_f32_16x16x32_bf16 v[56:59], v[162:165], v[186:189], v[56:59]
	v_mfma_f32_16x16x32_bf16 v[48:51], v[154:157], v[194:197], v[48:51]
	v_mfma_f32_16x16x32_bf16 v[40:43], v[162:165], v[194:197], v[40:43]
	v_mfma_f32_16x16x32_bf16 v[36:39], v[154:157], v[202:205], v[36:39]
	v_mfma_f32_16x16x32_bf16 v[32:35], v[162:165], v[202:205], v[32:35]
	s_barrier
	s_add_i32 s48, s39, s27
	v_lshl_add_u64 v[150:151], s[22:23], 0, v[132:133]
	s_mov_b32 m0, s48
	ds_read_b128 v[206:209], v172
	ds_read_b128 v[210:213], v172 offset:1024
	ds_read_b128 v[214:217], v172 offset:2048
	ds_read_b128 v[218:221], v172 offset:3072
	global_load_lds_dwordx4 v[150:151], off
	v_lshl_add_u64 v[166:167], s[22:23], 0, v[128:129]
	s_add_i32 m0, s48, 0x2000
	s_nop 0
	global_load_lds_dwordx4 v[166:167], off
	s_barrier
	s_waitcnt lgkmcnt(0)
	v_mfma_f32_16x16x32_bf16 v[124:127], v[206:209], v[174:177], v[124:127]
	v_mfma_f32_16x16x32_bf16 v[120:123], v[214:217], v[174:177], v[120:123]
	v_mfma_f32_16x16x32_bf16 v[116:119], v[206:209], v[182:185], v[116:119]
	v_mfma_f32_16x16x32_bf16 v[112:115], v[214:217], v[182:185], v[112:115]
	v_mfma_f32_16x16x32_bf16 v[108:111], v[206:209], v[190:193], v[108:111]
	v_mfma_f32_16x16x32_bf16 v[104:107], v[214:217], v[190:193], v[104:107]
	v_mfma_f32_16x16x32_bf16 v[100:103], v[206:209], v[198:201], v[100:103]
	v_mfma_f32_16x16x32_bf16 v[96:99], v[214:217], v[198:201], v[96:99]
	v_mfma_f32_16x16x32_bf16 v[124:127], v[210:213], v[178:181], v[124:127]
	v_mfma_f32_16x16x32_bf16 v[120:123], v[218:221], v[178:181], v[120:123]
	v_mfma_f32_16x16x32_bf16 v[116:119], v[210:213], v[186:189], v[116:119]
	v_mfma_f32_16x16x32_bf16 v[112:115], v[218:221], v[186:189], v[112:115]
	v_mfma_f32_16x16x32_bf16 v[108:111], v[210:213], v[194:197], v[108:111]
	v_mfma_f32_16x16x32_bf16 v[104:107], v[218:221], v[194:197], v[104:107]
	v_mfma_f32_16x16x32_bf16 v[100:103], v[210:213], v[202:205], v[100:103]
	v_mfma_f32_16x16x32_bf16 v[96:99], v[218:221], v[202:205], v[96:99]
	s_mov_b32 m0, s30
	v_lshl_add_u64 v[222:223], s[24:25], 0, v[134:135]
	s_barrier
	ds_read_b128 v[174:177], v171 offset:16384
	ds_read_b128 v[178:181], v171 offset:17408
	ds_read_b128 v[182:185], v171 offset:18432
	ds_read_b128 v[186:189], v171 offset:19456
	ds_read_b128 v[190:193], v171 offset:20480
	ds_read_b128 v[194:197], v171 offset:21504
	ds_read_b128 v[198:201], v171 offset:22528
	ds_read_b128 v[202:205], v171 offset:23552
	global_load_lds_dwordx4 v[222:223], off
	v_lshl_add_u64 v[224:225], s[24:25], 0, v[130:131]
	s_mov_b32 m0, s31
	s_nop 0
	global_load_lds_dwordx4 v[224:225], off
	s_barrier
	s_waitcnt lgkmcnt(0)
	v_mfma_f32_16x16x32_bf16 v[28:31], v[146:149], v[174:177], v[28:31]
	v_mfma_f32_16x16x32_bf16 v[24:27], v[158:161], v[174:177], v[24:27]
	v_mfma_f32_16x16x32_bf16 v[20:23], v[146:149], v[182:185], v[20:23]
	v_mfma_f32_16x16x32_bf16 v[16:19], v[158:161], v[182:185], v[16:19]
	v_mfma_f32_16x16x32_bf16 v[12:15], v[146:149], v[190:193], v[12:15]
	v_mfma_f32_16x16x32_bf16 v[8:11], v[158:161], v[190:193], v[8:11]
	v_mfma_f32_16x16x32_bf16 v[4:7], v[146:149], v[198:201], v[4:7]
	v_mfma_f32_16x16x32_bf16 v[0:3], v[158:161], v[198:201], v[0:3]
	v_mfma_f32_16x16x32_bf16 v[28:31], v[154:157], v[178:181], v[28:31]
	v_mfma_f32_16x16x32_bf16 v[24:27], v[162:165], v[178:181], v[24:27]
	v_mfma_f32_16x16x32_bf16 v[20:23], v[154:157], v[186:189], v[20:23]
	v_mfma_f32_16x16x32_bf16 v[16:19], v[162:165], v[186:189], v[16:19]
	v_mfma_f32_16x16x32_bf16 v[12:15], v[154:157], v[194:197], v[12:15]
	v_mfma_f32_16x16x32_bf16 v[8:11], v[162:165], v[194:197], v[8:11]
	v_mfma_f32_16x16x32_bf16 v[4:7], v[154:157], v[202:205], v[4:7]
	v_mfma_f32_16x16x32_bf16 v[0:3], v[162:165], v[202:205], v[0:3]
	s_barrier
	s_add_u32 s48, s22, 0x40000
	s_addc_u32 s49, s23, 0
	s_add_i32 s50, s40, s27
	v_lshl_add_u64 v[146:147], s[48:49], 0, v[132:133]
	s_mov_b32 m0, s50
	s_nop 0
	global_load_lds_dwordx4 v[146:147], off
	v_lshl_add_u64 v[146:147], s[48:49], 0, v[128:129]
	s_add_i32 m0, s50, 0x2000
	s_nop 0
	global_load_lds_dwordx4 v[146:147], off
	s_waitcnt vmcnt(6)
	s_barrier
; #define PG8_STAGE(bufoff, gbase, voff) do { _Pragma("unroll") for (int _i = 0; _i < 2; ++_i) \
;         __builtin_amdgcn_global_load_lds((const unsigned*)((const char*)(gbase) + (voff)[_i]), (LAS unsigned*)(lds + (bufoff) + ldsw + _i * 8192), 16, 0, 0); } while (0)
; #define PG8_LDA(dst, b, h) do { _Pragma("unroll") for (int m = 0; m < 4; ++m) _Pragma("unroll") for (int k = 0; k < 2; ++k) dst[m][k] = *(const LAS bf16x8*)(lds + PG8_SA(b, h) + aoff + m * 2048 + k * 1024); } while (0)
; #define PG8_LDB(dst, b, h) do { _Pragma("unroll") for (int n = 0; n < 2; ++n) _Pragma("unroll") for (int k = 0; k < 2; ++k) dst[n][k] = *(const LAS bf16x8*)(lds + PG8_SB(b, h) + boff + n * 2048 + k * 1024); } while (0)
; #define PG8_MMA(ai, bj, At, Bt) do { __builtin_amdgcn_s_setprio(1); _Pragma("unroll") for (int m = 0; m < 4; ++m) _Pragma("unroll") for (int n = 0; n < 2; ++n) _Pragma("unroll") for (int k = 0; k < 2; ++k) \
;         acc[ai][bj][m][n] = __builtin_amdgcn_mfma_f32_16x16x32_bf16(Bt[n][k], At[m][k], acc[ai][bj][m][n], 0, 0, 0); __builtin_amdgcn_s_setprio(0); } while (0)
; #define PG8_WAIT_V(n) asm volatile("s_waitcnt vmcnt(" #n ")" ::: "memory")
; #define PG8_WAIT_L(n) asm volatile("s_waitcnt lgkmcnt(" #n ")" ::: "memory")
; #define PG8_BAR __builtin_amdgcn_s_barrier()
; #define PG8_SCHED __builtin_amdgcn_sched_barrier(0)
; template <class Epi>
; __device__ __forceinline__ void gemm_phase(LAS unsigned char* lds, const Gemm g, const StaticOrder& S, const Epi& E) {
;     ...
;             PG8_WAIT_V(6); PG8_BAR; PG8_MMA(1, 1, At, B1); PG8_BAR;
;             PG8_LDB(B0, 1, 0); PG8_SCHED; PG8_LDA(At, 1, 0); PG8_STAGE(PG8_SA(0, 1), a2 + hstepA, voffA);
;             PG8_WAIT_L(8); PG8_BAR; PG8_WAIT_L(0); PG8_MMA(0, 0, At, B0); PG8_BAR; PG8_SCHED;
;             PG8_LDB(B1, 1, 1); PG8_STAGE(PG8_SB(1, 0), b3, voffB);
;             PG8_BAR; PG8_WAIT_L(0); PG8_MMA(0, 1, At, B1); PG8_BAR;
;             PG8_LDA(At, 1, 1); PG8_STAGE(PG8_SA(1, 0), a3, voffA);
	v_mfma_f32_16x16x32_bf16 v[92:95], v[206:209], v[174:177], v[92:95]
	v_mfma_f32_16x16x32_bf16 v[88:91], v[214:217], v[174:177], v[88:91]
	v_mfma_f32_16x16x32_bf16 v[84:87], v[206:209], v[182:185], v[84:87]
	v_mfma_f32_16x16x32_bf16 v[80:83], v[214:217], v[182:185], v[80:83]
	v_mfma_f32_16x16x32_bf16 v[72:75], v[206:209], v[190:193], v[72:75]
	v_mfma_f32_16x16x32_bf16 v[68:71], v[214:217], v[190:193], v[68:71]
	v_mfma_f32_16x16x32_bf16 v[52:55], v[206:209], v[198:201], v[52:55]
	v_mfma_f32_16x16x32_bf16 v[44:47], v[214:217], v[198:201], v[44:47]
	v_mfma_f32_16x16x32_bf16 v[92:95], v[210:213], v[178:181], v[92:95]
	v_mfma_f32_16x16x32_bf16 v[88:91], v[218:221], v[178:181], v[88:91]
	v_mfma_f32_16x16x32_bf16 v[84:87], v[210:213], v[186:189], v[84:87]
	v_mfma_f32_16x16x32_bf16 v[80:83], v[218:221], v[186:189], v[80:83]
	v_mfma_f32_16x16x32_bf16 v[72:75], v[210:213], v[194:197], v[72:75]
	v_mfma_f32_16x16x32_bf16 v[68:71], v[218:221], v[194:197], v[68:71]
	v_mfma_f32_16x16x32_bf16 v[52:55], v[210:213], v[202:205], v[52:55]
	v_mfma_f32_16x16x32_bf16 v[44:47], v[218:221], v[202:205], v[44:47]
	s_add_i32 s48, 0, 0x18000
	v_add_u32_e32 v162, s48, v168
	s_barrier
	ds_read_b128 v[146:149], v162
	ds_read_b128 v[154:157], v162 offset:1024
	ds_read_b128 v[158:161], v162 offset:2048
	ds_read_b128 v[162:165], v162 offset:3072
	s_add_u32 s24, s24, 0x40000
	s_addc_u32 s25, s25, 0
	s_mov_b32 m0, s33
	v_lshl_add_u64 v[206:207], s[24:25], 0, v[134:135]
	ds_read_b128 v[174:177], v171 offset:32768
	ds_read_b128 v[178:181], v171 offset:33792
	ds_read_b128 v[182:185], v171 offset:34816
	ds_read_b128 v[186:189], v171 offset:35840
	ds_read_b128 v[190:193], v171 offset:36864
	ds_read_b128 v[194:197], v171 offset:37888
	ds_read_b128 v[198:201], v171 offset:38912
	ds_read_b128 v[202:205], v171 offset:39936
	global_load_lds_dwordx4 v[206:207], off
	v_lshl_add_u64 v[206:207], s[24:25], 0, v[130:131]
	s_mov_b32 m0, s34
	s_nop 0
	global_load_lds_dwordx4 v[206:207], off
	s_waitcnt lgkmcnt(8)
	s_barrier
	s_waitcnt lgkmcnt(0)
	v_mfma_f32_16x16x32_bf16 v[76:79], v[146:149], v[174:177], v[76:79]
	v_mfma_f32_16x16x32_bf16 v[64:67], v[158:161], v[174:177], v[64:67]
	v_mfma_f32_16x16x32_bf16 v[60:63], v[146:149], v[182:185], v[60:63]
	v_mfma_f32_16x16x32_bf16 v[56:59], v[158:161], v[182:185], v[56:59]
	v_mfma_f32_16x16x32_bf16 v[48:51], v[146:149], v[190:193], v[48:51]
	v_mfma_f32_16x16x32_bf16 v[40:43], v[158:161], v[190:193], v[40:43]
	v_mfma_f32_16x16x32_bf16 v[36:39], v[146:149], v[198:201], v[36:39]
	v_mfma_f32_16x16x32_bf16 v[32:35], v[158:161], v[198:201], v[32:35]
	v_mfma_f32_16x16x32_bf16 v[76:79], v[154:157], v[178:181], v[76:79]
	v_mfma_f32_16x16x32_bf16 v[64:67], v[162:165], v[178:181], v[64:67]
	v_mfma_f32_16x16x32_bf16 v[60:63], v[154:157], v[186:189], v[60:63]
	v_mfma_f32_16x16x32_bf16 v[56:59], v[162:165], v[186:189], v[56:59]
	v_mfma_f32_16x16x32_bf16 v[48:51], v[154:157], v[194:197], v[48:51]
	v_mfma_f32_16x16x32_bf16 v[40:43], v[162:165], v[194:197], v[40:43]
	v_mfma_f32_16x16x32_bf16 v[36:39], v[154:157], v[202:205], v[36:39]
	v_mfma_f32_16x16x32_bf16 v[32:35], v[162:165], v[202:205], v[32:35]
	s_barrier
	s_add_i32 s24, 0, 0x1c000
	s_add_i32 s25, s48, s27
	v_add_u32_e32 v218, s24, v168
	v_lshl_add_u64 v[150:151], v[150:151], 0, s[6:7]
	s_mov_b32 m0, s25
	ds_read_b128 v[206:209], v218
	ds_read_b128 v[210:213], v218 offset:1024
	ds_read_b128 v[214:217], v218 offset:2048
	ds_read_b128 v[218:221], v218 offset:3072
	global_load_lds_dwordx4 v[150:151], off
	v_lshl_add_u64 v[150:151], v[166:167], 0, s[6:7]
	s_add_i32 m0, s25, 0x2000
	s_nop 0
	global_load_lds_dwordx4 v[150:151], off
	s_barrier
	s_waitcnt lgkmcnt(0)
	v_mfma_f32_16x16x32_bf16 v[124:127], v[206:209], v[174:177], v[124:127]
	v_mfma_f32_16x16x32_bf16 v[120:123], v[214:217], v[174:177], v[120:123]
	v_mfma_f32_16x16x32_bf16 v[116:119], v[206:209], v[182:185], v[116:119]
	v_mfma_f32_16x16x32_bf16 v[112:115], v[214:217], v[182:185], v[112:115]
	v_mfma_f32_16x16x32_bf16 v[108:111], v[206:209], v[190:193], v[108:111]
	v_mfma_f32_16x16x32_bf16 v[104:107], v[214:217], v[190:193], v[104:107]
	v_mfma_f32_16x16x32_bf16 v[100:103], v[206:209], v[198:201], v[100:103]
	v_mfma_f32_16x16x32_bf16 v[96:99], v[214:217], v[198:201], v[96:99]
	v_mfma_f32_16x16x32_bf16 v[124:127], v[210:213], v[178:181], v[124:127]
	v_mfma_f32_16x16x32_bf16 v[120:123], v[218:221], v[178:181], v[120:123]
	v_mfma_f32_16x16x32_bf16 v[116:119], v[210:213], v[186:189], v[116:119]
	v_mfma_f32_16x16x32_bf16 v[112:115], v[218:221], v[186:189], v[112:115]
	v_mfma_f32_16x16x32_bf16 v[108:111], v[210:213], v[194:197], v[108:111]
	v_mfma_f32_16x16x32_bf16 v[104:107], v[218:221], v[194:197], v[104:107]
	v_mfma_f32_16x16x32_bf16 v[100:103], v[210:213], v[202:205], v[100:103]
	v_mfma_f32_16x16x32_bf16 v[96:99], v[218:221], v[202:205], v[96:99]
	s_mov_b32 m0, s36
	v_lshl_add_u64 v[150:151], v[222:223], 0, s[6:7]
	s_barrier
	ds_read_b128 v[174:177], v171 offset:49152
	ds_read_b128 v[178:181], v171 offset:50176
	ds_read_b128 v[182:185], v171 offset:51200
	ds_read_b128 v[186:189], v171 offset:52224
	ds_read_b128 v[190:193], v171 offset:53248
	ds_read_b128 v[194:197], v171 offset:54272
	ds_read_b128 v[198:201], v171 offset:55296
	ds_read_b128 v[202:205], v171 offset:56320
	global_load_lds_dwordx4 v[150:151], off
	v_lshl_add_u64 v[150:151], v[224:225], 0, s[6:7]
	s_mov_b32 m0, s37
	s_nop 0
	global_load_lds_dwordx4 v[150:151], off
	s_barrier
; __device__ __forceinline__ unsigned pk2(float lo, float hi) { const f32x2 v = (f32x2){lo, hi}; const bf16x2_t b = __builtin_convertvector(v, bf16x2_t); return __builtin_bit_cast(unsigned, b); }
; #define PG8_STAGE(bufoff, gbase, voff) do { _Pragma("unroll") for (int _i = 0; _i < 2; ++_i) \
;         __builtin_amdgcn_global_load_lds((const unsigned*)((const char*)(gbase) + (voff)[_i]), (LAS unsigned*)(lds + (bufoff) + ldsw + _i * 8192), 16, 0, 0); } while (0)
; #define PG8_MMA(ai, bj, At, Bt) do { __builtin_amdgcn_s_setprio(1); _Pragma("unroll") for (int m = 0; m < 4; ++m) _Pragma("unroll") for (int n = 0; n < 2; ++n) _Pragma("unroll") for (int k = 0; k < 2; ++k) \
;         acc[ai][bj][m][n] = __builtin_amdgcn_mfma_f32_16x16x32_bf16(Bt[n][k], At[m][k], acc[ai][bj][m][n], 0, 0, 0); __builtin_amdgcn_s_setprio(0); } while (0)
; #define PG8_WAIT_V(n) asm volatile("s_waitcnt vmcnt(" #n ")" ::: "memory")
; #define PG8_WAIT_L(n) asm volatile("s_waitcnt lgkmcnt(" #n ")" ::: "memory")
;     __device__ __forceinline__ void operator()(const f32x4 (&acc)[2][2][4][2], const Unit& u, int wr, int wc, int fr, int fq, const float (&)[8]) const {
;     ...
;         const int col0 = u.pn * BM + wc * 32 + 8 * fq;
; #pragma unroll
;         for (int ai = 0; ai < 2; ++ai)
; #pragma unroll
;             for (int m = 0; m < 4; ++m) { const int row = row0 + ai * HALF + m * 16; const float rs = rsqrtf(ep[ai * 4 + m] * (1.0f / 1024.0f) + EPS);
;                 u16* rowp = O + (size_t)row * ldc + col0;
; #pragma unroll
;                 for (int bj = 0; bj < 2; ++bj) { f32x4 v0 = acc[ai][bj][m][0] * rs, v1 = acc[ai][bj][m][1] * rs;
;                     if (ACT == 1) {
; #pragma unroll
;                         for (int j = 0; j < 4; ++j) { const float a0 = fmaxf(v0[j], 0.f), a1 = fmaxf(v1[j], 0.f); v0[j] = a0 * a0; v1[j] = a1 * a1; } }
;                     u32x4 w; w.x = pk2(v0[0], v0[1]); w.y = pk2(v0[2], v0[3]); w.z = pk2(v1[0], v1[1]); w.w = pk2(v1[2], v1[3]);
;                     *(u32x4*)(rowp + bj * HALF) = w; } }
; template <class Epi>
; __device__ __forceinline__ void gemm_phase(LAS unsigned char* lds, const Gemm g, const StaticOrder& S, const Epi& E) {
;     ...
;             PG8_BAR; PG8_WAIT_L(0); PG8_MMA(1, 0, At, B0); PG8_BAR; PG8_SCHED;
;             PG8_STAGE(PG8_SB(1, 1), b3 + hstepB, voffB);
;             PG8_WAIT_V(6); PG8_BAR; PG8_MMA(1, 1, At, B1); PG8_BAR;
	s_waitcnt lgkmcnt(0)
	v_mfma_f32_16x16x32_bf16 v[28:31], v[146:149], v[174:177], v[28:31]
	v_mfma_f32_16x16x32_bf16 v[24:27], v[158:161], v[174:177], v[24:27]
	v_mfma_f32_16x16x32_bf16 v[20:23], v[146:149], v[182:185], v[20:23]
	v_mfma_f32_16x16x32_bf16 v[16:19], v[158:161], v[182:185], v[16:19]
	v_mfma_f32_16x16x32_bf16 v[12:15], v[146:149], v[190:193], v[12:15]
	v_mfma_f32_16x16x32_bf16 v[8:11], v[158:161], v[190:193], v[8:11]
	v_mfma_f32_16x16x32_bf16 v[4:7], v[146:149], v[198:201], v[4:7]
	v_mfma_f32_16x16x32_bf16 v[0:3], v[158:161], v[198:201], v[0:3]
	v_mfma_f32_16x16x32_bf16 v[28:31], v[154:157], v[178:181], v[28:31]
	v_mfma_f32_16x16x32_bf16 v[24:27], v[162:165], v[178:181], v[24:27]
	v_mfma_f32_16x16x32_bf16 v[20:23], v[154:157], v[186:189], v[20:23]
	v_mfma_f32_16x16x32_bf16 v[16:19], v[162:165], v[186:189], v[16:19]
	v_mfma_f32_16x16x32_bf16 v[12:15], v[154:157], v[194:197], v[12:15]
	v_mfma_f32_16x16x32_bf16 v[8:11], v[162:165], v[194:197], v[8:11]
	v_mfma_f32_16x16x32_bf16 v[4:7], v[154:157], v[202:205], v[4:7]
	v_mfma_f32_16x16x32_bf16 v[0:3], v[162:165], v[202:205], v[0:3]
	s_barrier
	s_add_u32 s22, s22, 0x40080
	s_addc_u32 s23, s23, 0
	s_add_i32 s24, s24, s27
	v_lshl_add_u64 v[146:147], s[22:23], 0, v[132:133]
	s_mov_b32 m0, s24
	s_nop 0
	global_load_lds_dwordx4 v[146:147], off
	v_lshl_add_u64 v[146:147], s[22:23], 0, v[128:129]
	s_add_i32 m0, s24, 0x2000
	s_nop 0
	global_load_lds_dwordx4 v[146:147], off
	s_waitcnt vmcnt(6)
	s_barrier
	v_mfma_f32_16x16x32_bf16 v[92:95], v[206:209], v[174:177], v[92:95]
	v_mfma_f32_16x16x32_bf16 v[88:91], v[214:217], v[174:177], v[88:91]
	v_mfma_f32_16x16x32_bf16 v[84:87], v[206:209], v[182:185], v[84:87]
	v_mfma_f32_16x16x32_bf16 v[80:83], v[214:217], v[182:185], v[80:83]
	v_mfma_f32_16x16x32_bf16 v[72:75], v[206:209], v[190:193], v[72:75]
	v_mfma_f32_16x16x32_bf16 v[68:71], v[214:217], v[190:193], v[68:71]
	v_mfma_f32_16x16x32_bf16 v[52:55], v[206:209], v[198:201], v[52:55]
	v_mfma_f32_16x16x32_bf16 v[44:47], v[214:217], v[198:201], v[44:47]
	v_mfma_f32_16x16x32_bf16 v[92:95], v[210:213], v[178:181], v[92:95]
	v_mfma_f32_16x16x32_bf16 v[88:91], v[218:221], v[178:181], v[88:91]
	v_mfma_f32_16x16x32_bf16 v[84:87], v[210:213], v[186:189], v[84:87]
	v_mfma_f32_16x16x32_bf16 v[80:83], v[218:221], v[186:189], v[80:83]
	v_mfma_f32_16x16x32_bf16 v[72:75], v[210:213], v[194:197], v[72:75]
	v_mfma_f32_16x16x32_bf16 v[68:71], v[218:221], v[194:197], v[68:71]
	v_mfma_f32_16x16x32_bf16 v[52:55], v[210:213], v[202:205], v[52:55]
	v_mfma_f32_16x16x32_bf16 v[44:47], v[218:221], v[202:205], v[44:47]
	s_add_i32 s47, s47, 2
	s_add_u32 s20, s20, 0x100
	s_addc_u32 s21, s21, 0
	s_add_u32 s45, s45, 0x100
	s_addc_u32 s46, s46, 0
	s_cmp_gt_u32 s47, 13
	s_barrier
	s_cbranch_scc0 .LBB0_205
	s_setprio 0
	s_cmp_ge_u32 s98, 0x100
	s_cbranch_scc0 .Lep0_skip
	s_setprio 1
.Lep0_skip:
	s_bfe_u32 vcc_lo, s18, 0x20003
	s_lshl_b32 vcc_lo, vcc_lo, 10
	s_add_i32 vcc_lo, vcc_lo, 0x20010
	v_lshl_add_u32 v236, v153, 2, vcc_lo
	ds_read_b32 v228, v236
	ds_read_b32 v229, v236 offset:64
	ds_read_b32 v230, v236 offset:128
	ds_read_b32 v231, v236 offset:192
	ds_read_b32 v232, v236 offset:512
	ds_read_b32 v233, v236 offset:576
	ds_read_b32 v234, v236 offset:640
	ds_read_b32 v235, v236 offset:704
	s_waitcnt lgkmcnt(0)
	v_lshl_add_u32 v162, s18, 8, v153
	v_ashrrev_i32_e32 v163, 31, v162
	v_or_b32_e32 v160, 16, v162
	v_or_b32_e32 v158, 32, v162
	v_or_b32_e32 v156, 48, v162
	v_ashrrev_i32_e32 v161, 31, v160
	v_ashrrev_i32_e32 v159, 31, v158
	v_ashrrev_i32_e32 v157, 31, v156
	v_add_u32_e32 v154, 0x80, v162
	v_add_u32_e32 v150, 0x90, v162
	v_add_u32_e32 v148, 0xa0, v162
	v_add_u32_e32 v146, 0xb0, v162
	v_ashrrev_i32_e32 v155, 31, v154
	v_ashrrev_i32_e32 v151, 31, v150
	v_ashrrev_i32_e32 v149, 31, v148
	v_ashrrev_i32_e32 v147, 31, v146
	s_cmp_lg_u32 s43, 20
	s_mov_b64 s[18:19], -1
	s_cbranch_scc0 .LBB0_208
	s_waitcnt vmcnt(8)
	v_lshl_or_b32 v166, s43, 8, v169
	v_ashrrev_i32_e32 v167, 31, v166
	v_lshlrev_b64 v[166:167], 1, v[166:167]
	v_mov_b32_e32 v186, v228
	v_mov_b64_e32 v[164:165], s[96:97]
	v_mad_i64_i32 v[182:183], s[18:19], v162, s42, v[164:165]
	v_lshl_add_u64 v[188:189], v[182:183], 0, v[166:167]
	v_pk_mul_f32 v[184:185], v[78:79], v[186:187] op_sel_hi:[1,0]
	v_pk_mul_f32 v[182:183], v[76:77], v[186:187] op_sel_hi:[1,0]
	v_pk_mul_f32 v[190:191], v[66:67], v[186:187] op_sel_hi:[1,0]
	v_pk_mul_f32 v[192:193], v[64:65], v[186:187] op_sel_hi:[1,0]
	v_cvt_pk_bf16_f32 v182, v182, v183
	v_cvt_pk_bf16_f32 v183, v184, v185
	v_cvt_pk_bf16_f32 v184, v192, v193
	v_cvt_pk_bf16_f32 v185, v190, v191
	v_pk_mul_f32 v[124:125], v[124:125], v[186:187] op_sel_hi:[1,0]
	global_store_dwordx4 v[188:189], v[182:185], off
	v_pk_mul_f32 v[126:127], v[126:127], v[186:187] op_sel_hi:[1,0]
	s_nop 0
	v_pk_mul_f32 v[182:183], v[122:123], v[186:187] op_sel_hi:[1,0]
	v_pk_mul_f32 v[122:123], v[120:121], v[186:187] op_sel_hi:[1,0]
	v_cvt_pk_bf16_f32 v120, v124, v125
	v_cvt_pk_bf16_f32 v121, v126, v127
	v_cvt_pk_bf16_f32 v122, v122, v123
	v_cvt_pk_bf16_f32 v123, v182, v183
	global_store_dwordx4 v[188:189], v[120:123], off offset:256
	s_nop 1
	v_mov_b32_e32 v124, v229
	v_mad_i64_i32 v[120:121], s[18:19], v160, s42, v[164:165]
	v_lshl_add_u64 v[126:127], v[120:121], 0, v[166:167]
	v_pk_mul_f32 v[122:123], v[62:63], v[124:125] op_sel_hi:[1,0]
	v_pk_mul_f32 v[120:121], v[60:61], v[124:125] op_sel_hi:[1,0]
	v_pk_mul_f32 v[182:183], v[58:59], v[124:125] op_sel_hi:[1,0]
	v_pk_mul_f32 v[184:185], v[56:57], v[124:125] op_sel_hi:[1,0]
	v_cvt_pk_bf16_f32 v120, v120, v121
	v_cvt_pk_bf16_f32 v121, v122, v123
	v_cvt_pk_bf16_f32 v122, v184, v185
	v_cvt_pk_bf16_f32 v123, v182, v183
; __device__ __forceinline__ unsigned pk2(float lo, float hi) { const f32x2 v = (f32x2){lo, hi}; const bf16x2_t b = __builtin_convertvector(v, bf16x2_t); return __builtin_bit_cast(unsigned, b); }
;     __device__ __forceinline__ void operator()(const f32x4 (&acc)[2][2][4][2], const Unit& u, int wr, int wc, int fr, int fq, const float (&)[8]) const {
;     ...
;             for (int m = 0; m < 4; ++m) { const int row = row0 + ai * HALF + m * 16; const float rs = rsqrtf(ep[ai * 4 + m] * (1.0f / 1024.0f) + EPS);
;                 u16* rowp = O + (size_t)row * ldc + col0;
; #pragma unroll
;                 for (int bj = 0; bj < 2; ++bj) { f32x4 v0 = acc[ai][bj][m][0] * rs, v1 = acc[ai][bj][m][1] * rs;
;                     if (ACT == 1) {
; #pragma unroll
;                         for (int j = 0; j < 4; ++j) { const float a0 = fmaxf(v0[j], 0.f), a1 = fmaxf(v1[j], 0.f); v0[j] = a0 * a0; v1[j] = a1 * a1; } }
;                     u32x4 w; w.x = pk2(v0[0], v0[1]); w.y = pk2(v0[2], v0[3]); w.z = pk2(v1[0], v1[1]); w.w = pk2(v1[2], v1[3]);
;                     *(u32x4*)(rowp + bj * HALF) = w; } }
	v_pk_mul_f32 v[116:117], v[116:117], v[124:125] op_sel_hi:[1,0]
	global_store_dwordx4 v[126:127], v[120:123], off
	v_pk_mul_f32 v[118:119], v[118:119], v[124:125] op_sel_hi:[1,0]
	s_nop 0
	v_pk_mul_f32 v[120:121], v[114:115], v[124:125] op_sel_hi:[1,0]
	v_pk_mul_f32 v[114:115], v[112:113], v[124:125] op_sel_hi:[1,0]
	v_cvt_pk_bf16_f32 v112, v116, v117
	v_cvt_pk_bf16_f32 v113, v118, v119
	v_cvt_pk_bf16_f32 v114, v114, v115
	v_cvt_pk_bf16_f32 v115, v120, v121
	global_store_dwordx4 v[126:127], v[112:115], off offset:256
	s_nop 1
	v_mov_b32_e32 v116, v230
	v_mad_i64_i32 v[112:113], s[18:19], v158, s42, v[164:165]
	v_lshl_add_u64 v[118:119], v[112:113], 0, v[166:167]
	v_pk_mul_f32 v[114:115], v[50:51], v[116:117] op_sel_hi:[1,0]
	v_pk_mul_f32 v[112:113], v[48:49], v[116:117] op_sel_hi:[1,0]
	v_pk_mul_f32 v[120:121], v[42:43], v[116:117] op_sel_hi:[1,0]
	v_pk_mul_f32 v[122:123], v[40:41], v[116:117] op_sel_hi:[1,0]
	v_cvt_pk_bf16_f32 v112, v112, v113
	v_cvt_pk_bf16_f32 v113, v114, v115
	v_cvt_pk_bf16_f32 v114, v122, v123
	v_cvt_pk_bf16_f32 v115, v120, v121
	v_pk_mul_f32 v[108:109], v[108:109], v[116:117] op_sel_hi:[1,0]
	global_store_dwordx4 v[118:119], v[112:115], off
	v_pk_mul_f32 v[110:111], v[110:111], v[116:117] op_sel_hi:[1,0]
	s_nop 0
	v_pk_mul_f32 v[112:113], v[106:107], v[116:117] op_sel_hi:[1,0]
	v_pk_mul_f32 v[106:107], v[104:105], v[116:117] op_sel_hi:[1,0]
	v_cvt_pk_bf16_f32 v104, v108, v109
	v_cvt_pk_bf16_f32 v105, v110, v111
	v_cvt_pk_bf16_f32 v106, v106, v107
	v_cvt_pk_bf16_f32 v107, v112, v113
	global_store_dwordx4 v[118:119], v[104:107], off offset:256
	s_nop 1
	v_mov_b32_e32 v108, v231
	v_mad_i64_i32 v[104:105], s[18:19], v156, s42, v[164:165]
	v_lshl_add_u64 v[110:111], v[104:105], 0, v[166:167]
	v_pk_mul_f32 v[106:107], v[38:39], v[108:109] op_sel_hi:[1,0]
	v_pk_mul_f32 v[104:105], v[36:37], v[108:109] op_sel_hi:[1,0]
	v_pk_mul_f32 v[112:113], v[34:35], v[108:109] op_sel_hi:[1,0]
	v_pk_mul_f32 v[114:115], v[32:33], v[108:109] op_sel_hi:[1,0]
	v_cvt_pk_bf16_f32 v104, v104, v105
	v_cvt_pk_bf16_f32 v105, v106, v107
	v_cvt_pk_bf16_f32 v106, v114, v115
	v_cvt_pk_bf16_f32 v107, v112, v113
	v_pk_mul_f32 v[100:101], v[100:101], v[108:109] op_sel_hi:[1,0]
	global_store_dwordx4 v[110:111], v[104:107], off
	v_pk_mul_f32 v[102:103], v[102:103], v[108:109] op_sel_hi:[1,0]
	s_nop 0
	v_pk_mul_f32 v[104:105], v[98:99], v[108:109] op_sel_hi:[1,0]
	v_pk_mul_f32 v[98:99], v[96:97], v[108:109] op_sel_hi:[1,0]
	v_cvt_pk_bf16_f32 v96, v100, v101
	v_cvt_pk_bf16_f32 v97, v102, v103
	v_cvt_pk_bf16_f32 v98, v98, v99
	v_cvt_pk_bf16_f32 v99, v104, v105
	global_store_dwordx4 v[110:111], v[96:99], off offset:256
	s_nop 1
	v_mov_b32_e32 v100, v232
	v_mad_i64_i32 v[96:97], s[18:19], v154, s42, v[164:165]
	v_lshl_add_u64 v[102:103], v[96:97], 0, v[166:167]
	v_pk_mul_f32 v[98:99], v[30:31], v[100:101] op_sel_hi:[1,0]
	v_pk_mul_f32 v[96:97], v[28:29], v[100:101] op_sel_hi:[1,0]
	v_pk_mul_f32 v[104:105], v[26:27], v[100:101] op_sel_hi:[1,0]
	v_pk_mul_f32 v[106:107], v[24:25], v[100:101] op_sel_hi:[1,0]
	v_cvt_pk_bf16_f32 v96, v96, v97
	v_cvt_pk_bf16_f32 v97, v98, v99
	v_cvt_pk_bf16_f32 v98, v106, v107
	v_cvt_pk_bf16_f32 v99, v104, v105
	v_pk_mul_f32 v[92:93], v[92:93], v[100:101] op_sel_hi:[1,0]
	global_store_dwordx4 v[102:103], v[96:99], off
	v_pk_mul_f32 v[94:95], v[94:95], v[100:101] op_sel_hi:[1,0]
	s_nop 0
	v_pk_mul_f32 v[96:97], v[90:91], v[100:101] op_sel_hi:[1,0]
	v_pk_mul_f32 v[90:91], v[88:89], v[100:101] op_sel_hi:[1,0]
	v_cvt_pk_bf16_f32 v88, v92, v93
	v_cvt_pk_bf16_f32 v89, v94, v95
	v_cvt_pk_bf16_f32 v90, v90, v91
	v_cvt_pk_bf16_f32 v91, v96, v97
	global_store_dwordx4 v[102:103], v[88:91], off offset:256
	s_nop 1
	v_mov_b32_e32 v92, v233
	v_mad_i64_i32 v[88:89], s[18:19], v150, s42, v[164:165]
	v_lshl_add_u64 v[94:95], v[88:89], 0, v[166:167]
	v_pk_mul_f32 v[90:91], v[22:23], v[92:93] op_sel_hi:[1,0]
	v_pk_mul_f32 v[88:89], v[20:21], v[92:93] op_sel_hi:[1,0]
	v_pk_mul_f32 v[96:97], v[18:19], v[92:93] op_sel_hi:[1,0]
	v_pk_mul_f32 v[98:99], v[16:17], v[92:93] op_sel_hi:[1,0]
	v_cvt_pk_bf16_f32 v88, v88, v89
	v_cvt_pk_bf16_f32 v89, v90, v91
	v_cvt_pk_bf16_f32 v90, v98, v99
	v_cvt_pk_bf16_f32 v91, v96, v97
	v_pk_mul_f32 v[84:85], v[84:85], v[92:93] op_sel_hi:[1,0]
	global_store_dwordx4 v[94:95], v[88:91], off
	v_pk_mul_f32 v[86:87], v[86:87], v[92:93] op_sel_hi:[1,0]
	s_nop 0
	v_pk_mul_f32 v[88:89], v[82:83], v[92:93] op_sel_hi:[1,0]
	v_pk_mul_f32 v[82:83], v[80:81], v[92:93] op_sel_hi:[1,0]
	v_cvt_pk_bf16_f32 v80, v84, v85
	v_cvt_pk_bf16_f32 v81, v86, v87
	v_cvt_pk_bf16_f32 v82, v82, v83
	v_cvt_pk_bf16_f32 v83, v88, v89
	global_store_dwordx4 v[94:95], v[80:83], off offset:256
	s_nop 1
	v_mov_b32_e32 v84, v234
	v_mad_i64_i32 v[80:81], s[18:19], v148, s42, v[164:165]
	v_lshl_add_u64 v[86:87], v[80:81], 0, v[166:167]
	v_pk_mul_f32 v[82:83], v[14:15], v[84:85] op_sel_hi:[1,0]
	v_pk_mul_f32 v[80:81], v[12:13], v[84:85] op_sel_hi:[1,0]
	v_pk_mul_f32 v[88:89], v[10:11], v[84:85] op_sel_hi:[1,0]
	v_pk_mul_f32 v[90:91], v[8:9], v[84:85] op_sel_hi:[1,0]
	v_cvt_pk_bf16_f32 v80, v80, v81
	v_cvt_pk_bf16_f32 v81, v82, v83
	v_cvt_pk_bf16_f32 v82, v90, v91
	v_cvt_pk_bf16_f32 v83, v88, v89
	v_pk_mul_f32 v[72:73], v[72:73], v[84:85] op_sel_hi:[1,0]
	global_store_dwordx4 v[86:87], v[80:83], off
	v_pk_mul_f32 v[74:75], v[74:75], v[84:85] op_sel_hi:[1,0]
	s_nop 0
	v_pk_mul_f32 v[80:81], v[70:71], v[84:85] op_sel_hi:[1,0]
	v_pk_mul_f32 v[70:71], v[68:69], v[84:85] op_sel_hi:[1,0]
	v_cvt_pk_bf16_f32 v68, v72, v73
	v_cvt_pk_bf16_f32 v69, v74, v75
	v_cvt_pk_bf16_f32 v70, v70, v71
	v_cvt_pk_bf16_f32 v71, v80, v81
	global_store_dwordx4 v[86:87], v[68:71], off offset:256
	s_nop 1
	v_mov_b32_e32 v72, v235
	v_mad_i64_i32 v[68:69], s[18:19], v146, s42, v[164:165]
	v_lshl_add_u64 v[74:75], v[68:69], 0, v[166:167]
	v_pk_mul_f32 v[70:71], v[6:7], v[72:73] op_sel_hi:[1,0]
	v_pk_mul_f32 v[68:69], v[4:5], v[72:73] op_sel_hi:[1,0]
	v_pk_mul_f32 v[80:81], v[2:3], v[72:73] op_sel_hi:[1,0]
	v_pk_mul_f32 v[82:83], v[0:1], v[72:73] op_sel_hi:[1,0]
	v_cvt_pk_bf16_f32 v68, v68, v69
	v_cvt_pk_bf16_f32 v69, v70, v71
	v_cvt_pk_bf16_f32 v70, v82, v83
	v_cvt_pk_bf16_f32 v71, v80, v81
	global_store_dwordx4 v[74:75], v[68:71], off
	v_pk_mul_f32 v[54:55], v[54:55], v[72:73] op_sel_hi:[1,0]
	v_pk_mul_f32 v[52:53], v[52:53], v[72:73] op_sel_hi:[1,0]
	v_pk_mul_f32 v[68:69], v[46:47], v[72:73] op_sel_hi:[1,0]
	v_pk_mul_f32 v[46:47], v[44:45], v[72:73] op_sel_hi:[1,0]
	v_cvt_pk_bf16_f32 v44, v52, v53
	v_cvt_pk_bf16_f32 v45, v54, v55
	v_cvt_pk_bf16_f32 v46, v46, v47
	v_cvt_pk_bf16_f32 v47, v68, v69
	global_store_dwordx4 v[74:75], v[44:47], off offset:256
	s_mov_b64 s[18:19], 0

; #define PG8_STAGE(bufoff, gbase, voff) do { _Pragma("unroll") for (int _i = 0; _i < 2; ++_i) \
;         __builtin_amdgcn_global_load_lds((const unsigned*)((const char*)(gbase) + (voff)[_i]), (LAS unsigned*)(lds + (bufoff) + ldsw + _i * 8192), 16, 0, 0); } while (0)
; #define PG8_LDA(dst, b, h) do { _Pragma("unroll") for (int m = 0; m < 4; ++m) _Pragma("unroll") for (int k = 0; k < 2; ++k) dst[m][k] = *(const LAS bf16x8*)(lds + PG8_SA(b, h) + aoff + m * 2048 + k * 1024); } while (0)
; #define PG8_LDB(dst, b, h) do { _Pragma("unroll") for (int n = 0; n < 2; ++n) _Pragma("unroll") for (int k = 0; k < 2; ++k) dst[n][k] = *(const LAS bf16x8*)(lds + PG8_SB(b, h) + boff + n * 2048 + k * 1024); } while (0)
; #define PG8_MMA(ai, bj, At, Bt) do { __builtin_amdgcn_s_setprio(1); _Pragma("unroll") for (int m = 0; m < 4; ++m) _Pragma("unroll") for (int n = 0; n < 2; ++n) _Pragma("unroll") for (int k = 0; k < 2; ++k) \
;         acc[ai][bj][m][n] = __builtin_amdgcn_mfma_f32_16x16x32_bf16(Bt[n][k], At[m][k], acc[ai][bj][m][n], 0, 0, 0); __builtin_amdgcn_s_setprio(0); } while (0)
; #define PG8_WAIT_V(n) asm volatile("s_waitcnt vmcnt(" #n ")" ::: "memory")
; #define PG8_WAIT_L(n) asm volatile("s_waitcnt lgkmcnt(" #n ")" ::: "memory")
; #define PG8_BAR __builtin_amdgcn_s_barrier()
; #define PG8_SCHED __builtin_amdgcn_sched_barrier(0)
; template <class Epi>
; __device__ __forceinline__ void gemm_phase(LAS unsigned char* lds, const Gemm g, const StaticOrder& S, const Epi& E) {
;     ...
;             PG8_LDB(B0, 0, 0); PG8_SCHED; PG8_LDA(At, 0, 0); PG8_STAGE(PG8_SA(1, 1), a1 + hstepA, voffA);
;             PG8_WAIT_L(8); PG8_BAR; PG8_WAIT_L(0); PG8_MMA(0, 0, At, B0); PG8_BAR; PG8_SCHED;
;             PG8_LDB(B1, 0, 1); PG8_STAGE(PG8_SB(0, 0), b2, voffB);
;             PG8_BAR; PG8_WAIT_L(0); PG8_MMA(0, 1, At, B1); PG8_BAR;
;             PG8_LDA(At, 0, 1); PG8_STAGE(PG8_SA(0, 0), a2, voffA);
;             PG8_BAR; PG8_WAIT_L(0); PG8_MMA(1, 0, At, B0); PG8_BAR; PG8_SCHED;
;             PG8_STAGE(PG8_SB(0, 1), b2 + hstepB, voffB);
;             PG8_WAIT_V(6); PG8_BAR; PG8_MMA(1, 1, At, B1); PG8_BAR;
.LBB0_684:
	ds_read_b128 v[128:131], v191
	ds_read_b128 v[132:135], v191 offset:1024
	ds_read_b128 v[136:139], v191 offset:2048
	ds_read_b128 v[140:143], v191 offset:3072
	s_add_u32 s22, s4, 0xffec0080
	s_addc_u32 s23, s5, -1
	s_cmp_eq_u32 s48, 28
	s_cselect_b32 s25, s19, s23
	s_cselect_b32 s24, s18, s22
	s_cselect_b32 s23, s17, s47
	s_cselect_b32 s22, s45, s46
	v_lshl_add_u64 v[186:187], s[4:5], 0, v[162:163]
	s_add_i32 m0, s11, 0xc000
	ds_read_b128 v[144:147], v192
	ds_read_b128 v[148:151], v192 offset:1024
	ds_read_b128 v[170:173], v192 offset:2048
	ds_read_b128 v[174:177], v192 offset:3072
	ds_read_b128 v[178:181], v192 offset:4096
	ds_read_b128 v[182:185], v192 offset:5120
	ds_read_b128 v[196:199], v192 offset:6144
	ds_read_b128 v[200:203], v192 offset:7168
	global_load_lds_dwordx4 v[186:187], off
	v_lshl_add_u64 v[186:187], s[4:5], 0, v[164:165]
	s_add_i32 m0, s11, 0xe000
	s_nop 0
	global_load_lds_dwordx4 v[186:187], off
	s_waitcnt lgkmcnt(8)
	s_barrier
	s_waitcnt lgkmcnt(0)
	v_mfma_f32_16x16x32_bf16 v[124:127], v[128:131], v[144:147], v[124:127]
	v_mfma_f32_16x16x32_bf16 v[120:123], v[136:139], v[144:147], v[120:123]
	v_mfma_f32_16x16x32_bf16 v[108:111], v[128:131], v[170:173], v[108:111]
	v_mfma_f32_16x16x32_bf16 v[104:107], v[136:139], v[170:173], v[104:107]
	v_mfma_f32_16x16x32_bf16 v[92:95], v[128:131], v[178:181], v[92:95]
	v_mfma_f32_16x16x32_bf16 v[88:91], v[136:139], v[178:181], v[88:91]
	v_mfma_f32_16x16x32_bf16 v[76:79], v[128:131], v[196:199], v[76:79]
	v_mfma_f32_16x16x32_bf16 v[72:75], v[136:139], v[196:199], v[72:75]
	v_mfma_f32_16x16x32_bf16 v[124:127], v[132:135], v[148:151], v[124:127]
	v_mfma_f32_16x16x32_bf16 v[120:123], v[140:143], v[148:151], v[120:123]
	v_mfma_f32_16x16x32_bf16 v[108:111], v[132:135], v[174:177], v[108:111]
	v_mfma_f32_16x16x32_bf16 v[104:107], v[140:143], v[174:177], v[104:107]
	v_mfma_f32_16x16x32_bf16 v[92:95], v[132:135], v[182:185], v[92:95]
	v_mfma_f32_16x16x32_bf16 v[88:91], v[140:143], v[182:185], v[88:91]
	v_mfma_f32_16x16x32_bf16 v[76:79], v[132:135], v[200:203], v[76:79]
	v_mfma_f32_16x16x32_bf16 v[72:75], v[140:143], v[200:203], v[72:75]
	s_barrier
	s_add_i32 s49, s42, s31
	v_lshl_add_u64 v[186:187], s[22:23], 0, v[156:157]
	s_mov_b32 m0, s49
	ds_read_b128 v[204:207], v193
	ds_read_b128 v[208:211], v193 offset:1024
	ds_read_b128 v[212:215], v193 offset:2048
	ds_read_b128 v[216:219], v193 offset:3072
	global_load_lds_dwordx4 v[186:187], off
	v_lshl_add_u64 v[220:221], s[22:23], 0, v[160:161]
	s_add_i32 m0, s49, 0x2000
	s_nop 0
	global_load_lds_dwordx4 v[220:221], off
	s_barrier
	s_waitcnt lgkmcnt(0)
	v_mfma_f32_16x16x32_bf16 v[116:119], v[204:207], v[144:147], v[116:119]
	v_mfma_f32_16x16x32_bf16 v[112:115], v[212:215], v[144:147], v[112:115]
	v_mfma_f32_16x16x32_bf16 v[100:103], v[204:207], v[170:173], v[100:103]
	v_mfma_f32_16x16x32_bf16 v[96:99], v[212:215], v[170:173], v[96:99]
	v_mfma_f32_16x16x32_bf16 v[84:87], v[204:207], v[178:181], v[84:87]
	v_mfma_f32_16x16x32_bf16 v[80:83], v[212:215], v[178:181], v[80:83]
	v_mfma_f32_16x16x32_bf16 v[68:71], v[204:207], v[196:199], v[68:71]
	v_mfma_f32_16x16x32_bf16 v[64:67], v[212:215], v[196:199], v[64:67]
	v_mfma_f32_16x16x32_bf16 v[116:119], v[208:211], v[148:151], v[116:119]
	v_mfma_f32_16x16x32_bf16 v[112:115], v[216:219], v[148:151], v[112:115]
	v_mfma_f32_16x16x32_bf16 v[100:103], v[208:211], v[174:177], v[100:103]
	v_mfma_f32_16x16x32_bf16 v[96:99], v[216:219], v[174:177], v[96:99]
	v_mfma_f32_16x16x32_bf16 v[84:87], v[208:211], v[182:185], v[84:87]
	v_mfma_f32_16x16x32_bf16 v[80:83], v[216:219], v[182:185], v[80:83]
	v_mfma_f32_16x16x32_bf16 v[68:71], v[208:211], v[200:203], v[68:71]
	v_mfma_f32_16x16x32_bf16 v[64:67], v[216:219], v[200:203], v[64:67]
	s_mov_b32 m0, s11
	v_lshl_add_u64 v[222:223], s[24:25], 0, v[154:155]
	s_barrier
	ds_read_b128 v[144:147], v192 offset:16384
	ds_read_b128 v[148:151], v192 offset:17408
	ds_read_b128 v[170:173], v192 offset:18432
	ds_read_b128 v[174:177], v192 offset:19456
	ds_read_b128 v[178:181], v192 offset:20480
	ds_read_b128 v[182:185], v192 offset:21504
	ds_read_b128 v[196:199], v192 offset:22528
	ds_read_b128 v[200:203], v192 offset:23552
	global_load_lds_dwordx4 v[222:223], off
	v_lshl_add_u64 v[224:225], s[24:25], 0, v[158:159]
	s_mov_b32 m0, s34
	s_nop 0
	global_load_lds_dwordx4 v[224:225], off
	s_barrier
	s_waitcnt lgkmcnt(0)
	v_mfma_f32_16x16x32_bf16 v[60:63], v[128:131], v[144:147], v[60:63]
	v_mfma_f32_16x16x32_bf16 v[56:59], v[136:139], v[144:147], v[56:59]
	v_mfma_f32_16x16x32_bf16 v[44:47], v[128:131], v[170:173], v[44:47]
	v_mfma_f32_16x16x32_bf16 v[40:43], v[136:139], v[170:173], v[40:43]
	v_mfma_f32_16x16x32_bf16 v[28:31], v[128:131], v[178:181], v[28:31]
	v_mfma_f32_16x16x32_bf16 v[24:27], v[136:139], v[178:181], v[24:27]
	v_mfma_f32_16x16x32_bf16 v[12:15], v[128:131], v[196:199], v[12:15]
	v_mfma_f32_16x16x32_bf16 v[8:11], v[136:139], v[196:199], v[8:11]
	v_mfma_f32_16x16x32_bf16 v[60:63], v[132:135], v[148:151], v[60:63]
	v_mfma_f32_16x16x32_bf16 v[56:59], v[140:143], v[148:151], v[56:59]
	v_mfma_f32_16x16x32_bf16 v[44:47], v[132:135], v[174:177], v[44:47]
	v_mfma_f32_16x16x32_bf16 v[40:43], v[140:143], v[174:177], v[40:43]
	v_mfma_f32_16x16x32_bf16 v[28:31], v[132:135], v[182:185], v[28:31]
	v_mfma_f32_16x16x32_bf16 v[24:27], v[140:143], v[182:185], v[24:27]
	v_mfma_f32_16x16x32_bf16 v[12:15], v[132:135], v[200:203], v[12:15]
	v_mfma_f32_16x16x32_bf16 v[8:11], v[140:143], v[200:203], v[8:11]
	s_barrier
; #define PG8_STAGE(bufoff, gbase, voff) do { _Pragma("unroll") for (int _i = 0; _i < 2; ++_i) \
;         __builtin_amdgcn_global_load_lds((const unsigned*)((const char*)(gbase) + (voff)[_i]), (LAS unsigned*)(lds + (bufoff) + ldsw + _i * 8192), 16, 0, 0); } while (0)
; #define PG8_LDA(dst, b, h) do { _Pragma("unroll") for (int m = 0; m < 4; ++m) _Pragma("unroll") for (int k = 0; k < 2; ++k) dst[m][k] = *(const LAS bf16x8*)(lds + PG8_SA(b, h) + aoff + m * 2048 + k * 1024); } while (0)
; #define PG8_LDB(dst, b, h) do { _Pragma("unroll") for (int n = 0; n < 2; ++n) _Pragma("unroll") for (int k = 0; k < 2; ++k) dst[n][k] = *(const LAS bf16x8*)(lds + PG8_SB(b, h) + boff + n * 2048 + k * 1024); } while (0)
; #define PG8_MMA(ai, bj, At, Bt) do { __builtin_amdgcn_s_setprio(1); _Pragma("unroll") for (int m = 0; m < 4; ++m) _Pragma("unroll") for (int n = 0; n < 2; ++n) _Pragma("unroll") for (int k = 0; k < 2; ++k) \
;         acc[ai][bj][m][n] = __builtin_amdgcn_mfma_f32_16x16x32_bf16(Bt[n][k], At[m][k], acc[ai][bj][m][n], 0, 0, 0); __builtin_amdgcn_s_setprio(0); } while (0)
; #define PG8_WAIT_V(n) asm volatile("s_waitcnt vmcnt(" #n ")" ::: "memory")
; #define PG8_WAIT_L(n) asm volatile("s_waitcnt lgkmcnt(" #n ")" ::: "memory")
; #define PG8_BAR __builtin_amdgcn_s_barrier()
; #define PG8_SCHED __builtin_amdgcn_sched_barrier(0)
; template <class Epi>
; __device__ __forceinline__ void gemm_phase(LAS unsigned char* lds, const Gemm g, const StaticOrder& S, const Epi& E) {
;     ...
;             PG8_WAIT_V(6); PG8_BAR; PG8_MMA(1, 1, At, B1); PG8_BAR;
;             PG8_LDB(B0, 1, 0); PG8_SCHED; PG8_LDA(At, 1, 0); PG8_STAGE(PG8_SA(0, 1), a2 + hstepA, voffA);
;             PG8_WAIT_L(8); PG8_BAR; PG8_WAIT_L(0); PG8_MMA(0, 0, At, B0); PG8_BAR; PG8_SCHED;
;             PG8_LDB(B1, 1, 1); PG8_STAGE(PG8_SB(1, 0), b3, voffB);
;             PG8_BAR; PG8_WAIT_L(0); PG8_MMA(0, 1, At, B1); PG8_BAR;
;             PG8_LDA(At, 1, 1); PG8_STAGE(PG8_SA(1, 0), a3, voffA);
	s_add_u32 s50, s22, 0x80000
	s_addc_u32 s51, s23, 0
	s_add_i32 s49, s43, s31
	v_lshl_add_u64 v[128:129], s[50:51], 0, v[156:157]
	s_mov_b32 m0, s49
	s_nop 0
	global_load_lds_dwordx4 v[128:129], off
	v_lshl_add_u64 v[128:129], s[50:51], 0, v[160:161]
	s_add_i32 m0, s49, 0x2000
	s_nop 0
	global_load_lds_dwordx4 v[128:129], off
	s_waitcnt vmcnt(6)
	s_barrier
	v_mfma_f32_16x16x32_bf16 v[52:55], v[204:207], v[144:147], v[52:55]
	v_mfma_f32_16x16x32_bf16 v[48:51], v[212:215], v[144:147], v[48:51]
	v_mfma_f32_16x16x32_bf16 v[36:39], v[204:207], v[170:173], v[36:39]
	v_mfma_f32_16x16x32_bf16 v[32:35], v[212:215], v[170:173], v[32:35]
	v_mfma_f32_16x16x32_bf16 v[20:23], v[204:207], v[178:181], v[20:23]
	v_mfma_f32_16x16x32_bf16 v[16:19], v[212:215], v[178:181], v[16:19]
	v_mfma_f32_16x16x32_bf16 v[4:7], v[204:207], v[196:199], v[4:7]
	v_mfma_f32_16x16x32_bf16 v[0:3], v[212:215], v[196:199], v[0:3]
	v_mfma_f32_16x16x32_bf16 v[52:55], v[208:211], v[148:151], v[52:55]
	v_mfma_f32_16x16x32_bf16 v[48:51], v[216:219], v[148:151], v[48:51]
	v_mfma_f32_16x16x32_bf16 v[36:39], v[208:211], v[174:177], v[36:39]
	v_mfma_f32_16x16x32_bf16 v[32:35], v[216:219], v[174:177], v[32:35]
	v_mfma_f32_16x16x32_bf16 v[20:23], v[208:211], v[182:185], v[20:23]
	v_mfma_f32_16x16x32_bf16 v[16:19], v[216:219], v[182:185], v[16:19]
	v_mfma_f32_16x16x32_bf16 v[4:7], v[208:211], v[200:203], v[4:7]
	v_mfma_f32_16x16x32_bf16 v[0:3], v[216:219], v[200:203], v[0:3]
	s_add_i32 s49, 0, 0x18000
	v_add_u32_e32 v140, s49, v189
	s_barrier
	ds_read_b128 v[128:131], v140
	ds_read_b128 v[132:135], v140 offset:1024
	ds_read_b128 v[136:139], v140 offset:2048
	ds_read_b128 v[140:143], v140 offset:3072
	s_add_u32 s24, s24, 0x140000
	s_addc_u32 s25, s25, 0
	s_mov_b32 m0, s35
	v_lshl_add_u64 v[204:205], s[24:25], 0, v[154:155]
	ds_read_b128 v[144:147], v192 offset:32768
	ds_read_b128 v[148:151], v192 offset:33792
	ds_read_b128 v[170:173], v192 offset:34816
	ds_read_b128 v[174:177], v192 offset:35840
	ds_read_b128 v[178:181], v192 offset:36864
	ds_read_b128 v[182:185], v192 offset:37888
	ds_read_b128 v[196:199], v192 offset:38912
	ds_read_b128 v[200:203], v192 offset:39936
	global_load_lds_dwordx4 v[204:205], off
	v_lshl_add_u64 v[204:205], s[24:25], 0, v[158:159]
	s_mov_b32 m0, s36
	s_nop 0
	global_load_lds_dwordx4 v[204:205], off
	s_waitcnt lgkmcnt(8)
	s_barrier
	s_waitcnt lgkmcnt(0)
	v_mfma_f32_16x16x32_bf16 v[124:127], v[128:131], v[144:147], v[124:127]
	v_mfma_f32_16x16x32_bf16 v[120:123], v[136:139], v[144:147], v[120:123]
	v_mfma_f32_16x16x32_bf16 v[108:111], v[128:131], v[170:173], v[108:111]
	v_mfma_f32_16x16x32_bf16 v[104:107], v[136:139], v[170:173], v[104:107]
	v_mfma_f32_16x16x32_bf16 v[92:95], v[128:131], v[178:181], v[92:95]
	v_mfma_f32_16x16x32_bf16 v[88:91], v[136:139], v[178:181], v[88:91]
	v_mfma_f32_16x16x32_bf16 v[76:79], v[128:131], v[196:199], v[76:79]
	v_mfma_f32_16x16x32_bf16 v[72:75], v[136:139], v[196:199], v[72:75]
	v_mfma_f32_16x16x32_bf16 v[124:127], v[132:135], v[148:151], v[124:127]
	v_mfma_f32_16x16x32_bf16 v[120:123], v[140:143], v[148:151], v[120:123]
	v_mfma_f32_16x16x32_bf16 v[108:111], v[132:135], v[174:177], v[108:111]
	v_mfma_f32_16x16x32_bf16 v[104:107], v[140:143], v[174:177], v[104:107]
	v_mfma_f32_16x16x32_bf16 v[92:95], v[132:135], v[182:185], v[92:95]
	v_mfma_f32_16x16x32_bf16 v[88:91], v[140:143], v[182:185], v[88:91]
	v_mfma_f32_16x16x32_bf16 v[76:79], v[132:135], v[200:203], v[76:79]
	v_mfma_f32_16x16x32_bf16 v[72:75], v[140:143], v[200:203], v[72:75]
	s_barrier
	s_add_i32 s24, 0, 0x1c000
	s_add_i32 s25, s49, s31
	v_add_u32_e32 v195, s24, v189
	v_lshl_add_u64 v[186:187], v[186:187], 0, s[14:15]
	s_mov_b32 m0, s25
	ds_read_b128 v[204:207], v195
	ds_read_b128 v[208:211], v195 offset:1024
	ds_read_b128 v[212:215], v195 offset:2048
	ds_read_b128 v[216:219], v195 offset:3072
	global_load_lds_dwordx4 v[186:187], off
	v_lshl_add_u64 v[186:187], v[220:221], 0, s[14:15]
	s_add_i32 m0, s25, 0x2000
	s_nop 0
	global_load_lds_dwordx4 v[186:187], off
	s_barrier
	s_waitcnt lgkmcnt(0)
	v_mfma_f32_16x16x32_bf16 v[116:119], v[204:207], v[144:147], v[116:119]
	v_mfma_f32_16x16x32_bf16 v[112:115], v[212:215], v[144:147], v[112:115]
	v_mfma_f32_16x16x32_bf16 v[100:103], v[204:207], v[170:173], v[100:103]
	v_mfma_f32_16x16x32_bf16 v[96:99], v[212:215], v[170:173], v[96:99]
	v_mfma_f32_16x16x32_bf16 v[84:87], v[204:207], v[178:181], v[84:87]
	v_mfma_f32_16x16x32_bf16 v[80:83], v[212:215], v[178:181], v[80:83]
	v_mfma_f32_16x16x32_bf16 v[68:71], v[204:207], v[196:199], v[68:71]
	v_mfma_f32_16x16x32_bf16 v[64:67], v[212:215], v[196:199], v[64:67]
	v_mfma_f32_16x16x32_bf16 v[116:119], v[208:211], v[148:151], v[116:119]
	v_mfma_f32_16x16x32_bf16 v[112:115], v[216:219], v[148:151], v[112:115]
	v_mfma_f32_16x16x32_bf16 v[100:103], v[208:211], v[174:177], v[100:103]
	v_mfma_f32_16x16x32_bf16 v[96:99], v[216:219], v[174:177], v[96:99]
	v_mfma_f32_16x16x32_bf16 v[84:87], v[208:211], v[182:185], v[84:87]
	v_mfma_f32_16x16x32_bf16 v[80:83], v[216:219], v[182:185], v[80:83]
	v_mfma_f32_16x16x32_bf16 v[68:71], v[208:211], v[200:203], v[68:71]
	v_mfma_f32_16x16x32_bf16 v[64:67], v[216:219], v[200:203], v[64:67]
	s_mov_b32 m0, s38
	v_lshl_add_u64 v[186:187], v[222:223], 0, s[14:15]
	s_barrier
	ds_read_b128 v[144:147], v192 offset:49152
	ds_read_b128 v[148:151], v192 offset:50176
	ds_read_b128 v[170:173], v192 offset:51200
	ds_read_b128 v[174:177], v192 offset:52224
	ds_read_b128 v[178:181], v192 offset:53248
	ds_read_b128 v[182:185], v192 offset:54272
	ds_read_b128 v[196:199], v192 offset:55296
	ds_read_b128 v[200:203], v192 offset:56320
	global_load_lds_dwordx4 v[186:187], off
	v_lshl_add_u64 v[186:187], v[224:225], 0, s[14:15]
	s_mov_b32 m0, s39
	s_nop 0
	global_load_lds_dwordx4 v[186:187], off
	s_barrier
; #define PG8_STAGE(bufoff, gbase, voff) do { _Pragma("unroll") for (int _i = 0; _i < 2; ++_i) \
;         __builtin_amdgcn_global_load_lds((const unsigned*)((const char*)(gbase) + (voff)[_i]), (LAS unsigned*)(lds + (bufoff) + ldsw + _i * 8192), 16, 0, 0); } while (0)
; #define PG8_MMA(ai, bj, At, Bt) do { __builtin_amdgcn_s_setprio(1); _Pragma("unroll") for (int m = 0; m < 4; ++m) _Pragma("unroll") for (int n = 0; n < 2; ++n) _Pragma("unroll") for (int k = 0; k < 2; ++k) \
;         acc[ai][bj][m][n] = __builtin_amdgcn_mfma_f32_16x16x32_bf16(Bt[n][k], At[m][k], acc[ai][bj][m][n], 0, 0, 0); __builtin_amdgcn_s_setprio(0); } while (0)
; #define PG8_WAIT_V(n) asm volatile("s_waitcnt vmcnt(" #n ")" ::: "memory")
; #define PG8_WAIT_L(n) asm volatile("s_waitcnt lgkmcnt(" #n ")" ::: "memory")
; #define PG8_BAR __builtin_amdgcn_s_barrier()
; #define PG8_SCHED __builtin_amdgcn_sched_barrier(0)
; template <class Epi>
; __device__ __forceinline__ void gemm_phase(LAS unsigned char* lds, const Gemm g, const StaticOrder& S, const Epi& E) {
;     ...
;             PG8_BAR; PG8_WAIT_L(0); PG8_MMA(1, 0, At, B0); PG8_BAR; PG8_SCHED;
;             PG8_STAGE(PG8_SB(1, 1), b3 + hstepB, voffB);
;             PG8_WAIT_V(6); PG8_BAR; PG8_MMA(1, 1, At, B1); PG8_BAR;
	s_waitcnt lgkmcnt(0)
	v_mfma_f32_16x16x32_bf16 v[60:63], v[128:131], v[144:147], v[60:63]
	v_mfma_f32_16x16x32_bf16 v[56:59], v[136:139], v[144:147], v[56:59]
	v_mfma_f32_16x16x32_bf16 v[44:47], v[128:131], v[170:173], v[44:47]
	v_mfma_f32_16x16x32_bf16 v[40:43], v[136:139], v[170:173], v[40:43]
	v_mfma_f32_16x16x32_bf16 v[28:31], v[128:131], v[178:181], v[28:31]
	v_mfma_f32_16x16x32_bf16 v[24:27], v[136:139], v[178:181], v[24:27]
	v_mfma_f32_16x16x32_bf16 v[12:15], v[128:131], v[196:199], v[12:15]
	v_mfma_f32_16x16x32_bf16 v[8:11], v[136:139], v[196:199], v[8:11]
	v_mfma_f32_16x16x32_bf16 v[60:63], v[132:135], v[148:151], v[60:63]
	v_mfma_f32_16x16x32_bf16 v[56:59], v[140:143], v[148:151], v[56:59]
	v_mfma_f32_16x16x32_bf16 v[44:47], v[132:135], v[174:177], v[44:47]
	v_mfma_f32_16x16x32_bf16 v[40:43], v[140:143], v[174:177], v[40:43]
	v_mfma_f32_16x16x32_bf16 v[28:31], v[132:135], v[182:185], v[28:31]
	v_mfma_f32_16x16x32_bf16 v[24:27], v[140:143], v[182:185], v[24:27]
	v_mfma_f32_16x16x32_bf16 v[12:15], v[132:135], v[200:203], v[12:15]
	v_mfma_f32_16x16x32_bf16 v[8:11], v[140:143], v[200:203], v[8:11]
	s_barrier
	s_add_u32 s22, s22, 0x80080
	s_addc_u32 s23, s23, 0
	s_add_i32 s24, s24, s31
	v_lshl_add_u64 v[128:129], s[22:23], 0, v[156:157]
	s_mov_b32 m0, s24
	s_nop 0
	global_load_lds_dwordx4 v[128:129], off
	v_lshl_add_u64 v[128:129], s[22:23], 0, v[160:161]
	s_add_i32 m0, s24, 0x2000
	s_nop 0
	global_load_lds_dwordx4 v[128:129], off
	s_waitcnt vmcnt(6)
	s_barrier
	v_mfma_f32_16x16x32_bf16 v[52:55], v[204:207], v[144:147], v[52:55]
	v_mfma_f32_16x16x32_bf16 v[48:51], v[212:215], v[144:147], v[48:51]
	v_mfma_f32_16x16x32_bf16 v[36:39], v[204:207], v[170:173], v[36:39]
	v_mfma_f32_16x16x32_bf16 v[32:35], v[212:215], v[170:173], v[32:35]
	v_mfma_f32_16x16x32_bf16 v[20:23], v[204:207], v[178:181], v[20:23]
	v_mfma_f32_16x16x32_bf16 v[16:19], v[212:215], v[178:181], v[16:19]
	v_mfma_f32_16x16x32_bf16 v[4:7], v[204:207], v[196:199], v[4:7]
	v_mfma_f32_16x16x32_bf16 v[0:3], v[212:215], v[196:199], v[0:3]
	v_mfma_f32_16x16x32_bf16 v[52:55], v[208:211], v[148:151], v[52:55]
	v_mfma_f32_16x16x32_bf16 v[48:51], v[216:219], v[148:151], v[48:51]
	v_mfma_f32_16x16x32_bf16 v[36:39], v[208:211], v[174:177], v[36:39]
	v_mfma_f32_16x16x32_bf16 v[32:35], v[216:219], v[174:177], v[32:35]
	v_mfma_f32_16x16x32_bf16 v[20:23], v[208:211], v[182:185], v[20:23]
	v_mfma_f32_16x16x32_bf16 v[16:19], v[216:219], v[182:185], v[16:19]
	v_mfma_f32_16x16x32_bf16 v[4:7], v[208:211], v[200:203], v[4:7]
	v_mfma_f32_16x16x32_bf16 v[0:3], v[216:219], v[200:203], v[0:3]
	s_add_i32 s48, s48, 2
	s_add_u32 s4, s4, 0x100
	s_addc_u32 s5, s5, 0
	s_add_u32 s46, s46, 0x100
	s_addc_u32 s47, s47, 0
	s_cmp_gt_u32 s48, 29
	s_barrier
	s_cbranch_scc0 .LBB0_684
	s_setprio 0
	s_cmp_ge_u32 s98, 0x100
	s_cbranch_scc0 .Lep1_skip
	s_setprio 1
; __device__ __forceinline__ unsigned pk2(float lo, float hi) { const f32x2 v = (f32x2){lo, hi}; const bf16x2_t b = __builtin_convertvector(v, bf16x2_t); return __builtin_bit_cast(unsigned, b); }
; __device__ __forceinline__ void unpack8(const u32x4 v, float* f) { f[0] = bf_lo(v.x); f[1] = bf_hi(v.x); f[2] = bf_lo(v.y); f[3] = bf_hi(v.y); f[4] = bf_lo(v.z); f[5] = bf_hi(v.z); f[6] = bf_lo(v.w); f[7] = bf_hi(v.w); }
;     __device__ __forceinline__ void operator()(const f32x4 (&acc)[2][2][4][2], const Unit& u, int wr, int wc, int fr, int fq, const float (&)[8]) const {
;         const int row0 = u.pm * BM + wr * 64 + fr, col0 = u.pn * BM + wc * 32 + 8 * fq;
; #pragma unroll
;         for (int ai = 0; ai < 2; ++ai) {
;             u32x4 bv[4][2];
; #pragma unroll
;             for (int m = 0; m < 4; ++m)
; #pragma unroll
;                 for (int bj = 0; bj < 2; ++bj) bv[m][bj] = *(const u32x4*)(xb + (size_t)(row0 + ai * HALF + m * 16) * DM + col0 + bj * HALF);
; #pragma unroll
;             for (int m = 0; m < 4; ++m) { const int row = row0 + ai * HALF + m * 16; const size_t ro = (size_t)row * DM + col0; float s = 0.f;
; #pragma unroll
;                 for (int bj = 0; bj < 2; ++bj) { float b8[8]; unpack8(bv[m][bj], b8);
;                     const f32x4 v0 = (f32x4){b8[0], b8[1], b8[2], b8[3]} + acc[ai][bj][m][0], v1 = (f32x4){b8[4], b8[5], b8[6], b8[7]} + acc[ai][bj][m][1];
;                     s += v0[0] * v0[0] + v0[1] * v0[1] + v0[2] * v0[2] + v0[3] * v0[3] + v1[0] * v1[0] + v1[1] * v1[1] + v1[2] * v1[2] + v1[3] * v1[3];
;                     if (LAST) { *(f32x4*)(out + ro + bj * HALF) = v0; *(f32x4*)(out + ro + bj * HALF + 4) = v1; }
;                     else { u32x4 w; w.x = pk2(v0[0], v0[1]); w.y = pk2(v0[2], v0[3]); w.z = pk2(v1[0], v1[1]); w.w = pk2(v1[2], v1[3]); *(u32x4*)(xb + ro + bj * HALF) = w; } }
;                 s += __shfl_xor(s, 16); s += __shfl_xor(s, 32);
;                 if (fq == 0) ss[(size_t)row * 16 + u.pn * 4 + wc] = s; }
.Lep1_skip:
	v_lshl_or_b32 v170, s10, 8, v190
	v_lshl_add_u32 v172, s12, 8, v188
	v_ashrrev_i32_e32 v171, 31, v170
	v_lshlrev_b64 v[206:207], 1, v[170:171]
	v_ashrrev_i32_e32 v173, 31, v172
	v_lshl_add_u64 v[174:175], s[76:77], 0, v[206:207]
	v_lshlrev_b64 v[208:209], 11, v[172:173]
	v_lshl_add_u64 v[128:129], v[174:175], 0, v[208:209]
	global_load_dwordx4 v[198:201], v[128:129], off
	global_load_dwordx4 v[202:205], v[128:129], off offset:256
	v_or_b32_e32 v184, 16, v172
	v_or_b32_e32 v180, 32, v172
	v_or_b32_e32 v176, 48, v172
	v_ashrrev_i32_e32 v185, 31, v184
	v_ashrrev_i32_e32 v181, 31, v180
	v_ashrrev_i32_e32 v177, 31, v176
	v_lshlrev_b64 v[186:187], 11, v[184:185]
	v_lshlrev_b64 v[182:183], 11, v[180:181]
	v_lshlrev_b64 v[178:179], 11, v[176:177]
	v_lshl_add_u64 v[128:129], v[174:175], 0, v[186:187]
	v_lshl_add_u64 v[130:131], v[174:175], 0, v[182:183]
	v_lshl_add_u64 v[196:197], v[174:175], 0, v[178:179]
	global_load_dwordx4 v[148:151], v[128:129], off
	global_load_dwordx4 v[144:147], v[128:129], off offset:256
	global_load_dwordx4 v[140:143], v[130:131], off
	global_load_dwordx4 v[136:139], v[130:131], off offset:256
	global_load_dwordx4 v[132:135], v[196:197], off
	s_nop 0
	global_load_dwordx4 v[128:131], v[196:197], off offset:256
	v_add_u32_e32 v218, 0x80, v172
	v_ashrrev_i32_e32 v219, 31, v218
	v_lshlrev_b64 v[218:219], 11, v[218:219]
	v_lshl_add_u64 v[218:219], v[174:175], 0, v[218:219]
	global_load_dwordx4 v[220:223], v[218:219], off
	global_load_dwordx4 v[224:227], v[218:219], off offset:256
	v_add_u32_e32 v218, 0x90, v172
	v_ashrrev_i32_e32 v219, 31, v218
	v_lshlrev_b64 v[218:219], 11, v[218:219]
	v_lshl_add_u64 v[218:219], v[174:175], 0, v[218:219]
	global_load_dwordx4 v[228:231], v[218:219], off
	global_load_dwordx4 v[232:235], v[218:219], off offset:256
	v_add_u32_e32 v218, 0xa0, v172
	v_ashrrev_i32_e32 v219, 31, v218
	v_lshlrev_b64 v[218:219], 11, v[218:219]
	v_lshl_add_u64 v[218:219], v[174:175], 0, v[218:219]
	global_load_dwordx4 v[236:239], v[218:219], off
	global_load_dwordx4 v[240:243], v[218:219], off offset:256
	v_add_u32_e32 v218, 0xb0, v172
	v_ashrrev_i32_e32 v219, 31, v218
	v_lshlrev_b64 v[218:219], 11, v[218:219]
	v_lshl_add_u64 v[218:219], v[174:175], 0, v[218:219]
	global_load_dwordx4 v[244:247], v[218:219], off
	global_load_dwordx4 v[252:255], v[218:219], off offset:256
	v_and_b32_e32 v196, 64, v194
	v_xor_b32_e32 v195, 16, v194
	v_add_u32_e32 v196, 64, v196
	v_xor_b32_e32 v197, 32, v194
	v_cmp_lt_i32_e32 vcc, v195, v196
	s_waitcnt vmcnt(15)
	v_lshlrev_b32_e32 v210, 16, v198
	v_cndmask_b32_e32 v195, v194, v195, vcc
	v_cmp_lt_i32_e32 vcc, v197, v196
	v_and_b32_e32 v211, 0xffff0000, v198
	s_waitcnt vmcnt(14)
	v_lshlrev_b32_e32 v214, 16, v202
	v_and_b32_e32 v215, 0xffff0000, v202
	v_cndmask_b32_e32 v197, v194, v197, vcc
	v_lshlrev_b32_e32 v212, 16, v200
	v_and_b32_e32 v213, 0xffff0000, v200
	v_lshlrev_b32_e32 v200, 16, v201
	v_and_b32_e32 v201, 0xffff0000, v201
	v_lshlrev_b32_e32 v216, 16, v204
	v_and_b32_e32 v217, 0xffff0000, v204
	v_pk_add_f32 v[124:125], v[124:125], v[210:211]
	v_pk_add_f32 v[116:117], v[116:117], v[214:215]
	v_lshlrev_b32_e32 v196, 2, v195
	v_lshlrev_b32_e32 v195, 2, v197
	v_lshlrev_b32_e32 v198, 16, v199
	v_and_b32_e32 v199, 0xffff0000, v199
	v_lshlrev_b32_e32 v202, 16, v203
	v_and_b32_e32 v203, 0xffff0000, v203
	v_pk_add_f32 v[122:123], v[122:123], v[200:201]
	v_pk_add_f32 v[200:201], v[112:113], v[216:217]
	v_mul_f32_e32 v197, v125, v125
	v_cvt_pk_bf16_f32 v112, v124, v125
	v_mul_f32_e32 v125, v117, v117
	v_pk_add_f32 v[126:127], v[126:127], v[198:199]
	v_pk_add_f32 v[118:119], v[118:119], v[202:203]
	v_fmac_f32_e32 v197, v124, v124
	v_fmac_f32_e32 v125, v116, v116
	v_fmac_f32_e32 v197, v126, v126
	v_fmac_f32_e32 v125, v118, v118
	v_pk_add_f32 v[120:121], v[120:121], v[212:213]
	v_fmac_f32_e32 v197, v127, v127
	v_fmac_f32_e32 v125, v119, v119
	v_lshlrev_b32_e32 v204, 16, v205
	v_and_b32_e32 v205, 0xffff0000, v205
	v_fmac_f32_e32 v197, v120, v120
	v_fmac_f32_e32 v125, v200, v200
	v_pk_add_f32 v[198:199], v[114:115], v[204:205]
	v_fmac_f32_e32 v197, v121, v121
	v_fmac_f32_e32 v125, v201, v201
	v_fmac_f32_e32 v197, v122, v122
	v_fmac_f32_e32 v125, v198, v198
	v_fmac_f32_e32 v197, v123, v123
	v_fmac_f32_e32 v125, v199, v199
	v_cvt_pk_bf16_f32 v115, v122, v123
	v_add_f32_e32 v122, v197, v125
	ds_bpermute_b32 v123, v196, v122
	v_cvt_pk_bf16_f32 v114, v120, v121
	v_lshl_add_u64 v[120:121], s[76:77], 0, v[208:209]
	v_cvt_pk_bf16_f32 v113, v126, v127
	v_lshl_add_u64 v[120:121], v[120:121], 0, v[206:207]
	global_store_dwordx4 v[120:121], v[112:115], off
	s_waitcnt lgkmcnt(0)
	s_nop 0
	v_add_f32_e32 v112, v122, v123
	ds_bpermute_b32 v113, v195, v112
	v_cvt_pk_bf16_f32 v114, v116, v117
	v_cvt_pk_bf16_f32 v115, v118, v119
	v_cvt_pk_bf16_f32 v116, v200, v201
	v_cvt_pk_bf16_f32 v117, v198, v199
	global_store_dwordx4 v[120:121], v[114:117], off offset:256
	s_and_saveexec_b64 s[4:5], s[0:1]
	s_cbranch_execz .LBB0_687
	s_waitcnt lgkmcnt(0)
	v_add_f32_e32 v114, v112, v113
	s_lshl_b32 s22, s10, 2
	v_lshlrev_b64 v[112:113], 6, v[172:173]
	s_ashr_i32 s23, s22, 31
	v_lshl_add_u64 v[112:113], s[6:7], 0, v[112:113]
	v_lshl_add_u64 v[112:113], s[22:23], 2, v[112:113]
	s_lshl_b32 s12, s37, 2
	v_lshl_add_u64 v[112:113], v[112:113], 0, s[12:13]
	global_store_dword v[112:113], v114, off

; #define PG8_STAGE(bufoff, gbase, voff) do { _Pragma("unroll") for (int _i = 0; _i < 2; ++_i) \
;         __builtin_amdgcn_global_load_lds((const unsigned*)((const char*)(gbase) + (voff)[_i]), (LAS unsigned*)(lds + (bufoff) + ldsw + _i * 8192), 16, 0, 0); } while (0)
; #define PG8_LDA(dst, b, h) do { _Pragma("unroll") for (int m = 0; m < 4; ++m) _Pragma("unroll") for (int k = 0; k < 2; ++k) dst[m][k] = *(const LAS bf16x8*)(lds + PG8_SA(b, h) + aoff + m * 2048 + k * 1024); } while (0)
; #define PG8_LDB(dst, b, h) do { _Pragma("unroll") for (int n = 0; n < 2; ++n) _Pragma("unroll") for (int k = 0; k < 2; ++k) dst[n][k] = *(const LAS bf16x8*)(lds + PG8_SB(b, h) + boff + n * 2048 + k * 1024); } while (0)
; #define PG8_MMA(ai, bj, At, Bt) do { __builtin_amdgcn_s_setprio(1); _Pragma("unroll") for (int m = 0; m < 4; ++m) _Pragma("unroll") for (int n = 0; n < 2; ++n) _Pragma("unroll") for (int k = 0; k < 2; ++k) \
;         acc[ai][bj][m][n] = __builtin_amdgcn_mfma_f32_16x16x32_bf16(Bt[n][k], At[m][k], acc[ai][bj][m][n], 0, 0, 0); __builtin_amdgcn_s_setprio(0); } while (0)
; #define PG8_WAIT_V(n) asm volatile("s_waitcnt vmcnt(" #n ")" ::: "memory")
; #define PG8_WAIT_L(n) asm volatile("s_waitcnt lgkmcnt(" #n ")" ::: "memory")
; #define PG8_BAR __builtin_amdgcn_s_barrier()
; #define PG8_SCHED __builtin_amdgcn_sched_barrier(0)
; template <class Epi>
; __device__ __forceinline__ void gemm_phase(LAS unsigned char* lds, const Gemm g, const StaticOrder& S, const Epi& E) {
;     ...
;             PG8_LDB(B0, 0, 0); PG8_SCHED; PG8_LDA(At, 0, 0); PG8_STAGE(PG8_SA(1, 1), a1 + hstepA, voffA);
;             PG8_WAIT_L(8); PG8_BAR; PG8_WAIT_L(0); PG8_MMA(0, 0, At, B0); PG8_BAR; PG8_SCHED;
;             PG8_LDB(B1, 0, 1); PG8_STAGE(PG8_SB(0, 0), b2, voffB);
;             PG8_BAR; PG8_WAIT_L(0); PG8_MMA(0, 1, At, B1); PG8_BAR;
;             PG8_LDA(At, 0, 1); PG8_STAGE(PG8_SA(0, 0), a2, voffA);
;             PG8_BAR; PG8_WAIT_L(0); PG8_MMA(1, 0, At, B0); PG8_BAR; PG8_SCHED;
;             PG8_STAGE(PG8_SB(0, 1), b2 + hstepB, voffB);
;             PG8_WAIT_V(6); PG8_BAR; PG8_MMA(1, 1, At, B1); PG8_BAR;
.LBB0_770:
	ds_read_b128 v[146:149], v177
	ds_read_b128 v[154:157], v177 offset:1024
	ds_read_b128 v[158:161], v177 offset:2048
	ds_read_b128 v[162:165], v177 offset:3072
	s_add_u32 s22, s20, 0xfffc0080
	s_addc_u32 s23, s21, -1
	s_cmp_eq_u32 s45, 12
	s_cselect_b32 s25, s13, s23
	s_cselect_b32 s24, s41, s22
	s_cselect_b32 s23, s11, s44
	s_cselect_b32 s22, s42, s43
	v_lshl_add_u64 v[150:151], s[20:21], 0, v[138:139]
	s_add_i32 m0, s19, 0xc000
	ds_read_b128 v[166:169], v178
	ds_read_b128 v[170:173], v178 offset:1024
	ds_read_b128 v[182:185], v178 offset:2048
	ds_read_b128 v[186:189], v178 offset:3072
	ds_read_b128 v[190:193], v178 offset:4096
	ds_read_b128 v[194:197], v178 offset:5120
	ds_read_b128 v[198:201], v178 offset:6144
	ds_read_b128 v[202:205], v178 offset:7168
	global_load_lds_dwordx4 v[150:151], off
	v_lshl_add_u64 v[150:151], s[20:21], 0, v[140:141]
	s_add_i32 m0, s19, 0xe000
	s_nop 0
	global_load_lds_dwordx4 v[150:151], off
	s_waitcnt lgkmcnt(8)
	s_barrier
	s_waitcnt lgkmcnt(0)
	v_mfma_f32_16x16x32_bf16 v[124:127], v[146:149], v[166:169], v[124:127]
	v_mfma_f32_16x16x32_bf16 v[120:123], v[158:161], v[166:169], v[120:123]
	v_mfma_f32_16x16x32_bf16 v[108:111], v[146:149], v[182:185], v[108:111]
	v_mfma_f32_16x16x32_bf16 v[104:107], v[158:161], v[182:185], v[104:107]
	v_mfma_f32_16x16x32_bf16 v[92:95], v[146:149], v[190:193], v[92:95]
	v_mfma_f32_16x16x32_bf16 v[88:91], v[158:161], v[190:193], v[88:91]
	v_mfma_f32_16x16x32_bf16 v[76:79], v[146:149], v[198:201], v[76:79]
	v_mfma_f32_16x16x32_bf16 v[72:75], v[158:161], v[198:201], v[72:75]
	v_mfma_f32_16x16x32_bf16 v[124:127], v[154:157], v[170:173], v[124:127]
	v_mfma_f32_16x16x32_bf16 v[120:123], v[162:165], v[170:173], v[120:123]
	v_mfma_f32_16x16x32_bf16 v[108:111], v[154:157], v[186:189], v[108:111]
	v_mfma_f32_16x16x32_bf16 v[104:107], v[162:165], v[186:189], v[104:107]
	v_mfma_f32_16x16x32_bf16 v[92:95], v[154:157], v[194:197], v[92:95]
	v_mfma_f32_16x16x32_bf16 v[88:91], v[162:165], v[194:197], v[88:91]
	v_mfma_f32_16x16x32_bf16 v[76:79], v[154:157], v[202:205], v[76:79]
	v_mfma_f32_16x16x32_bf16 v[72:75], v[162:165], v[202:205], v[72:75]
	s_barrier
	s_add_i32 s46, s7, s29
	v_lshl_add_u64 v[150:151], s[22:23], 0, v[130:131]
	s_mov_b32 m0, s46
	ds_read_b128 v[206:209], v179
	ds_read_b128 v[210:213], v179 offset:1024
	ds_read_b128 v[214:217], v179 offset:2048
	ds_read_b128 v[218:221], v179 offset:3072
	global_load_lds_dwordx4 v[150:151], off
	v_lshl_add_u64 v[222:223], s[22:23], 0, v[134:135]
	s_add_i32 m0, s46, 0x2000
	s_nop 0
	global_load_lds_dwordx4 v[222:223], off
	s_barrier
	s_waitcnt lgkmcnt(0)
	v_mfma_f32_16x16x32_bf16 v[116:119], v[206:209], v[166:169], v[116:119]
	v_mfma_f32_16x16x32_bf16 v[112:115], v[214:217], v[166:169], v[112:115]
	v_mfma_f32_16x16x32_bf16 v[100:103], v[206:209], v[182:185], v[100:103]
	v_mfma_f32_16x16x32_bf16 v[96:99], v[214:217], v[182:185], v[96:99]
	v_mfma_f32_16x16x32_bf16 v[84:87], v[206:209], v[190:193], v[84:87]
	v_mfma_f32_16x16x32_bf16 v[80:83], v[214:217], v[190:193], v[80:83]
	v_mfma_f32_16x16x32_bf16 v[68:71], v[206:209], v[198:201], v[68:71]
	v_mfma_f32_16x16x32_bf16 v[64:67], v[214:217], v[198:201], v[64:67]
	v_mfma_f32_16x16x32_bf16 v[116:119], v[210:213], v[170:173], v[116:119]
	v_mfma_f32_16x16x32_bf16 v[112:115], v[218:221], v[170:173], v[112:115]
	v_mfma_f32_16x16x32_bf16 v[100:103], v[210:213], v[186:189], v[100:103]
	v_mfma_f32_16x16x32_bf16 v[96:99], v[218:221], v[186:189], v[96:99]
	v_mfma_f32_16x16x32_bf16 v[84:87], v[210:213], v[194:197], v[84:87]
	v_mfma_f32_16x16x32_bf16 v[80:83], v[218:221], v[194:197], v[80:83]
	v_mfma_f32_16x16x32_bf16 v[68:71], v[210:213], v[202:205], v[68:71]
	v_mfma_f32_16x16x32_bf16 v[64:67], v[218:221], v[202:205], v[64:67]
	s_mov_b32 m0, s19
	v_lshl_add_u64 v[224:225], s[24:25], 0, v[128:129]
	s_barrier
	ds_read_b128 v[166:169], v178 offset:16384
	ds_read_b128 v[170:173], v178 offset:17408
	ds_read_b128 v[182:185], v178 offset:18432
	ds_read_b128 v[186:189], v178 offset:19456
	ds_read_b128 v[190:193], v178 offset:20480
	ds_read_b128 v[194:197], v178 offset:21504
	ds_read_b128 v[198:201], v178 offset:22528
	ds_read_b128 v[202:205], v178 offset:23552
	global_load_lds_dwordx4 v[224:225], off
	v_lshl_add_u64 v[226:227], s[24:25], 0, v[132:133]
	s_mov_b32 m0, s30
	s_nop 0
	global_load_lds_dwordx4 v[226:227], off
	s_barrier
	s_waitcnt lgkmcnt(0)
	v_mfma_f32_16x16x32_bf16 v[60:63], v[146:149], v[166:169], v[60:63]
	v_mfma_f32_16x16x32_bf16 v[56:59], v[158:161], v[166:169], v[56:59]
	v_mfma_f32_16x16x32_bf16 v[44:47], v[146:149], v[182:185], v[44:47]
	v_mfma_f32_16x16x32_bf16 v[40:43], v[158:161], v[182:185], v[40:43]
	v_mfma_f32_16x16x32_bf16 v[28:31], v[146:149], v[190:193], v[28:31]
	v_mfma_f32_16x16x32_bf16 v[24:27], v[158:161], v[190:193], v[24:27]
	v_mfma_f32_16x16x32_bf16 v[12:15], v[146:149], v[198:201], v[12:15]
	v_mfma_f32_16x16x32_bf16 v[8:11], v[158:161], v[198:201], v[8:11]
	v_mfma_f32_16x16x32_bf16 v[60:63], v[154:157], v[170:173], v[60:63]
	v_mfma_f32_16x16x32_bf16 v[56:59], v[162:165], v[170:173], v[56:59]
	v_mfma_f32_16x16x32_bf16 v[44:47], v[154:157], v[186:189], v[44:47]
	v_mfma_f32_16x16x32_bf16 v[40:43], v[162:165], v[186:189], v[40:43]
	v_mfma_f32_16x16x32_bf16 v[28:31], v[154:157], v[194:197], v[28:31]
	v_mfma_f32_16x16x32_bf16 v[24:27], v[162:165], v[194:197], v[24:27]
	v_mfma_f32_16x16x32_bf16 v[12:15], v[154:157], v[202:205], v[12:15]
	v_mfma_f32_16x16x32_bf16 v[8:11], v[162:165], v[202:205], v[8:11]
	s_barrier
; #define PG8_STAGE(bufoff, gbase, voff) do { _Pragma("unroll") for (int _i = 0; _i < 2; ++_i) \
;         __builtin_amdgcn_global_load_lds((const unsigned*)((const char*)(gbase) + (voff)[_i]), (LAS unsigned*)(lds + (bufoff) + ldsw + _i * 8192), 16, 0, 0); } while (0)
; #define PG8_LDA(dst, b, h) do { _Pragma("unroll") for (int m = 0; m < 4; ++m) _Pragma("unroll") for (int k = 0; k < 2; ++k) dst[m][k] = *(const LAS bf16x8*)(lds + PG8_SA(b, h) + aoff + m * 2048 + k * 1024); } while (0)
; #define PG8_LDB(dst, b, h) do { _Pragma("unroll") for (int n = 0; n < 2; ++n) _Pragma("unroll") for (int k = 0; k < 2; ++k) dst[n][k] = *(const LAS bf16x8*)(lds + PG8_SB(b, h) + boff + n * 2048 + k * 1024); } while (0)
; #define PG8_MMA(ai, bj, At, Bt) do { __builtin_amdgcn_s_setprio(1); _Pragma("unroll") for (int m = 0; m < 4; ++m) _Pragma("unroll") for (int n = 0; n < 2; ++n) _Pragma("unroll") for (int k = 0; k < 2; ++k) \
;         acc[ai][bj][m][n] = __builtin_amdgcn_mfma_f32_16x16x32_bf16(Bt[n][k], At[m][k], acc[ai][bj][m][n], 0, 0, 0); __builtin_amdgcn_s_setprio(0); } while (0)
; #define PG8_WAIT_V(n) asm volatile("s_waitcnt vmcnt(" #n ")" ::: "memory")
; #define PG8_WAIT_L(n) asm volatile("s_waitcnt lgkmcnt(" #n ")" ::: "memory")
; #define PG8_BAR __builtin_amdgcn_s_barrier()
; #define PG8_SCHED __builtin_amdgcn_sched_barrier(0)
; template <class Epi>
; __device__ __forceinline__ void gemm_phase(LAS unsigned char* lds, const Gemm g, const StaticOrder& S, const Epi& E) {
;     ...
;             PG8_WAIT_V(6); PG8_BAR; PG8_MMA(1, 1, At, B1); PG8_BAR;
;             PG8_LDB(B0, 1, 0); PG8_SCHED; PG8_LDA(At, 1, 0); PG8_STAGE(PG8_SA(0, 1), a2 + hstepA, voffA);
;             PG8_WAIT_L(8); PG8_BAR; PG8_WAIT_L(0); PG8_MMA(0, 0, At, B0); PG8_BAR; PG8_SCHED;
;             PG8_LDB(B1, 1, 1); PG8_STAGE(PG8_SB(1, 0), b3, voffB);
;             PG8_BAR; PG8_WAIT_L(0); PG8_MMA(0, 1, At, B1); PG8_BAR;
;             PG8_LDA(At, 1, 1); PG8_STAGE(PG8_SA(1, 0), a3, voffA);
	s_add_u32 s46, s22, 0x40000
	s_addc_u32 s47, s23, 0
	s_add_i32 s48, s38, s29
	v_lshl_add_u64 v[146:147], s[46:47], 0, v[130:131]
	s_mov_b32 m0, s48
	s_nop 0
	global_load_lds_dwordx4 v[146:147], off
	v_lshl_add_u64 v[146:147], s[46:47], 0, v[134:135]
	s_add_i32 m0, s48, 0x2000
	s_nop 0
	global_load_lds_dwordx4 v[146:147], off
	s_waitcnt vmcnt(6)
	s_barrier
	v_mfma_f32_16x16x32_bf16 v[52:55], v[206:209], v[166:169], v[52:55]
	v_mfma_f32_16x16x32_bf16 v[48:51], v[214:217], v[166:169], v[48:51]
	v_mfma_f32_16x16x32_bf16 v[36:39], v[206:209], v[182:185], v[36:39]
	v_mfma_f32_16x16x32_bf16 v[32:35], v[214:217], v[182:185], v[32:35]
	v_mfma_f32_16x16x32_bf16 v[20:23], v[206:209], v[190:193], v[20:23]
	v_mfma_f32_16x16x32_bf16 v[16:19], v[214:217], v[190:193], v[16:19]
	v_mfma_f32_16x16x32_bf16 v[4:7], v[206:209], v[198:201], v[4:7]
	v_mfma_f32_16x16x32_bf16 v[0:3], v[214:217], v[198:201], v[0:3]
	v_mfma_f32_16x16x32_bf16 v[52:55], v[210:213], v[170:173], v[52:55]
	v_mfma_f32_16x16x32_bf16 v[48:51], v[218:221], v[170:173], v[48:51]
	v_mfma_f32_16x16x32_bf16 v[36:39], v[210:213], v[186:189], v[36:39]
	v_mfma_f32_16x16x32_bf16 v[32:35], v[218:221], v[186:189], v[32:35]
	v_mfma_f32_16x16x32_bf16 v[20:23], v[210:213], v[194:197], v[20:23]
	v_mfma_f32_16x16x32_bf16 v[16:19], v[218:221], v[194:197], v[16:19]
	v_mfma_f32_16x16x32_bf16 v[4:7], v[210:213], v[202:205], v[4:7]
	v_mfma_f32_16x16x32_bf16 v[0:3], v[218:221], v[202:205], v[0:3]
	s_add_i32 s46, 0, 0x18000
	v_add_u32_e32 v162, s46, v175
	s_barrier
	ds_read_b128 v[146:149], v162
	ds_read_b128 v[154:157], v162 offset:1024
	ds_read_b128 v[158:161], v162 offset:2048
	ds_read_b128 v[162:165], v162 offset:3072
	s_add_u32 s24, s24, 0x40000
	s_addc_u32 s25, s25, 0
	s_mov_b32 m0, s31
	v_lshl_add_u64 v[206:207], s[24:25], 0, v[128:129]
	ds_read_b128 v[166:169], v178 offset:32768
	ds_read_b128 v[170:173], v178 offset:33792
	ds_read_b128 v[182:185], v178 offset:34816
	ds_read_b128 v[186:189], v178 offset:35840
	ds_read_b128 v[190:193], v178 offset:36864
	ds_read_b128 v[194:197], v178 offset:37888
	ds_read_b128 v[198:201], v178 offset:38912
	ds_read_b128 v[202:205], v178 offset:39936
	global_load_lds_dwordx4 v[206:207], off
	v_lshl_add_u64 v[206:207], s[24:25], 0, v[132:133]
	s_mov_b32 m0, s33
	s_nop 0
	global_load_lds_dwordx4 v[206:207], off
	s_waitcnt lgkmcnt(8)
	s_barrier
	s_waitcnt lgkmcnt(0)
	v_mfma_f32_16x16x32_bf16 v[124:127], v[146:149], v[166:169], v[124:127]
	v_mfma_f32_16x16x32_bf16 v[120:123], v[158:161], v[166:169], v[120:123]
	v_mfma_f32_16x16x32_bf16 v[108:111], v[146:149], v[182:185], v[108:111]
	v_mfma_f32_16x16x32_bf16 v[104:107], v[158:161], v[182:185], v[104:107]
	v_mfma_f32_16x16x32_bf16 v[92:95], v[146:149], v[190:193], v[92:95]
	v_mfma_f32_16x16x32_bf16 v[88:91], v[158:161], v[190:193], v[88:91]
	v_mfma_f32_16x16x32_bf16 v[76:79], v[146:149], v[198:201], v[76:79]
	v_mfma_f32_16x16x32_bf16 v[72:75], v[158:161], v[198:201], v[72:75]
	v_mfma_f32_16x16x32_bf16 v[124:127], v[154:157], v[170:173], v[124:127]
	v_mfma_f32_16x16x32_bf16 v[120:123], v[162:165], v[170:173], v[120:123]
	v_mfma_f32_16x16x32_bf16 v[108:111], v[154:157], v[186:189], v[108:111]
	v_mfma_f32_16x16x32_bf16 v[104:107], v[162:165], v[186:189], v[104:107]
	v_mfma_f32_16x16x32_bf16 v[92:95], v[154:157], v[194:197], v[92:95]
	v_mfma_f32_16x16x32_bf16 v[88:91], v[162:165], v[194:197], v[88:91]
	v_mfma_f32_16x16x32_bf16 v[76:79], v[154:157], v[202:205], v[76:79]
	v_mfma_f32_16x16x32_bf16 v[72:75], v[162:165], v[202:205], v[72:75]
	s_barrier
	s_add_i32 s24, 0, 0x1c000
	s_add_i32 s25, s46, s29
	v_add_u32_e32 v181, s24, v175
	v_lshl_add_u64 v[150:151], v[150:151], 0, s[4:5]
	s_mov_b32 m0, s25
	ds_read_b128 v[206:209], v181
	ds_read_b128 v[210:213], v181 offset:1024
	ds_read_b128 v[214:217], v181 offset:2048
	ds_read_b128 v[218:221], v181 offset:3072
	global_load_lds_dwordx4 v[150:151], off
	v_lshl_add_u64 v[150:151], v[222:223], 0, s[4:5]
	s_add_i32 m0, s25, 0x2000
	s_nop 0
	global_load_lds_dwordx4 v[150:151], off
	s_barrier
	s_waitcnt lgkmcnt(0)
	v_mfma_f32_16x16x32_bf16 v[116:119], v[206:209], v[166:169], v[116:119]
	v_mfma_f32_16x16x32_bf16 v[112:115], v[214:217], v[166:169], v[112:115]
	v_mfma_f32_16x16x32_bf16 v[100:103], v[206:209], v[182:185], v[100:103]
	v_mfma_f32_16x16x32_bf16 v[96:99], v[214:217], v[182:185], v[96:99]
	v_mfma_f32_16x16x32_bf16 v[84:87], v[206:209], v[190:193], v[84:87]
	v_mfma_f32_16x16x32_bf16 v[80:83], v[214:217], v[190:193], v[80:83]
	v_mfma_f32_16x16x32_bf16 v[68:71], v[206:209], v[198:201], v[68:71]
	v_mfma_f32_16x16x32_bf16 v[64:67], v[214:217], v[198:201], v[64:67]
	v_mfma_f32_16x16x32_bf16 v[116:119], v[210:213], v[170:173], v[116:119]
	v_mfma_f32_16x16x32_bf16 v[112:115], v[218:221], v[170:173], v[112:115]
	v_mfma_f32_16x16x32_bf16 v[100:103], v[210:213], v[186:189], v[100:103]
	v_mfma_f32_16x16x32_bf16 v[96:99], v[218:221], v[186:189], v[96:99]
	v_mfma_f32_16x16x32_bf16 v[84:87], v[210:213], v[194:197], v[84:87]
	v_mfma_f32_16x16x32_bf16 v[80:83], v[218:221], v[194:197], v[80:83]
	v_mfma_f32_16x16x32_bf16 v[68:71], v[210:213], v[202:205], v[68:71]
	v_mfma_f32_16x16x32_bf16 v[64:67], v[218:221], v[202:205], v[64:67]
	s_mov_b32 m0, s35
	v_lshl_add_u64 v[150:151], v[224:225], 0, s[4:5]
	s_barrier
	ds_read_b128 v[166:169], v178 offset:49152
	ds_read_b128 v[170:173], v178 offset:50176
	ds_read_b128 v[182:185], v178 offset:51200
	ds_read_b128 v[186:189], v178 offset:52224
	ds_read_b128 v[190:193], v178 offset:53248
	ds_read_b128 v[194:197], v178 offset:54272
	ds_read_b128 v[198:201], v178 offset:55296
	ds_read_b128 v[202:205], v178 offset:56320
	global_load_lds_dwordx4 v[150:151], off
	v_lshl_add_u64 v[150:151], v[226:227], 0, s[4:5]
	s_mov_b32 m0, s36
	s_nop 0
	global_load_lds_dwordx4 v[150:151], off
	s_barrier
; __device__ __forceinline__ unsigned pk2(float lo, float hi) { const f32x2 v = (f32x2){lo, hi}; const bf16x2_t b = __builtin_convertvector(v, bf16x2_t); return __builtin_bit_cast(unsigned, b); }
; #define PG8_STAGE(bufoff, gbase, voff) do { _Pragma("unroll") for (int _i = 0; _i < 2; ++_i) \
;         __builtin_amdgcn_global_load_lds((const unsigned*)((const char*)(gbase) + (voff)[_i]), (LAS unsigned*)(lds + (bufoff) + ldsw + _i * 8192), 16, 0, 0); } while (0)
; #define PG8_MMA(ai, bj, At, Bt) do { __builtin_amdgcn_s_setprio(1); _Pragma("unroll") for (int m = 0; m < 4; ++m) _Pragma("unroll") for (int n = 0; n < 2; ++n) _Pragma("unroll") for (int k = 0; k < 2; ++k) \
;         acc[ai][bj][m][n] = __builtin_amdgcn_mfma_f32_16x16x32_bf16(Bt[n][k], At[m][k], acc[ai][bj][m][n], 0, 0, 0); __builtin_amdgcn_s_setprio(0); } while (0)
; #define PG8_WAIT_V(n) asm volatile("s_waitcnt vmcnt(" #n ")" ::: "memory")
; #define PG8_WAIT_L(n) asm volatile("s_waitcnt lgkmcnt(" #n ")" ::: "memory")
;     __device__ __forceinline__ void operator()(const f32x4 (&acc)[2][2][4][2], const Unit& u, int wr, int wc, int fr, int fq, const float (&)[8]) const {
;     ...
;         const int col0 = u.pn * BM + wc * 32 + 8 * fq;
; #pragma unroll
;         for (int ai = 0; ai < 2; ++ai)
; #pragma unroll
;             for (int m = 0; m < 4; ++m) { const int row = row0 + ai * HALF + m * 16; const float rs = rsqrtf(ep[ai * 4 + m] * (1.0f / 1024.0f) + EPS);
;                 u16* rowp = O + (size_t)row * ldc + col0;
; #pragma unroll
;                 for (int bj = 0; bj < 2; ++bj) { f32x4 v0 = acc[ai][bj][m][0] * rs, v1 = acc[ai][bj][m][1] * rs;
;                     if (ACT == 1) {
; #pragma unroll
;                         for (int j = 0; j < 4; ++j) { const float a0 = fmaxf(v0[j], 0.f), a1 = fmaxf(v1[j], 0.f); v0[j] = a0 * a0; v1[j] = a1 * a1; } }
;                     u32x4 w; w.x = pk2(v0[0], v0[1]); w.y = pk2(v0[2], v0[3]); w.z = pk2(v1[0], v1[1]); w.w = pk2(v1[2], v1[3]);
;                     *(u32x4*)(rowp + bj * HALF) = w; } }
; template <class Epi>
; __device__ __forceinline__ void gemm_phase(LAS unsigned char* lds, const Gemm g, const StaticOrder& S, const Epi& E) {
;     ...
;             PG8_BAR; PG8_WAIT_L(0); PG8_MMA(1, 0, At, B0); PG8_BAR; PG8_SCHED;
;             PG8_STAGE(PG8_SB(1, 1), b3 + hstepB, voffB);
;             PG8_WAIT_V(6); PG8_BAR; PG8_MMA(1, 1, At, B1); PG8_BAR;
	s_waitcnt lgkmcnt(0)
	v_mfma_f32_16x16x32_bf16 v[60:63], v[146:149], v[166:169], v[60:63]
	v_mfma_f32_16x16x32_bf16 v[56:59], v[158:161], v[166:169], v[56:59]
	v_mfma_f32_16x16x32_bf16 v[44:47], v[146:149], v[182:185], v[44:47]
	v_mfma_f32_16x16x32_bf16 v[40:43], v[158:161], v[182:185], v[40:43]
	v_mfma_f32_16x16x32_bf16 v[28:31], v[146:149], v[190:193], v[28:31]
	v_mfma_f32_16x16x32_bf16 v[24:27], v[158:161], v[190:193], v[24:27]
	v_mfma_f32_16x16x32_bf16 v[12:15], v[146:149], v[198:201], v[12:15]
	v_mfma_f32_16x16x32_bf16 v[8:11], v[158:161], v[198:201], v[8:11]
	v_mfma_f32_16x16x32_bf16 v[60:63], v[154:157], v[170:173], v[60:63]
	v_mfma_f32_16x16x32_bf16 v[56:59], v[162:165], v[170:173], v[56:59]
	v_mfma_f32_16x16x32_bf16 v[44:47], v[154:157], v[186:189], v[44:47]
	v_mfma_f32_16x16x32_bf16 v[40:43], v[162:165], v[186:189], v[40:43]
	v_mfma_f32_16x16x32_bf16 v[28:31], v[154:157], v[194:197], v[28:31]
	v_mfma_f32_16x16x32_bf16 v[24:27], v[162:165], v[194:197], v[24:27]
	v_mfma_f32_16x16x32_bf16 v[12:15], v[154:157], v[202:205], v[12:15]
	v_mfma_f32_16x16x32_bf16 v[8:11], v[162:165], v[202:205], v[8:11]
	s_barrier
	s_add_u32 s22, s22, 0x40080
	s_addc_u32 s23, s23, 0
	s_add_i32 s24, s24, s29
	v_lshl_add_u64 v[146:147], s[22:23], 0, v[130:131]
	s_mov_b32 m0, s24
	s_nop 0
	global_load_lds_dwordx4 v[146:147], off
	v_lshl_add_u64 v[146:147], s[22:23], 0, v[134:135]
	s_add_i32 m0, s24, 0x2000
	s_nop 0
	global_load_lds_dwordx4 v[146:147], off
	s_waitcnt vmcnt(6)
	s_barrier
	v_mfma_f32_16x16x32_bf16 v[52:55], v[206:209], v[166:169], v[52:55]
	v_mfma_f32_16x16x32_bf16 v[48:51], v[214:217], v[166:169], v[48:51]
	v_mfma_f32_16x16x32_bf16 v[36:39], v[206:209], v[182:185], v[36:39]
	v_mfma_f32_16x16x32_bf16 v[32:35], v[214:217], v[182:185], v[32:35]
	v_mfma_f32_16x16x32_bf16 v[20:23], v[206:209], v[190:193], v[20:23]
	v_mfma_f32_16x16x32_bf16 v[16:19], v[214:217], v[190:193], v[16:19]
	v_mfma_f32_16x16x32_bf16 v[4:7], v[206:209], v[198:201], v[4:7]
	v_mfma_f32_16x16x32_bf16 v[0:3], v[214:217], v[198:201], v[0:3]
	v_mfma_f32_16x16x32_bf16 v[52:55], v[210:213], v[170:173], v[52:55]
	v_mfma_f32_16x16x32_bf16 v[48:51], v[218:221], v[170:173], v[48:51]
	v_mfma_f32_16x16x32_bf16 v[36:39], v[210:213], v[186:189], v[36:39]
	v_mfma_f32_16x16x32_bf16 v[32:35], v[218:221], v[186:189], v[32:35]
	v_mfma_f32_16x16x32_bf16 v[20:23], v[210:213], v[194:197], v[20:23]
	v_mfma_f32_16x16x32_bf16 v[16:19], v[218:221], v[194:197], v[16:19]
	v_mfma_f32_16x16x32_bf16 v[4:7], v[210:213], v[202:205], v[4:7]
	v_mfma_f32_16x16x32_bf16 v[0:3], v[218:221], v[202:205], v[0:3]
	s_add_i32 s45, s45, 2
	s_add_u32 s20, s20, 0x100
	s_addc_u32 s21, s21, 0
	s_add_u32 s43, s43, 0x100
	s_addc_u32 s44, s44, 0
	s_cmp_gt_u32 s45, 13
	s_barrier
	s_cbranch_scc0 .LBB0_770
	s_setprio 0
	s_cmp_ge_u32 s98, 0x100
	s_cbranch_scc0 .Lep2_skip
	s_setprio 1
.Lep2_skip:
	s_bfe_u32 vcc_lo, s18, 0x20003
	s_lshl_b32 vcc_lo, vcc_lo, 10
	s_add_i32 vcc_lo, vcc_lo, 0x20010
	v_lshl_add_u32 v236, v174, 2, vcc_lo
	ds_read_b32 v228, v236
	ds_read_b32 v229, v236 offset:64
	ds_read_b32 v230, v236 offset:128
	ds_read_b32 v231, v236 offset:192
	ds_read_b32 v232, v236 offset:512
	ds_read_b32 v233, v236 offset:576
	ds_read_b32 v234, v236 offset:640
	ds_read_b32 v235, v236 offset:704
	s_waitcnt lgkmcnt(0)
	v_lshl_add_u32 v148, s18, 8, v174
	v_ashrrev_i32_e32 v149, 31, v148
	v_or_b32_e32 v172, 16, v148
	v_ashrrev_i32_e32 v173, 31, v172
	v_or_b32_e32 v168, 32, v148
	v_or_b32_e32 v164, 48, v148
	v_ashrrev_i32_e32 v169, 31, v168
	v_ashrrev_i32_e32 v165, 31, v164
	v_add_u32_e32 v162, 0x80, v148
	v_add_u32_e32 v156, 0x90, v148
	v_ashrrev_i32_e32 v163, 31, v162
	v_ashrrev_i32_e32 v157, 31, v156
	v_add_u32_e32 v150, 0xa0, v148
	v_ashrrev_i32_e32 v151, 31, v150
	v_add_u32_e32 v146, 0xb0, v148
	v_ashrrev_i32_e32 v147, 31, v146
	v_lshl_or_b32 v166, s40, 8, v176
	v_ashrrev_i32_e32 v167, 31, v166
	v_lshlrev_b64 v[170:171], 13, v[148:149]
	v_lshlrev_b64 v[148:149], 1, v[166:167]
	v_lshl_add_u64 v[166:167], s[96:97], 0, v[170:171]
	v_lshl_add_u64 v[212:213], v[166:167], 0, v[148:149]
	s_mov_b32 s40, s10
	s_mov_b32 s18, s12
	s_mov_b64 s[22:23], s[16:17]
	s_mov_b64 s[20:21], s[14:15]
	s_waitcnt vmcnt(8)
	s_waitcnt lgkmcnt(0)
	s_waitcnt lgkmcnt(0)
	v_mov_b32_e32 v184, v228
	v_pk_mul_f32 v[120:121], v[120:121], v[184:185] op_sel_hi:[1,0]
	v_pk_mul_f32 v[126:127], v[126:127], v[184:185] op_sel_hi:[1,0]
	v_pk_mul_f32 v[124:125], v[124:125], v[184:185] op_sel_hi:[1,0]
	v_pk_mul_f32 v[122:123], v[122:123], v[184:185] op_sel_hi:[1,0]
	v_max_f32_e32 v120, 0, v120
	v_max_f32_e32 v121, 0, v121
	v_max_f32_e32 v124, 0, v124
	v_max_f32_e32 v125, 0, v125
	v_pk_mul_f32 v[190:191], v[120:121], v[120:121]
	v_max_f32_e32 v120, 0, v126
	v_max_f32_e32 v122, 0, v122
	v_max_f32_e32 v121, 0, v127
	v_max_f32_e32 v123, 0, v123
	v_pk_mul_f32 v[124:125], v[124:125], v[124:125]
	v_pk_mul_f32 v[126:127], v[120:121], v[120:121]
	v_pk_mul_f32 v[194:195], v[122:123], v[122:123]
	v_pk_mul_f32 v[114:115], v[114:115], v[184:185] op_sel_hi:[1,0]
	v_cvt_pk_bf16_f32 v120, v124, v125
	v_cvt_pk_bf16_f32 v121, v126, v127
	v_cvt_pk_bf16_f32 v122, v190, v191
	v_cvt_pk_bf16_f32 v123, v194, v195
	v_pk_mul_f32 v[116:117], v[116:117], v[184:185] op_sel_hi:[1,0]
	v_pk_mul_f32 v[112:113], v[112:113], v[184:185] op_sel_hi:[1,0]
	v_max_f32_e32 v114, 0, v114
	v_max_f32_e32 v115, 0, v115
	global_store_dwordx4 v[212:213], v[120:123], off
	v_pk_mul_f32 v[118:119], v[118:119], v[184:185] op_sel_hi:[1,0]
	v_max_f32_e32 v116, 0, v116
	v_max_f32_e32 v112, 0, v112
	v_max_f32_e32 v117, 0, v117
	v_max_f32_e32 v113, 0, v113
	v_pk_mul_f32 v[122:123], v[114:115], v[114:115]
	v_pk_mul_f32 v[116:117], v[116:117], v[116:117]
; __device__ __forceinline__ unsigned pk2(float lo, float hi) { const f32x2 v = (f32x2){lo, hi}; const bf16x2_t b = __builtin_convertvector(v, bf16x2_t); return __builtin_bit_cast(unsigned, b); }
;     __device__ __forceinline__ void operator()(const f32x4 (&acc)[2][2][4][2], const Unit& u, int wr, int wc, int fr, int fq, const float (&)[8]) const {
;     ...
;             for (int m = 0; m < 4; ++m) { const int row = row0 + ai * HALF + m * 16; const float rs = rsqrtf(ep[ai * 4 + m] * (1.0f / 1024.0f) + EPS);
;                 u16* rowp = O + (size_t)row * ldc + col0;
; #pragma unroll
;                 for (int bj = 0; bj < 2; ++bj) { f32x4 v0 = acc[ai][bj][m][0] * rs, v1 = acc[ai][bj][m][1] * rs;
;                     if (ACT == 1) {
; #pragma unroll
;                         for (int j = 0; j < 4; ++j) { const float a0 = fmaxf(v0[j], 0.f), a1 = fmaxf(v1[j], 0.f); v0[j] = a0 * a0; v1[j] = a1 * a1; } }
;                     u32x4 w; w.x = pk2(v0[0], v0[1]); w.y = pk2(v0[2], v0[3]); w.z = pk2(v1[0], v1[1]); w.w = pk2(v1[2], v1[3]);
;                     *(u32x4*)(rowp + bj * HALF) = w; } }
	v_pk_mul_f32 v[120:121], v[112:113], v[112:113]
	v_max_f32_e32 v112, 0, v118
	v_max_f32_e32 v113, 0, v119
	v_pk_mul_f32 v[118:119], v[112:113], v[112:113]
	v_cvt_pk_bf16_f32 v112, v116, v117
	v_cvt_pk_bf16_f32 v113, v118, v119
	v_cvt_pk_bf16_f32 v114, v120, v121
	v_cvt_pk_bf16_f32 v115, v122, v123
	global_store_dwordx4 v[212:213], v[112:115], off offset:256
	s_nop 1
	v_mov_b32_e32 v112, v229
	v_pk_mul_f32 v[104:105], v[104:105], v[112:113] op_sel_hi:[1,0]
	v_pk_mul_f32 v[110:111], v[110:111], v[112:113] op_sel_hi:[1,0]
	v_pk_mul_f32 v[108:109], v[108:109], v[112:113] op_sel_hi:[1,0]
	v_pk_mul_f32 v[106:107], v[106:107], v[112:113] op_sel_hi:[1,0]
	v_max_f32_e32 v104, 0, v104
	v_max_f32_e32 v105, 0, v105
	v_lshlrev_b64 v[114:115], 13, v[172:173]
	v_max_f32_e32 v108, 0, v108
	v_max_f32_e32 v109, 0, v109
	v_pk_mul_f32 v[116:117], v[104:105], v[104:105]
	v_max_f32_e32 v104, 0, v110
	v_max_f32_e32 v106, 0, v106
	v_max_f32_e32 v105, 0, v111
	v_max_f32_e32 v107, 0, v107
	v_lshl_add_u64 v[114:115], s[96:97], 0, v[114:115]
	v_pk_mul_f32 v[108:109], v[108:109], v[108:109]
	v_pk_mul_f32 v[110:111], v[104:105], v[104:105]
	v_pk_mul_f32 v[118:119], v[106:107], v[106:107]
	v_pk_mul_f32 v[96:97], v[96:97], v[112:113] op_sel_hi:[1,0]
	v_lshl_add_u64 v[114:115], v[114:115], 0, v[148:149]
	v_cvt_pk_bf16_f32 v104, v108, v109
	v_cvt_pk_bf16_f32 v105, v110, v111
	v_cvt_pk_bf16_f32 v106, v116, v117
	v_cvt_pk_bf16_f32 v107, v118, v119
	v_pk_mul_f32 v[102:103], v[102:103], v[112:113] op_sel_hi:[1,0]
	v_max_f32_e32 v96, 0, v96
	v_max_f32_e32 v97, 0, v97
	global_store_dwordx4 v[114:115], v[104:107], off
	v_pk_mul_f32 v[100:101], v[100:101], v[112:113] op_sel_hi:[1,0]
	v_pk_mul_f32 v[98:99], v[98:99], v[112:113] op_sel_hi:[1,0]
	v_pk_mul_f32 v[104:105], v[96:97], v[96:97]
	v_max_f32_e32 v96, 0, v102
	v_max_f32_e32 v97, 0, v103
	v_max_f32_e32 v100, 0, v100
	v_max_f32_e32 v101, 0, v101
	v_pk_mul_f32 v[100:101], v[100:101], v[100:101]
	v_pk_mul_f32 v[108:109], v[96:97], v[96:97]
	v_cvt_pk_bf16_f32 v96, v100, v101
	s_waitcnt lgkmcnt(0)
	v_max_f32_e32 v98, 0, v98
	v_max_f32_e32 v99, 0, v99
	v_pk_mul_f32 v[110:111], v[98:99], v[98:99]
	v_cvt_pk_bf16_f32 v97, v108, v109
	v_cvt_pk_bf16_f32 v98, v104, v105
	v_cvt_pk_bf16_f32 v99, v110, v111
	global_store_dwordx4 v[114:115], v[96:99], off offset:256
	s_waitcnt lgkmcnt(0)
	s_nop 0
	s_nop 0
	s_nop 0
	s_nop 1
	v_lshlrev_b64 v[98:99], 13, v[168:169]
	v_lshl_add_u64 v[98:99], s[96:97], 0, v[98:99]
	v_lshl_add_u64 v[98:99], v[98:99], 0, v[148:149]
	v_mov_b32_e32 v100, v230
	v_pk_mul_f32 v[88:89], v[88:89], v[100:101] op_sel_hi:[1,0]
	v_pk_mul_f32 v[94:95], v[94:95], v[100:101] op_sel_hi:[1,0]
	v_pk_mul_f32 v[92:93], v[92:93], v[100:101] op_sel_hi:[1,0]
	v_pk_mul_f32 v[90:91], v[90:91], v[100:101] op_sel_hi:[1,0]
	v_max_f32_e32 v88, 0, v88
	v_max_f32_e32 v89, 0, v89
	v_max_f32_e32 v92, 0, v92
	v_max_f32_e32 v93, 0, v93
	v_pk_mul_f32 v[102:103], v[88:89], v[88:89]
	v_max_f32_e32 v88, 0, v94
	v_max_f32_e32 v90, 0, v90
	v_max_f32_e32 v89, 0, v95
	v_max_f32_e32 v91, 0, v91
	v_pk_mul_f32 v[92:93], v[92:93], v[92:93]
	v_pk_mul_f32 v[94:95], v[88:89], v[88:89]
	v_pk_mul_f32 v[104:105], v[90:91], v[90:91]
	v_pk_mul_f32 v[82:83], v[82:83], v[100:101] op_sel_hi:[1,0]
	v_cvt_pk_bf16_f32 v88, v92, v93
	v_cvt_pk_bf16_f32 v89, v94, v95
	v_cvt_pk_bf16_f32 v90, v102, v103
	v_cvt_pk_bf16_f32 v91, v104, v105
	v_pk_mul_f32 v[84:85], v[84:85], v[100:101] op_sel_hi:[1,0]
	v_pk_mul_f32 v[80:81], v[80:81], v[100:101] op_sel_hi:[1,0]
	v_max_f32_e32 v82, 0, v82
	v_max_f32_e32 v83, 0, v83
	global_store_dwordx4 v[98:99], v[88:91], off
	v_pk_mul_f32 v[86:87], v[86:87], v[100:101] op_sel_hi:[1,0]
	v_max_f32_e32 v84, 0, v84
	v_max_f32_e32 v80, 0, v80
	v_max_f32_e32 v85, 0, v85
	v_max_f32_e32 v81, 0, v81
	v_pk_mul_f32 v[90:91], v[82:83], v[82:83]
	v_pk_mul_f32 v[84:85], v[84:85], v[84:85]
	v_pk_mul_f32 v[88:89], v[80:81], v[80:81]
	v_max_f32_e32 v80, 0, v86
	v_max_f32_e32 v81, 0, v87
	v_pk_mul_f32 v[86:87], v[80:81], v[80:81]
	v_cvt_pk_bf16_f32 v80, v84, v85
	v_cvt_pk_bf16_f32 v81, v86, v87
	v_cvt_pk_bf16_f32 v82, v88, v89
	v_cvt_pk_bf16_f32 v83, v90, v91
	global_store_dwordx4 v[98:99], v[80:83], off offset:256
	s_nop 1
	v_mov_b32_e32 v80, v231
	v_pk_mul_f32 v[72:73], v[72:73], v[80:81] op_sel_hi:[1,0]
	v_pk_mul_f32 v[78:79], v[78:79], v[80:81] op_sel_hi:[1,0]
	v_pk_mul_f32 v[76:77], v[76:77], v[80:81] op_sel_hi:[1,0]
	v_pk_mul_f32 v[74:75], v[74:75], v[80:81] op_sel_hi:[1,0]
	v_max_f32_e32 v72, 0, v72
	v_max_f32_e32 v73, 0, v73
	v_lshlrev_b64 v[82:83], 13, v[164:165]
	v_max_f32_e32 v76, 0, v76
	v_max_f32_e32 v77, 0, v77
	v_pk_mul_f32 v[84:85], v[72:73], v[72:73]
	v_max_f32_e32 v72, 0, v78
	v_max_f32_e32 v74, 0, v74
	v_max_f32_e32 v73, 0, v79
	v_max_f32_e32 v75, 0, v75
	v_lshl_add_u64 v[82:83], s[96:97], 0, v[82:83]
	v_pk_mul_f32 v[76:77], v[76:77], v[76:77]
	v_pk_mul_f32 v[78:79], v[72:73], v[72:73]
	v_pk_mul_f32 v[86:87], v[74:75], v[74:75]
	v_pk_mul_f32 v[64:65], v[64:65], v[80:81] op_sel_hi:[1,0]
	v_lshl_add_u64 v[82:83], v[82:83], 0, v[148:149]
	v_cvt_pk_bf16_f32 v72, v76, v77
	v_cvt_pk_bf16_f32 v73, v78, v79
	v_cvt_pk_bf16_f32 v74, v84, v85
	v_cvt_pk_bf16_f32 v75, v86, v87
	v_pk_mul_f32 v[70:71], v[70:71], v[80:81] op_sel_hi:[1,0]
	v_max_f32_e32 v64, 0, v64
	v_max_f32_e32 v65, 0, v65
	global_store_dwordx4 v[82:83], v[72:75], off
	v_pk_mul_f32 v[68:69], v[68:69], v[80:81] op_sel_hi:[1,0]
	v_pk_mul_f32 v[66:67], v[66:67], v[80:81] op_sel_hi:[1,0]
	v_pk_mul_f32 v[72:73], v[64:65], v[64:65]
	v_max_f32_e32 v64, 0, v70
	v_max_f32_e32 v65, 0, v71
	v_max_f32_e32 v68, 0, v68
	v_max_f32_e32 v69, 0, v69
	v_pk_mul_f32 v[68:69], v[68:69], v[68:69]
	v_pk_mul_f32 v[76:77], v[64:65], v[64:65]
	v_cvt_pk_bf16_f32 v64, v68, v69
	s_waitcnt lgkmcnt(0)
; __device__ __forceinline__ unsigned pk2(float lo, float hi) { const f32x2 v = (f32x2){lo, hi}; const bf16x2_t b = __builtin_convertvector(v, bf16x2_t); return __builtin_bit_cast(unsigned, b); }
;     __device__ __forceinline__ void operator()(const f32x4 (&acc)[2][2][4][2], const Unit& u, int wr, int wc, int fr, int fq, const float (&)[8]) const {
;     ...
;             for (int m = 0; m < 4; ++m) { const int row = row0 + ai * HALF + m * 16; const float rs = rsqrtf(ep[ai * 4 + m] * (1.0f / 1024.0f) + EPS);
;                 u16* rowp = O + (size_t)row * ldc + col0;
; #pragma unroll
;                 for (int bj = 0; bj < 2; ++bj) { f32x4 v0 = acc[ai][bj][m][0] * rs, v1 = acc[ai][bj][m][1] * rs;
;                     if (ACT == 1) {
; #pragma unroll
;                         for (int j = 0; j < 4; ++j) { const float a0 = fmaxf(v0[j], 0.f), a1 = fmaxf(v1[j], 0.f); v0[j] = a0 * a0; v1[j] = a1 * a1; } }
;                     u32x4 w; w.x = pk2(v0[0], v0[1]); w.y = pk2(v0[2], v0[3]); w.z = pk2(v1[0], v1[1]); w.w = pk2(v1[2], v1[3]);
;                     *(u32x4*)(rowp + bj * HALF) = w; } }
	v_max_f32_e32 v66, 0, v66
	v_max_f32_e32 v67, 0, v67
	v_pk_mul_f32 v[78:79], v[66:67], v[66:67]
	v_cvt_pk_bf16_f32 v65, v76, v77
	v_cvt_pk_bf16_f32 v66, v72, v73
	v_cvt_pk_bf16_f32 v67, v78, v79
	global_store_dwordx4 v[82:83], v[64:67], off offset:256
	s_waitcnt lgkmcnt(0)
	s_nop 0
	s_nop 0
	s_nop 0
	s_nop 1
	v_lshlrev_b64 v[66:67], 13, v[162:163]
	v_lshl_add_u64 v[66:67], s[96:97], 0, v[66:67]
	v_lshl_add_u64 v[66:67], v[66:67], 0, v[148:149]
	v_mov_b32_e32 v68, v232
	v_pk_mul_f32 v[56:57], v[56:57], v[68:69] op_sel_hi:[1,0]
	v_pk_mul_f32 v[62:63], v[62:63], v[68:69] op_sel_hi:[1,0]
	v_pk_mul_f32 v[60:61], v[60:61], v[68:69] op_sel_hi:[1,0]
	v_pk_mul_f32 v[58:59], v[58:59], v[68:69] op_sel_hi:[1,0]
	v_max_f32_e32 v56, 0, v56
	v_max_f32_e32 v57, 0, v57
	v_max_f32_e32 v60, 0, v60
	v_max_f32_e32 v61, 0, v61
	v_pk_mul_f32 v[70:71], v[56:57], v[56:57]
	v_max_f32_e32 v56, 0, v62
	v_max_f32_e32 v58, 0, v58
	v_max_f32_e32 v57, 0, v63
	v_max_f32_e32 v59, 0, v59
	v_pk_mul_f32 v[60:61], v[60:61], v[60:61]
	v_pk_mul_f32 v[62:63], v[56:57], v[56:57]
	v_pk_mul_f32 v[72:73], v[58:59], v[58:59]
	v_pk_mul_f32 v[50:51], v[50:51], v[68:69] op_sel_hi:[1,0]
	v_cvt_pk_bf16_f32 v56, v60, v61
	v_cvt_pk_bf16_f32 v57, v62, v63
	v_cvt_pk_bf16_f32 v58, v70, v71
	v_cvt_pk_bf16_f32 v59, v72, v73
	v_pk_mul_f32 v[52:53], v[52:53], v[68:69] op_sel_hi:[1,0]
	v_pk_mul_f32 v[48:49], v[48:49], v[68:69] op_sel_hi:[1,0]
	v_max_f32_e32 v50, 0, v50
	v_max_f32_e32 v51, 0, v51
	global_store_dwordx4 v[66:67], v[56:59], off
	v_pk_mul_f32 v[54:55], v[54:55], v[68:69] op_sel_hi:[1,0]
	v_max_f32_e32 v52, 0, v52
	v_max_f32_e32 v48, 0, v48
	v_max_f32_e32 v53, 0, v53
	v_max_f32_e32 v49, 0, v49
	v_pk_mul_f32 v[58:59], v[50:51], v[50:51]
	v_pk_mul_f32 v[52:53], v[52:53], v[52:53]
	v_pk_mul_f32 v[56:57], v[48:49], v[48:49]
	v_max_f32_e32 v48, 0, v54
	v_max_f32_e32 v49, 0, v55
	v_pk_mul_f32 v[54:55], v[48:49], v[48:49]
	v_cvt_pk_bf16_f32 v48, v52, v53
	v_cvt_pk_bf16_f32 v49, v54, v55
	v_cvt_pk_bf16_f32 v50, v56, v57
	v_cvt_pk_bf16_f32 v51, v58, v59
	global_store_dwordx4 v[66:67], v[48:51], off offset:256
	s_nop 1
	v_mov_b32_e32 v48, v233
	v_pk_mul_f32 v[40:41], v[40:41], v[48:49] op_sel_hi:[1,0]
	v_pk_mul_f32 v[46:47], v[46:47], v[48:49] op_sel_hi:[1,0]
	v_pk_mul_f32 v[44:45], v[44:45], v[48:49] op_sel_hi:[1,0]
	v_pk_mul_f32 v[42:43], v[42:43], v[48:49] op_sel_hi:[1,0]
	v_max_f32_e32 v40, 0, v40
	v_max_f32_e32 v41, 0, v41
	v_lshlrev_b64 v[50:51], 13, v[156:157]
	v_max_f32_e32 v44, 0, v44
	v_max_f32_e32 v45, 0, v45
	v_pk_mul_f32 v[52:53], v[40:41], v[40:41]
	v_max_f32_e32 v40, 0, v46
	v_max_f32_e32 v42, 0, v42
	v_max_f32_e32 v41, 0, v47
	v_max_f32_e32 v43, 0, v43
	v_lshl_add_u64 v[50:51], s[96:97], 0, v[50:51]
	v_pk_mul_f32 v[44:45], v[44:45], v[44:45]
	v_pk_mul_f32 v[46:47], v[40:41], v[40:41]
	v_pk_mul_f32 v[54:55], v[42:43], v[42:43]
	v_pk_mul_f32 v[32:33], v[32:33], v[48:49] op_sel_hi:[1,0]
	v_lshl_add_u64 v[50:51], v[50:51], 0, v[148:149]
	v_cvt_pk_bf16_f32 v40, v44, v45
	v_cvt_pk_bf16_f32 v41, v46, v47
	v_cvt_pk_bf16_f32 v42, v52, v53
	v_cvt_pk_bf16_f32 v43, v54, v55
	v_pk_mul_f32 v[38:39], v[38:39], v[48:49] op_sel_hi:[1,0]
	v_max_f32_e32 v32, 0, v32
	v_max_f32_e32 v33, 0, v33
	global_store_dwordx4 v[50:51], v[40:43], off
	v_pk_mul_f32 v[36:37], v[36:37], v[48:49] op_sel_hi:[1,0]
	v_pk_mul_f32 v[34:35], v[34:35], v[48:49] op_sel_hi:[1,0]
	v_pk_mul_f32 v[40:41], v[32:33], v[32:33]
	v_max_f32_e32 v32, 0, v38
	v_max_f32_e32 v33, 0, v39
	v_max_f32_e32 v36, 0, v36
	v_max_f32_e32 v37, 0, v37
	v_pk_mul_f32 v[36:37], v[36:37], v[36:37]
	v_pk_mul_f32 v[44:45], v[32:33], v[32:33]
	v_cvt_pk_bf16_f32 v32, v36, v37
	s_waitcnt lgkmcnt(0)
	v_max_f32_e32 v34, 0, v34
	v_max_f32_e32 v35, 0, v35
	v_pk_mul_f32 v[46:47], v[34:35], v[34:35]
	v_cvt_pk_bf16_f32 v33, v44, v45
	v_cvt_pk_bf16_f32 v34, v40, v41
	v_cvt_pk_bf16_f32 v35, v46, v47
	global_store_dwordx4 v[50:51], v[32:35], off offset:256
	s_waitcnt lgkmcnt(0)
; __device__ __forceinline__ unsigned pk2(float lo, float hi) { const f32x2 v = (f32x2){lo, hi}; const bf16x2_t b = __builtin_convertvector(v, bf16x2_t); return __builtin_bit_cast(unsigned, b); }
; #define PG8_WAIT_V(n) asm volatile("s_waitcnt vmcnt(" #n ")" ::: "memory")
; #define PG8_BAR __builtin_amdgcn_s_barrier()
;     __device__ __forceinline__ void operator()(const f32x4 (&acc)[2][2][4][2], const Unit& u, int wr, int wc, int fr, int fq, const float (&)[8]) const {
;     ...
;             for (int m = 0; m < 4; ++m) { const int row = row0 + ai * HALF + m * 16; const float rs = rsqrtf(ep[ai * 4 + m] * (1.0f / 1024.0f) + EPS);
;                 u16* rowp = O + (size_t)row * ldc + col0;
; #pragma unroll
;                 for (int bj = 0; bj < 2; ++bj) { f32x4 v0 = acc[ai][bj][m][0] * rs, v1 = acc[ai][bj][m][1] * rs;
;                     if (ACT == 1) {
; #pragma unroll
;                         for (int j = 0; j < 4; ++j) { const float a0 = fmaxf(v0[j], 0.f), a1 = fmaxf(v1[j], 0.f); v0[j] = a0 * a0; v1[j] = a1 * a1; } }
;                     u32x4 w; w.x = pk2(v0[0], v0[1]); w.y = pk2(v0[2], v0[3]); w.z = pk2(v1[0], v1[1]); w.w = pk2(v1[2], v1[3]);
;                     *(u32x4*)(rowp + bj * HALF) = w; } }
; template <class Epi>
; __device__ __forceinline__ void gemm_phase(LAS unsigned char* lds, const Gemm g, const StaticOrder& S, const Epi& E) {
;     ...
;         if (!has_next) break;
; #pragma unroll
;         for (int a = 0; a < 2; ++a)
; #pragma unroll
;             for (int b = 0; b < 2; ++b)
; #pragma unroll
;                 for (int m = 0; m < 4; ++m)
; #pragma unroll
;                     for (int n = 0; n < 2; ++n) acc[a][b][m][n] = (f32x4){0.f, 0.f, 0.f, 0.f};
;         cur = nxt; cA = nA; cB = nB; ++ui;
;     }
;     PG8_WAIT_V(0);
;     if (wr == 0) PG8_BAR;
	s_nop 0
	s_nop 0
	s_nop 0
	s_nop 1
	v_lshlrev_b64 v[34:35], 13, v[150:151]
	v_lshl_add_u64 v[34:35], s[96:97], 0, v[34:35]
	v_lshl_add_u64 v[34:35], v[34:35], 0, v[148:149]
	v_mov_b32_e32 v36, v234
	v_pk_mul_f32 v[24:25], v[24:25], v[36:37] op_sel_hi:[1,0]
	v_pk_mul_f32 v[30:31], v[30:31], v[36:37] op_sel_hi:[1,0]
	v_pk_mul_f32 v[28:29], v[28:29], v[36:37] op_sel_hi:[1,0]
	v_pk_mul_f32 v[26:27], v[26:27], v[36:37] op_sel_hi:[1,0]
	v_max_f32_e32 v24, 0, v24
	v_max_f32_e32 v25, 0, v25
	v_max_f32_e32 v28, 0, v28
	v_max_f32_e32 v29, 0, v29
	v_pk_mul_f32 v[38:39], v[24:25], v[24:25]
	v_max_f32_e32 v24, 0, v30
	v_max_f32_e32 v26, 0, v26
	v_max_f32_e32 v25, 0, v31
	v_max_f32_e32 v27, 0, v27
	v_pk_mul_f32 v[28:29], v[28:29], v[28:29]
	v_pk_mul_f32 v[30:31], v[24:25], v[24:25]
	v_pk_mul_f32 v[40:41], v[26:27], v[26:27]
	v_pk_mul_f32 v[18:19], v[18:19], v[36:37] op_sel_hi:[1,0]
	v_cvt_pk_bf16_f32 v24, v28, v29
	v_cvt_pk_bf16_f32 v25, v30, v31
	v_cvt_pk_bf16_f32 v26, v38, v39
	v_cvt_pk_bf16_f32 v27, v40, v41
	v_pk_mul_f32 v[20:21], v[20:21], v[36:37] op_sel_hi:[1,0]
	v_pk_mul_f32 v[16:17], v[16:17], v[36:37] op_sel_hi:[1,0]
	v_max_f32_e32 v18, 0, v18
	v_max_f32_e32 v19, 0, v19
	global_store_dwordx4 v[34:35], v[24:27], off
	v_pk_mul_f32 v[22:23], v[22:23], v[36:37] op_sel_hi:[1,0]
	v_max_f32_e32 v20, 0, v20
	v_max_f32_e32 v16, 0, v16
	v_max_f32_e32 v21, 0, v21
	v_max_f32_e32 v17, 0, v17
	v_pk_mul_f32 v[26:27], v[18:19], v[18:19]
	v_pk_mul_f32 v[20:21], v[20:21], v[20:21]
	v_pk_mul_f32 v[24:25], v[16:17], v[16:17]
	v_max_f32_e32 v16, 0, v22
	v_max_f32_e32 v17, 0, v23
	v_pk_mul_f32 v[22:23], v[16:17], v[16:17]
	v_cvt_pk_bf16_f32 v16, v20, v21
	v_cvt_pk_bf16_f32 v17, v22, v23
	v_cvt_pk_bf16_f32 v18, v24, v25
	v_cvt_pk_bf16_f32 v19, v26, v27
	global_store_dwordx4 v[34:35], v[16:19], off offset:256
	s_nop 1
	v_mov_b32_e32 v16, v235
	v_pk_mul_f32 v[8:9], v[8:9], v[16:17] op_sel_hi:[1,0]
	v_pk_mul_f32 v[14:15], v[14:15], v[16:17] op_sel_hi:[1,0]
	v_pk_mul_f32 v[12:13], v[12:13], v[16:17] op_sel_hi:[1,0]
	v_pk_mul_f32 v[10:11], v[10:11], v[16:17] op_sel_hi:[1,0]
	v_max_f32_e32 v8, 0, v8
	v_max_f32_e32 v9, 0, v9
	v_lshlrev_b64 v[18:19], 13, v[146:147]
	v_max_f32_e32 v12, 0, v12
	v_max_f32_e32 v13, 0, v13
	v_pk_mul_f32 v[20:21], v[8:9], v[8:9]
	v_max_f32_e32 v8, 0, v14
	v_max_f32_e32 v10, 0, v10
	v_max_f32_e32 v9, 0, v15
	v_max_f32_e32 v11, 0, v11
	v_lshl_add_u64 v[18:19], s[96:97], 0, v[18:19]
	v_pk_mul_f32 v[12:13], v[12:13], v[12:13]
	v_pk_mul_f32 v[14:15], v[8:9], v[8:9]
	v_pk_mul_f32 v[22:23], v[10:11], v[10:11]
	v_pk_mul_f32 v[0:1], v[0:1], v[16:17] op_sel_hi:[1,0]
	v_lshl_add_u64 v[18:19], v[18:19], 0, v[148:149]
	v_cvt_pk_bf16_f32 v8, v12, v13
	v_cvt_pk_bf16_f32 v9, v14, v15
	v_cvt_pk_bf16_f32 v10, v20, v21
	v_cvt_pk_bf16_f32 v11, v22, v23
	v_pk_mul_f32 v[6:7], v[6:7], v[16:17] op_sel_hi:[1,0]
	v_pk_mul_f32 v[4:5], v[4:5], v[16:17] op_sel_hi:[1,0]
	v_pk_mul_f32 v[2:3], v[2:3], v[16:17] op_sel_hi:[1,0]
	v_max_f32_e32 v0, 0, v0
	v_max_f32_e32 v1, 0, v1
	global_store_dwordx4 v[18:19], v[8:11], off
	v_max_f32_e32 v4, 0, v4
	v_max_f32_e32 v5, 0, v5
	v_pk_mul_f32 v[8:9], v[0:1], v[0:1]
	v_max_f32_e32 v0, 0, v6
	v_max_f32_e32 v2, 0, v2
	v_max_f32_e32 v1, 0, v7
	v_max_f32_e32 v3, 0, v3
	v_pk_mul_f32 v[4:5], v[4:5], v[4:5]
	v_pk_mul_f32 v[6:7], v[0:1], v[0:1]
	v_pk_mul_f32 v[10:11], v[2:3], v[2:3]
	v_cvt_pk_bf16_f32 v0, v4, v5
	v_cvt_pk_bf16_f32 v1, v6, v7
	v_cvt_pk_bf16_f32 v2, v8, v9
	v_cvt_pk_bf16_f32 v3, v10, v11
	s_and_b64 vcc, exec, s[0:1]
	global_store_dwordx4 v[18:19], v[0:3], off offset:256
	s_cbranch_vccz .LBB0_763
	s_waitcnt vmcnt(0)
	s_cmpk_gt_u32 s9, 0xff
	s_cbranch_scc1 .LBB0_774
	s_barrier

; #define PG8_STAGE(bufoff, gbase, voff) do { _Pragma("unroll") for (int _i = 0; _i < 2; ++_i) \
;         __builtin_amdgcn_global_load_lds((const unsigned*)((const char*)(gbase) + (voff)[_i]), (LAS unsigned*)(lds + (bufoff) + ldsw + _i * 8192), 16, 0, 0); } while (0)
; #define PG8_LDA(dst, b, h) do { _Pragma("unroll") for (int m = 0; m < 4; ++m) _Pragma("unroll") for (int k = 0; k < 2; ++k) dst[m][k] = *(const LAS bf16x8*)(lds + PG8_SA(b, h) + aoff + m * 2048 + k * 1024); } while (0)
; #define PG8_LDB(dst, b, h) do { _Pragma("unroll") for (int n = 0; n < 2; ++n) _Pragma("unroll") for (int k = 0; k < 2; ++k) dst[n][k] = *(const LAS bf16x8*)(lds + PG8_SB(b, h) + boff + n * 2048 + k * 1024); } while (0)
; #define PG8_MMA(ai, bj, At, Bt) do { __builtin_amdgcn_s_setprio(1); _Pragma("unroll") for (int m = 0; m < 4; ++m) _Pragma("unroll") for (int n = 0; n < 2; ++n) _Pragma("unroll") for (int k = 0; k < 2; ++k) \
;         acc[ai][bj][m][n] = __builtin_amdgcn_mfma_f32_16x16x32_bf16(Bt[n][k], At[m][k], acc[ai][bj][m][n], 0, 0, 0); __builtin_amdgcn_s_setprio(0); } while (0)
; #define PG8_WAIT_V(n) asm volatile("s_waitcnt vmcnt(" #n ")" ::: "memory")
; #define PG8_WAIT_L(n) asm volatile("s_waitcnt lgkmcnt(" #n ")" ::: "memory")
; #define PG8_BAR __builtin_amdgcn_s_barrier()
; #define PG8_SCHED __builtin_amdgcn_sched_barrier(0)
; template <class Epi>
; __device__ __forceinline__ void gemm_phase(LAS unsigned char* lds, const Gemm g, const StaticOrder& S, const Epi& E) {
;     ...
;             PG8_LDB(B0, 0, 0); PG8_SCHED; PG8_LDA(At, 0, 0); PG8_STAGE(PG8_SA(1, 1), a1 + hstepA, voffA);
;             PG8_WAIT_L(8); PG8_BAR; PG8_WAIT_L(0); PG8_MMA(0, 0, At, B0); PG8_BAR; PG8_SCHED;
;             PG8_LDB(B1, 0, 1); PG8_STAGE(PG8_SB(0, 0), b2, voffB);
;             PG8_BAR; PG8_WAIT_L(0); PG8_MMA(0, 1, At, B1); PG8_BAR;
;             PG8_LDA(At, 0, 1); PG8_STAGE(PG8_SA(0, 0), a2, voffA);
;             PG8_BAR; PG8_WAIT_L(0); PG8_MMA(1, 0, At, B0); PG8_BAR; PG8_SCHED;
;             PG8_STAGE(PG8_SB(0, 1), b2 + hstepB, voffB);
;             PG8_WAIT_V(6); PG8_BAR; PG8_MMA(1, 1, At, B1); PG8_BAR;
.LBB0_844:
	ds_read_b128 v[128:131], v191
	ds_read_b128 v[132:135], v191 offset:1024
	ds_read_b128 v[136:139], v191 offset:2048
	ds_read_b128 v[140:143], v191 offset:3072
	s_add_u32 s24, s22, 0xfff00080
	s_addc_u32 s25, s23, -1
	s_cmp_eq_u32 s48, 60
	s_cselect_b32 s27, s17, s25
	s_cselect_b32 s26, s44, s24
	s_cselect_b32 s25, s15, s47
	s_cselect_b32 s24, s45, s46
	v_lshl_add_u64 v[186:187], s[22:23], 0, v[162:163]
	s_add_i32 m0, s7, 0xc000
	ds_read_b128 v[144:147], v192
	ds_read_b128 v[148:151], v192 offset:1024
	ds_read_b128 v[170:173], v192 offset:2048
	ds_read_b128 v[174:177], v192 offset:3072
	ds_read_b128 v[178:181], v192 offset:4096
	ds_read_b128 v[182:185], v192 offset:5120
	ds_read_b128 v[196:199], v192 offset:6144
	ds_read_b128 v[200:203], v192 offset:7168
	global_load_lds_dwordx4 v[186:187], off
	v_lshl_add_u64 v[186:187], s[22:23], 0, v[164:165]
	s_add_i32 m0, s7, 0xe000
	s_nop 0
	global_load_lds_dwordx4 v[186:187], off
	s_waitcnt lgkmcnt(8)
	s_barrier
	s_waitcnt lgkmcnt(0)
	v_mfma_f32_16x16x32_bf16 v[124:127], v[128:131], v[144:147], v[124:127]
	v_mfma_f32_16x16x32_bf16 v[120:123], v[136:139], v[144:147], v[120:123]
	v_mfma_f32_16x16x32_bf16 v[108:111], v[128:131], v[170:173], v[108:111]
	v_mfma_f32_16x16x32_bf16 v[104:107], v[136:139], v[170:173], v[104:107]
	v_mfma_f32_16x16x32_bf16 v[92:95], v[128:131], v[178:181], v[92:95]
	v_mfma_f32_16x16x32_bf16 v[88:91], v[136:139], v[178:181], v[88:91]
	v_mfma_f32_16x16x32_bf16 v[76:79], v[128:131], v[196:199], v[76:79]
	v_mfma_f32_16x16x32_bf16 v[72:75], v[136:139], v[196:199], v[72:75]
	v_mfma_f32_16x16x32_bf16 v[124:127], v[132:135], v[148:151], v[124:127]
	v_mfma_f32_16x16x32_bf16 v[120:123], v[140:143], v[148:151], v[120:123]
	v_mfma_f32_16x16x32_bf16 v[108:111], v[132:135], v[174:177], v[108:111]
	v_mfma_f32_16x16x32_bf16 v[104:107], v[140:143], v[174:177], v[104:107]
	v_mfma_f32_16x16x32_bf16 v[92:95], v[132:135], v[182:185], v[92:95]
	v_mfma_f32_16x16x32_bf16 v[88:91], v[140:143], v[182:185], v[88:91]
	v_mfma_f32_16x16x32_bf16 v[76:79], v[132:135], v[200:203], v[76:79]
	v_mfma_f32_16x16x32_bf16 v[72:75], v[140:143], v[200:203], v[72:75]
	s_barrier
	s_add_i32 s49, s42, s31
	v_lshl_add_u64 v[186:187], s[24:25], 0, v[156:157]
	s_mov_b32 m0, s49
	ds_read_b128 v[204:207], v193
	ds_read_b128 v[208:211], v193 offset:1024
	ds_read_b128 v[212:215], v193 offset:2048
	ds_read_b128 v[216:219], v193 offset:3072
	global_load_lds_dwordx4 v[186:187], off
	v_lshl_add_u64 v[220:221], s[24:25], 0, v[160:161]
	s_add_i32 m0, s49, 0x2000
	s_nop 0
	global_load_lds_dwordx4 v[220:221], off
	s_barrier
	s_waitcnt lgkmcnt(0)
	v_mfma_f32_16x16x32_bf16 v[116:119], v[204:207], v[144:147], v[116:119]
	v_mfma_f32_16x16x32_bf16 v[112:115], v[212:215], v[144:147], v[112:115]
	v_mfma_f32_16x16x32_bf16 v[100:103], v[204:207], v[170:173], v[100:103]
	v_mfma_f32_16x16x32_bf16 v[96:99], v[212:215], v[170:173], v[96:99]
	v_mfma_f32_16x16x32_bf16 v[84:87], v[204:207], v[178:181], v[84:87]
	v_mfma_f32_16x16x32_bf16 v[80:83], v[212:215], v[178:181], v[80:83]
	v_mfma_f32_16x16x32_bf16 v[68:71], v[204:207], v[196:199], v[68:71]
	v_mfma_f32_16x16x32_bf16 v[64:67], v[212:215], v[196:199], v[64:67]
	v_mfma_f32_16x16x32_bf16 v[116:119], v[208:211], v[148:151], v[116:119]
	v_mfma_f32_16x16x32_bf16 v[112:115], v[216:219], v[148:151], v[112:115]
	v_mfma_f32_16x16x32_bf16 v[100:103], v[208:211], v[174:177], v[100:103]
	v_mfma_f32_16x16x32_bf16 v[96:99], v[216:219], v[174:177], v[96:99]
	v_mfma_f32_16x16x32_bf16 v[84:87], v[208:211], v[182:185], v[84:87]
	v_mfma_f32_16x16x32_bf16 v[80:83], v[216:219], v[182:185], v[80:83]
	v_mfma_f32_16x16x32_bf16 v[68:71], v[208:211], v[200:203], v[68:71]
	v_mfma_f32_16x16x32_bf16 v[64:67], v[216:219], v[200:203], v[64:67]
	s_mov_b32 m0, s7
	v_lshl_add_u64 v[222:223], s[26:27], 0, v[154:155]
	s_barrier
	ds_read_b128 v[144:147], v192 offset:16384
	ds_read_b128 v[148:151], v192 offset:17408
	ds_read_b128 v[170:173], v192 offset:18432
	ds_read_b128 v[174:177], v192 offset:19456
	ds_read_b128 v[178:181], v192 offset:20480
	ds_read_b128 v[182:185], v192 offset:21504
	ds_read_b128 v[196:199], v192 offset:22528
	ds_read_b128 v[200:203], v192 offset:23552
	global_load_lds_dwordx4 v[222:223], off
	v_lshl_add_u64 v[224:225], s[26:27], 0, v[158:159]
	s_mov_b32 m0, s34
	s_nop 0
	global_load_lds_dwordx4 v[224:225], off
	s_barrier
	s_waitcnt lgkmcnt(0)
	v_mfma_f32_16x16x32_bf16 v[60:63], v[128:131], v[144:147], v[60:63]
	v_mfma_f32_16x16x32_bf16 v[56:59], v[136:139], v[144:147], v[56:59]
	v_mfma_f32_16x16x32_bf16 v[44:47], v[128:131], v[170:173], v[44:47]
	v_mfma_f32_16x16x32_bf16 v[40:43], v[136:139], v[170:173], v[40:43]
	v_mfma_f32_16x16x32_bf16 v[28:31], v[128:131], v[178:181], v[28:31]
	v_mfma_f32_16x16x32_bf16 v[24:27], v[136:139], v[178:181], v[24:27]
	v_mfma_f32_16x16x32_bf16 v[12:15], v[128:131], v[196:199], v[12:15]
	v_mfma_f32_16x16x32_bf16 v[8:11], v[136:139], v[196:199], v[8:11]
	v_mfma_f32_16x16x32_bf16 v[60:63], v[132:135], v[148:151], v[60:63]
	v_mfma_f32_16x16x32_bf16 v[56:59], v[140:143], v[148:151], v[56:59]
	v_mfma_f32_16x16x32_bf16 v[44:47], v[132:135], v[174:177], v[44:47]
	v_mfma_f32_16x16x32_bf16 v[40:43], v[140:143], v[174:177], v[40:43]
	v_mfma_f32_16x16x32_bf16 v[28:31], v[132:135], v[182:185], v[28:31]
	v_mfma_f32_16x16x32_bf16 v[24:27], v[140:143], v[182:185], v[24:27]
	v_mfma_f32_16x16x32_bf16 v[12:15], v[132:135], v[200:203], v[12:15]
	v_mfma_f32_16x16x32_bf16 v[8:11], v[140:143], v[200:203], v[8:11]
	s_barrier
; #define PG8_STAGE(bufoff, gbase, voff) do { _Pragma("unroll") for (int _i = 0; _i < 2; ++_i) \
;         __builtin_amdgcn_global_load_lds((const unsigned*)((const char*)(gbase) + (voff)[_i]), (LAS unsigned*)(lds + (bufoff) + ldsw + _i * 8192), 16, 0, 0); } while (0)
; #define PG8_LDA(dst, b, h) do { _Pragma("unroll") for (int m = 0; m < 4; ++m) _Pragma("unroll") for (int k = 0; k < 2; ++k) dst[m][k] = *(const LAS bf16x8*)(lds + PG8_SA(b, h) + aoff + m * 2048 + k * 1024); } while (0)
; #define PG8_LDB(dst, b, h) do { _Pragma("unroll") for (int n = 0; n < 2; ++n) _Pragma("unroll") for (int k = 0; k < 2; ++k) dst[n][k] = *(const LAS bf16x8*)(lds + PG8_SB(b, h) + boff + n * 2048 + k * 1024); } while (0)
; #define PG8_MMA(ai, bj, At, Bt) do { __builtin_amdgcn_s_setprio(1); _Pragma("unroll") for (int m = 0; m < 4; ++m) _Pragma("unroll") for (int n = 0; n < 2; ++n) _Pragma("unroll") for (int k = 0; k < 2; ++k) \
;         acc[ai][bj][m][n] = __builtin_amdgcn_mfma_f32_16x16x32_bf16(Bt[n][k], At[m][k], acc[ai][bj][m][n], 0, 0, 0); __builtin_amdgcn_s_setprio(0); } while (0)
; #define PG8_WAIT_V(n) asm volatile("s_waitcnt vmcnt(" #n ")" ::: "memory")
; #define PG8_WAIT_L(n) asm volatile("s_waitcnt lgkmcnt(" #n ")" ::: "memory")
; #define PG8_BAR __builtin_amdgcn_s_barrier()
; #define PG8_SCHED __builtin_amdgcn_sched_barrier(0)
; template <class Epi>
; __device__ __forceinline__ void gemm_phase(LAS unsigned char* lds, const Gemm g, const StaticOrder& S, const Epi& E) {
;     ...
;             PG8_WAIT_V(6); PG8_BAR; PG8_MMA(1, 1, At, B1); PG8_BAR;
;             PG8_LDB(B0, 1, 0); PG8_SCHED; PG8_LDA(At, 1, 0); PG8_STAGE(PG8_SA(0, 1), a2 + hstepA, voffA);
;             PG8_WAIT_L(8); PG8_BAR; PG8_WAIT_L(0); PG8_MMA(0, 0, At, B0); PG8_BAR; PG8_SCHED;
;             PG8_LDB(B1, 1, 1); PG8_STAGE(PG8_SB(1, 0), b3, voffB);
;             PG8_BAR; PG8_WAIT_L(0); PG8_MMA(0, 1, At, B1); PG8_BAR;
;             PG8_LDA(At, 1, 1); PG8_STAGE(PG8_SA(1, 0), a3, voffA);
	s_add_u32 s50, s24, 0x100000
	s_addc_u32 s51, s25, 0
	s_add_i32 s49, s43, s31
	v_lshl_add_u64 v[128:129], s[50:51], 0, v[156:157]
	s_mov_b32 m0, s49
	s_nop 0
	global_load_lds_dwordx4 v[128:129], off
	v_lshl_add_u64 v[128:129], s[50:51], 0, v[160:161]
	s_add_i32 m0, s49, 0x2000
	s_nop 0
	global_load_lds_dwordx4 v[128:129], off
	s_waitcnt vmcnt(6)
	s_barrier
	v_mfma_f32_16x16x32_bf16 v[52:55], v[204:207], v[144:147], v[52:55]
	v_mfma_f32_16x16x32_bf16 v[48:51], v[212:215], v[144:147], v[48:51]
	v_mfma_f32_16x16x32_bf16 v[36:39], v[204:207], v[170:173], v[36:39]
	v_mfma_f32_16x16x32_bf16 v[32:35], v[212:215], v[170:173], v[32:35]
	v_mfma_f32_16x16x32_bf16 v[20:23], v[204:207], v[178:181], v[20:23]
	v_mfma_f32_16x16x32_bf16 v[16:19], v[212:215], v[178:181], v[16:19]
	v_mfma_f32_16x16x32_bf16 v[4:7], v[204:207], v[196:199], v[4:7]
	v_mfma_f32_16x16x32_bf16 v[0:3], v[212:215], v[196:199], v[0:3]
	v_mfma_f32_16x16x32_bf16 v[52:55], v[208:211], v[148:151], v[52:55]
	v_mfma_f32_16x16x32_bf16 v[48:51], v[216:219], v[148:151], v[48:51]
	v_mfma_f32_16x16x32_bf16 v[36:39], v[208:211], v[174:177], v[36:39]
	v_mfma_f32_16x16x32_bf16 v[32:35], v[216:219], v[174:177], v[32:35]
	v_mfma_f32_16x16x32_bf16 v[20:23], v[208:211], v[182:185], v[20:23]
	v_mfma_f32_16x16x32_bf16 v[16:19], v[216:219], v[182:185], v[16:19]
	v_mfma_f32_16x16x32_bf16 v[4:7], v[208:211], v[200:203], v[4:7]
	v_mfma_f32_16x16x32_bf16 v[0:3], v[216:219], v[200:203], v[0:3]
	s_add_i32 s49, 0, 0x18000
	v_add_u32_e32 v140, s49, v189
	s_barrier
	ds_read_b128 v[128:131], v140
	ds_read_b128 v[132:135], v140 offset:1024
	ds_read_b128 v[136:139], v140 offset:2048
	ds_read_b128 v[140:143], v140 offset:3072
	s_add_u32 s26, s26, 0x100000
	s_addc_u32 s27, s27, 0
	s_mov_b32 m0, s35
	v_lshl_add_u64 v[204:205], s[26:27], 0, v[154:155]
	ds_read_b128 v[144:147], v192 offset:32768
	ds_read_b128 v[148:151], v192 offset:33792
	ds_read_b128 v[170:173], v192 offset:34816
	ds_read_b128 v[174:177], v192 offset:35840
	ds_read_b128 v[178:181], v192 offset:36864
	ds_read_b128 v[182:185], v192 offset:37888
	ds_read_b128 v[196:199], v192 offset:38912
	ds_read_b128 v[200:203], v192 offset:39936
	global_load_lds_dwordx4 v[204:205], off
	v_lshl_add_u64 v[204:205], s[26:27], 0, v[158:159]
	s_mov_b32 m0, s36
	s_nop 0
	global_load_lds_dwordx4 v[204:205], off
	s_waitcnt lgkmcnt(8)
	s_barrier
	s_waitcnt lgkmcnt(0)
	v_mfma_f32_16x16x32_bf16 v[124:127], v[128:131], v[144:147], v[124:127]
	v_mfma_f32_16x16x32_bf16 v[120:123], v[136:139], v[144:147], v[120:123]
	v_mfma_f32_16x16x32_bf16 v[108:111], v[128:131], v[170:173], v[108:111]
	v_mfma_f32_16x16x32_bf16 v[104:107], v[136:139], v[170:173], v[104:107]
	v_mfma_f32_16x16x32_bf16 v[92:95], v[128:131], v[178:181], v[92:95]
	v_mfma_f32_16x16x32_bf16 v[88:91], v[136:139], v[178:181], v[88:91]
	v_mfma_f32_16x16x32_bf16 v[76:79], v[128:131], v[196:199], v[76:79]
	v_mfma_f32_16x16x32_bf16 v[72:75], v[136:139], v[196:199], v[72:75]
	v_mfma_f32_16x16x32_bf16 v[124:127], v[132:135], v[148:151], v[124:127]
	v_mfma_f32_16x16x32_bf16 v[120:123], v[140:143], v[148:151], v[120:123]
	v_mfma_f32_16x16x32_bf16 v[108:111], v[132:135], v[174:177], v[108:111]
	v_mfma_f32_16x16x32_bf16 v[104:107], v[140:143], v[174:177], v[104:107]
	v_mfma_f32_16x16x32_bf16 v[92:95], v[132:135], v[182:185], v[92:95]
	v_mfma_f32_16x16x32_bf16 v[88:91], v[140:143], v[182:185], v[88:91]
	v_mfma_f32_16x16x32_bf16 v[76:79], v[132:135], v[200:203], v[76:79]
	v_mfma_f32_16x16x32_bf16 v[72:75], v[140:143], v[200:203], v[72:75]
	s_barrier
	s_add_i32 s26, 0, 0x1c000
	s_add_i32 s27, s49, s31
	v_add_u32_e32 v195, s26, v189
	v_lshl_add_u64 v[186:187], v[186:187], 0, s[12:13]
	s_mov_b32 m0, s27
	ds_read_b128 v[204:207], v195
	ds_read_b128 v[208:211], v195 offset:1024
	ds_read_b128 v[212:215], v195 offset:2048
	ds_read_b128 v[216:219], v195 offset:3072
	global_load_lds_dwordx4 v[186:187], off
	v_lshl_add_u64 v[186:187], v[220:221], 0, s[12:13]
	s_add_i32 m0, s27, 0x2000
	s_nop 0
	global_load_lds_dwordx4 v[186:187], off
	s_barrier
	s_waitcnt lgkmcnt(0)
	v_mfma_f32_16x16x32_bf16 v[116:119], v[204:207], v[144:147], v[116:119]
	v_mfma_f32_16x16x32_bf16 v[112:115], v[212:215], v[144:147], v[112:115]
	v_mfma_f32_16x16x32_bf16 v[100:103], v[204:207], v[170:173], v[100:103]
	v_mfma_f32_16x16x32_bf16 v[96:99], v[212:215], v[170:173], v[96:99]
	v_mfma_f32_16x16x32_bf16 v[84:87], v[204:207], v[178:181], v[84:87]
	v_mfma_f32_16x16x32_bf16 v[80:83], v[212:215], v[178:181], v[80:83]
	v_mfma_f32_16x16x32_bf16 v[68:71], v[204:207], v[196:199], v[68:71]
	v_mfma_f32_16x16x32_bf16 v[64:67], v[212:215], v[196:199], v[64:67]
	v_mfma_f32_16x16x32_bf16 v[116:119], v[208:211], v[148:151], v[116:119]
	v_mfma_f32_16x16x32_bf16 v[112:115], v[216:219], v[148:151], v[112:115]
	v_mfma_f32_16x16x32_bf16 v[100:103], v[208:211], v[174:177], v[100:103]
	v_mfma_f32_16x16x32_bf16 v[96:99], v[216:219], v[174:177], v[96:99]
	v_mfma_f32_16x16x32_bf16 v[84:87], v[208:211], v[182:185], v[84:87]
	v_mfma_f32_16x16x32_bf16 v[80:83], v[216:219], v[182:185], v[80:83]
	v_mfma_f32_16x16x32_bf16 v[68:71], v[208:211], v[200:203], v[68:71]
	v_mfma_f32_16x16x32_bf16 v[64:67], v[216:219], v[200:203], v[64:67]
	s_mov_b32 m0, s38
	v_lshl_add_u64 v[186:187], v[222:223], 0, s[12:13]
	s_barrier
	ds_read_b128 v[144:147], v192 offset:49152
	ds_read_b128 v[148:151], v192 offset:50176
	ds_read_b128 v[170:173], v192 offset:51200
	ds_read_b128 v[174:177], v192 offset:52224
	ds_read_b128 v[178:181], v192 offset:53248
	ds_read_b128 v[182:185], v192 offset:54272
	ds_read_b128 v[196:199], v192 offset:55296
	ds_read_b128 v[200:203], v192 offset:56320
	global_load_lds_dwordx4 v[186:187], off
	v_lshl_add_u64 v[186:187], v[224:225], 0, s[12:13]
	s_mov_b32 m0, s39
	s_nop 0
	global_load_lds_dwordx4 v[186:187], off
	s_barrier
; #define PG8_STAGE(bufoff, gbase, voff) do { _Pragma("unroll") for (int _i = 0; _i < 2; ++_i) \
;         __builtin_amdgcn_global_load_lds((const unsigned*)((const char*)(gbase) + (voff)[_i]), (LAS unsigned*)(lds + (bufoff) + ldsw + _i * 8192), 16, 0, 0); } while (0)
; #define PG8_MMA(ai, bj, At, Bt) do { __builtin_amdgcn_s_setprio(1); _Pragma("unroll") for (int m = 0; m < 4; ++m) _Pragma("unroll") for (int n = 0; n < 2; ++n) _Pragma("unroll") for (int k = 0; k < 2; ++k) \
;         acc[ai][bj][m][n] = __builtin_amdgcn_mfma_f32_16x16x32_bf16(Bt[n][k], At[m][k], acc[ai][bj][m][n], 0, 0, 0); __builtin_amdgcn_s_setprio(0); } while (0)
; #define PG8_WAIT_V(n) asm volatile("s_waitcnt vmcnt(" #n ")" ::: "memory")
; #define PG8_WAIT_L(n) asm volatile("s_waitcnt lgkmcnt(" #n ")" ::: "memory")
; #define PG8_BAR __builtin_amdgcn_s_barrier()
; #define PG8_SCHED __builtin_amdgcn_sched_barrier(0)
; template <class Epi>
; __device__ __forceinline__ void gemm_phase(LAS unsigned char* lds, const Gemm g, const StaticOrder& S, const Epi& E) {
;     ...
;             PG8_BAR; PG8_WAIT_L(0); PG8_MMA(1, 0, At, B0); PG8_BAR; PG8_SCHED;
;             PG8_STAGE(PG8_SB(1, 1), b3 + hstepB, voffB);
;             PG8_WAIT_V(6); PG8_BAR; PG8_MMA(1, 1, At, B1); PG8_BAR;
	s_waitcnt lgkmcnt(0)
	v_mfma_f32_16x16x32_bf16 v[60:63], v[128:131], v[144:147], v[60:63]
	v_mfma_f32_16x16x32_bf16 v[56:59], v[136:139], v[144:147], v[56:59]
	v_mfma_f32_16x16x32_bf16 v[44:47], v[128:131], v[170:173], v[44:47]
	v_mfma_f32_16x16x32_bf16 v[40:43], v[136:139], v[170:173], v[40:43]
	v_mfma_f32_16x16x32_bf16 v[28:31], v[128:131], v[178:181], v[28:31]
	v_mfma_f32_16x16x32_bf16 v[24:27], v[136:139], v[178:181], v[24:27]
	v_mfma_f32_16x16x32_bf16 v[12:15], v[128:131], v[196:199], v[12:15]
	v_mfma_f32_16x16x32_bf16 v[8:11], v[136:139], v[196:199], v[8:11]
	v_mfma_f32_16x16x32_bf16 v[60:63], v[132:135], v[148:151], v[60:63]
	v_mfma_f32_16x16x32_bf16 v[56:59], v[140:143], v[148:151], v[56:59]
	v_mfma_f32_16x16x32_bf16 v[44:47], v[132:135], v[174:177], v[44:47]
	v_mfma_f32_16x16x32_bf16 v[40:43], v[140:143], v[174:177], v[40:43]
	v_mfma_f32_16x16x32_bf16 v[28:31], v[132:135], v[182:185], v[28:31]
	v_mfma_f32_16x16x32_bf16 v[24:27], v[140:143], v[182:185], v[24:27]
	v_mfma_f32_16x16x32_bf16 v[12:15], v[132:135], v[200:203], v[12:15]
	v_mfma_f32_16x16x32_bf16 v[8:11], v[140:143], v[200:203], v[8:11]
	s_barrier
	s_add_u32 s24, s24, 0x100080
	s_addc_u32 s25, s25, 0
	s_add_i32 s26, s26, s31
	v_lshl_add_u64 v[128:129], s[24:25], 0, v[156:157]
	s_mov_b32 m0, s26
	s_nop 0
	global_load_lds_dwordx4 v[128:129], off
	v_lshl_add_u64 v[128:129], s[24:25], 0, v[160:161]
	s_add_i32 m0, s26, 0x2000
	s_nop 0
	global_load_lds_dwordx4 v[128:129], off
	s_waitcnt vmcnt(6)
	s_barrier
	v_mfma_f32_16x16x32_bf16 v[52:55], v[204:207], v[144:147], v[52:55]
	v_mfma_f32_16x16x32_bf16 v[48:51], v[212:215], v[144:147], v[48:51]
	v_mfma_f32_16x16x32_bf16 v[36:39], v[204:207], v[170:173], v[36:39]
	v_mfma_f32_16x16x32_bf16 v[32:35], v[212:215], v[170:173], v[32:35]
	v_mfma_f32_16x16x32_bf16 v[20:23], v[204:207], v[178:181], v[20:23]
	v_mfma_f32_16x16x32_bf16 v[16:19], v[212:215], v[178:181], v[16:19]
	v_mfma_f32_16x16x32_bf16 v[4:7], v[204:207], v[196:199], v[4:7]
	v_mfma_f32_16x16x32_bf16 v[0:3], v[212:215], v[196:199], v[0:3]
	v_mfma_f32_16x16x32_bf16 v[52:55], v[208:211], v[148:151], v[52:55]
	v_mfma_f32_16x16x32_bf16 v[48:51], v[216:219], v[148:151], v[48:51]
	v_mfma_f32_16x16x32_bf16 v[36:39], v[208:211], v[174:177], v[36:39]
	v_mfma_f32_16x16x32_bf16 v[32:35], v[216:219], v[174:177], v[32:35]
	v_mfma_f32_16x16x32_bf16 v[20:23], v[208:211], v[182:185], v[20:23]
	v_mfma_f32_16x16x32_bf16 v[16:19], v[216:219], v[182:185], v[16:19]
	v_mfma_f32_16x16x32_bf16 v[4:7], v[208:211], v[200:203], v[4:7]
	v_mfma_f32_16x16x32_bf16 v[0:3], v[216:219], v[200:203], v[0:3]
	s_add_i32 s48, s48, 2
	s_add_u32 s22, s22, 0x100
	s_addc_u32 s23, s23, 0
	s_add_u32 s46, s46, 0x100
	s_addc_u32 s47, s47, 0
	s_cmp_gt_u32 s48, 61
	s_barrier
	s_cbranch_scc0 .LBB0_844
	s_setprio 0
	s_cmp_ge_u32 s98, 0x100
	s_cbranch_scc0 .Lep3_skip
	s_setprio 1
; __device__ __forceinline__ unsigned pk2(float lo, float hi) { const f32x2 v = (f32x2){lo, hi}; const bf16x2_t b = __builtin_convertvector(v, bf16x2_t); return __builtin_bit_cast(unsigned, b); }
; __device__ __forceinline__ void unpack8(const u32x4 v, float* f) { f[0] = bf_lo(v.x); f[1] = bf_hi(v.x); f[2] = bf_lo(v.y); f[3] = bf_hi(v.y); f[4] = bf_lo(v.z); f[5] = bf_hi(v.z); f[6] = bf_lo(v.w); f[7] = bf_hi(v.w); }
;     __device__ __forceinline__ void operator()(const f32x4 (&acc)[2][2][4][2], const Unit& u, int wr, int wc, int fr, int fq, const float (&)[8]) const {
;         const int row0 = u.pm * BM + wr * 64 + fr, col0 = u.pn * BM + wc * 32 + 8 * fq;
; #pragma unroll
;         for (int ai = 0; ai < 2; ++ai) {
;             u32x4 bv[4][2];
; #pragma unroll
;             for (int m = 0; m < 4; ++m)
; #pragma unroll
;                 for (int bj = 0; bj < 2; ++bj) bv[m][bj] = *(const u32x4*)(xb + (size_t)(row0 + ai * HALF + m * 16) * DM + col0 + bj * HALF);
; #pragma unroll
;             for (int m = 0; m < 4; ++m) { const int row = row0 + ai * HALF + m * 16; const size_t ro = (size_t)row * DM + col0; float s = 0.f;
; #pragma unroll
;                 for (int bj = 0; bj < 2; ++bj) { float b8[8]; unpack8(bv[m][bj], b8);
;                     const f32x4 v0 = (f32x4){b8[0], b8[1], b8[2], b8[3]} + acc[ai][bj][m][0], v1 = (f32x4){b8[4], b8[5], b8[6], b8[7]} + acc[ai][bj][m][1];
;                     s += v0[0] * v0[0] + v0[1] * v0[1] + v0[2] * v0[2] + v0[3] * v0[3] + v1[0] * v1[0] + v1[1] * v1[1] + v1[2] * v1[2] + v1[3] * v1[3];
;                     if (LAST) { *(f32x4*)(out + ro + bj * HALF) = v0; *(f32x4*)(out + ro + bj * HALF + 4) = v1; }
;                     else { u32x4 w; w.x = pk2(v0[0], v0[1]); w.y = pk2(v0[2], v0[3]); w.z = pk2(v1[0], v1[1]); w.w = pk2(v1[2], v1[3]); *(u32x4*)(xb + ro + bj * HALF) = w; } }
;                 s += __shfl_xor(s, 16); s += __shfl_xor(s, 32);
;                 if (fq == 0) ss[(size_t)row * 16 + u.pn * 4 + wc] = s; }
.Lep3_skip:
	v_lshl_or_b32 v170, s6, 8, v190
	v_lshl_add_u32 v172, s8, 8, v188
	v_ashrrev_i32_e32 v171, 31, v170
	v_lshlrev_b64 v[206:207], 1, v[170:171]
	v_ashrrev_i32_e32 v173, 31, v172
	v_lshl_add_u64 v[174:175], s[76:77], 0, v[206:207]
	v_lshlrev_b64 v[208:209], 11, v[172:173]
	v_lshl_add_u64 v[128:129], v[174:175], 0, v[208:209]
	global_load_dwordx4 v[198:201], v[128:129], off
	global_load_dwordx4 v[202:205], v[128:129], off offset:256
	v_or_b32_e32 v184, 16, v172
	v_or_b32_e32 v180, 32, v172
	v_or_b32_e32 v176, 48, v172
	v_ashrrev_i32_e32 v185, 31, v184
	v_ashrrev_i32_e32 v181, 31, v180
	v_ashrrev_i32_e32 v177, 31, v176
	v_lshlrev_b64 v[186:187], 11, v[184:185]
	v_lshlrev_b64 v[182:183], 11, v[180:181]
	v_lshlrev_b64 v[178:179], 11, v[176:177]
	v_lshl_add_u64 v[128:129], v[174:175], 0, v[186:187]
	v_lshl_add_u64 v[130:131], v[174:175], 0, v[182:183]
	v_lshl_add_u64 v[196:197], v[174:175], 0, v[178:179]
	global_load_dwordx4 v[148:151], v[128:129], off
	global_load_dwordx4 v[144:147], v[128:129], off offset:256
	global_load_dwordx4 v[140:143], v[130:131], off
	global_load_dwordx4 v[136:139], v[130:131], off offset:256
	global_load_dwordx4 v[132:135], v[196:197], off
	s_nop 0
	global_load_dwordx4 v[128:131], v[196:197], off offset:256
	v_add_u32_e32 v218, 0x80, v172
	v_ashrrev_i32_e32 v219, 31, v218
	v_lshlrev_b64 v[218:219], 11, v[218:219]
	v_lshl_add_u64 v[218:219], v[174:175], 0, v[218:219]
	global_load_dwordx4 v[220:223], v[218:219], off
	global_load_dwordx4 v[224:227], v[218:219], off offset:256
	v_add_u32_e32 v218, 0x90, v172
	v_ashrrev_i32_e32 v219, 31, v218
	v_lshlrev_b64 v[218:219], 11, v[218:219]
	v_lshl_add_u64 v[218:219], v[174:175], 0, v[218:219]
	global_load_dwordx4 v[228:231], v[218:219], off
	global_load_dwordx4 v[232:235], v[218:219], off offset:256
	v_add_u32_e32 v218, 0xa0, v172
	v_ashrrev_i32_e32 v219, 31, v218
	v_lshlrev_b64 v[218:219], 11, v[218:219]
	v_lshl_add_u64 v[218:219], v[174:175], 0, v[218:219]
	global_load_dwordx4 v[236:239], v[218:219], off
	global_load_dwordx4 v[240:243], v[218:219], off offset:256
	v_add_u32_e32 v218, 0xb0, v172
	v_ashrrev_i32_e32 v219, 31, v218
	v_lshlrev_b64 v[218:219], 11, v[218:219]
	v_lshl_add_u64 v[218:219], v[174:175], 0, v[218:219]
	global_load_dwordx4 v[244:247], v[218:219], off
	global_load_dwordx4 v[252:255], v[218:219], off offset:256
	v_and_b32_e32 v196, 64, v194
	v_xor_b32_e32 v195, 16, v194
	v_add_u32_e32 v196, 64, v196
	v_xor_b32_e32 v197, 32, v194
	v_cmp_lt_i32_e32 vcc, v195, v196
	s_waitcnt vmcnt(15)
	v_lshlrev_b32_e32 v210, 16, v198
	v_cndmask_b32_e32 v195, v194, v195, vcc
	v_cmp_lt_i32_e32 vcc, v197, v196
	v_and_b32_e32 v211, 0xffff0000, v198
	s_waitcnt vmcnt(14)
	v_lshlrev_b32_e32 v214, 16, v202
	v_and_b32_e32 v215, 0xffff0000, v202
	v_cndmask_b32_e32 v197, v194, v197, vcc
	v_lshlrev_b32_e32 v212, 16, v200
	v_and_b32_e32 v213, 0xffff0000, v200
	v_lshlrev_b32_e32 v200, 16, v201
	v_and_b32_e32 v201, 0xffff0000, v201
	v_lshlrev_b32_e32 v216, 16, v204
	v_and_b32_e32 v217, 0xffff0000, v204
	v_pk_add_f32 v[124:125], v[124:125], v[210:211]
	v_pk_add_f32 v[116:117], v[116:117], v[214:215]
	v_lshlrev_b32_e32 v196, 2, v195
	v_lshlrev_b32_e32 v195, 2, v197
	v_lshlrev_b32_e32 v198, 16, v199
	v_and_b32_e32 v199, 0xffff0000, v199
	v_lshlrev_b32_e32 v202, 16, v203
	v_and_b32_e32 v203, 0xffff0000, v203
	v_pk_add_f32 v[122:123], v[122:123], v[200:201]
	v_pk_add_f32 v[200:201], v[112:113], v[216:217]
	v_mul_f32_e32 v197, v125, v125
	v_cvt_pk_bf16_f32 v112, v124, v125
	v_mul_f32_e32 v125, v117, v117
	v_pk_add_f32 v[126:127], v[126:127], v[198:199]
	v_pk_add_f32 v[118:119], v[118:119], v[202:203]
	v_fmac_f32_e32 v197, v124, v124
	v_fmac_f32_e32 v125, v116, v116
	v_fmac_f32_e32 v197, v126, v126
	v_fmac_f32_e32 v125, v118, v118
	v_pk_add_f32 v[120:121], v[120:121], v[212:213]
	v_fmac_f32_e32 v197, v127, v127
	v_fmac_f32_e32 v125, v119, v119
	v_lshlrev_b32_e32 v204, 16, v205
	v_and_b32_e32 v205, 0xffff0000, v205
	v_fmac_f32_e32 v197, v120, v120
	v_fmac_f32_e32 v125, v200, v200
	v_pk_add_f32 v[198:199], v[114:115], v[204:205]
	v_fmac_f32_e32 v197, v121, v121
	v_fmac_f32_e32 v125, v201, v201
	v_fmac_f32_e32 v197, v122, v122
	v_fmac_f32_e32 v125, v198, v198
	v_fmac_f32_e32 v197, v123, v123
	v_fmac_f32_e32 v125, v199, v199
	v_cvt_pk_bf16_f32 v115, v122, v123
	v_add_f32_e32 v122, v197, v125
	ds_bpermute_b32 v123, v196, v122
	v_cvt_pk_bf16_f32 v114, v120, v121
	v_lshl_add_u64 v[120:121], s[76:77], 0, v[208:209]
	v_cvt_pk_bf16_f32 v113, v126, v127
	v_lshl_add_u64 v[120:121], v[120:121], 0, v[206:207]
	global_store_dwordx4 v[120:121], v[112:115], off
	s_waitcnt lgkmcnt(0)
	s_nop 0
	v_add_f32_e32 v112, v122, v123
	ds_bpermute_b32 v113, v195, v112
	v_cvt_pk_bf16_f32 v114, v116, v117
	v_cvt_pk_bf16_f32 v115, v118, v119
	v_cvt_pk_bf16_f32 v116, v200, v201
	v_cvt_pk_bf16_f32 v117, v198, v199
	global_store_dwordx4 v[120:121], v[114:117], off offset:256
	s_and_saveexec_b64 s[22:23], s[0:1]
	s_cbranch_execz .LBB0_847
	s_waitcnt lgkmcnt(0)
	v_add_f32_e32 v114, v112, v113
	s_lshl_b32 s24, s6, 2
	v_lshlrev_b64 v[112:113], 6, v[172:173]
	s_ashr_i32 s25, s24, 31
	v_lshl_add_u64 v[112:113], s[10:11], 0, v[112:113]
	v_lshl_add_u64 v[112:113], s[24:25], 2, v[112:113]
	s_lshl_b32 s8, s37, 2
	v_lshl_add_u64 v[112:113], v[112:113], 0, s[8:9]
	global_store_dword v[112:113], v114, off

; #define PG8_STAGE(bufoff, gbase, voff) do { _Pragma("unroll") for (int _i = 0; _i < 2; ++_i) \
;         __builtin_amdgcn_global_load_lds((const unsigned*)((const char*)(gbase) + (voff)[_i]), (LAS unsigned*)(lds + (bufoff) + ldsw + _i * 8192), 16, 0, 0); } while (0)
; #define PG8_LDA(dst, b, h) do { _Pragma("unroll") for (int m = 0; m < 4; ++m) _Pragma("unroll") for (int k = 0; k < 2; ++k) dst[m][k] = *(const LAS bf16x8*)(lds + PG8_SA(b, h) + aoff + m * 2048 + k * 1024); } while (0)
; #define PG8_LDB(dst, b, h) do { _Pragma("unroll") for (int n = 0; n < 2; ++n) _Pragma("unroll") for (int k = 0; k < 2; ++k) dst[n][k] = *(const LAS bf16x8*)(lds + PG8_SB(b, h) + boff + n * 2048 + k * 1024); } while (0)
; #define PG8_MMA(ai, bj, At, Bt) do { __builtin_amdgcn_s_setprio(1); _Pragma("unroll") for (int m = 0; m < 4; ++m) _Pragma("unroll") for (int n = 0; n < 2; ++n) _Pragma("unroll") for (int k = 0; k < 2; ++k) \
;         acc[ai][bj][m][n] = __builtin_amdgcn_mfma_f32_16x16x32_bf16(Bt[n][k], At[m][k], acc[ai][bj][m][n], 0, 0, 0); __builtin_amdgcn_s_setprio(0); } while (0)
; #define PG8_WAIT_V(n) asm volatile("s_waitcnt vmcnt(" #n ")" ::: "memory")
; #define PG8_WAIT_L(n) asm volatile("s_waitcnt lgkmcnt(" #n ")" ::: "memory")
; #define PG8_BAR __builtin_amdgcn_s_barrier()
; #define PG8_SCHED __builtin_amdgcn_sched_barrier(0)
; template <class Epi>
; __device__ __forceinline__ void gemm_phase(LAS unsigned char* lds, const Gemm g, const StaticOrder& S, const Epi& E) {
;     ...
;             PG8_LDB(B0, 0, 0); PG8_SCHED; PG8_LDA(At, 0, 0); PG8_STAGE(PG8_SA(1, 1), a1 + hstepA, voffA);
;             PG8_WAIT_L(8); PG8_BAR; PG8_WAIT_L(0); PG8_MMA(0, 0, At, B0); PG8_BAR; PG8_SCHED;
;             PG8_LDB(B1, 0, 1); PG8_STAGE(PG8_SB(0, 0), b2, voffB);
;             PG8_BAR; PG8_WAIT_L(0); PG8_MMA(0, 1, At, B1); PG8_BAR;
;             PG8_LDA(At, 0, 1); PG8_STAGE(PG8_SA(0, 0), a2, voffA);
;             PG8_BAR; PG8_WAIT_L(0); PG8_MMA(1, 0, At, B0); PG8_BAR; PG8_SCHED;
;             PG8_STAGE(PG8_SB(0, 1), b2 + hstepB, voffB);
;             PG8_WAIT_V(6); PG8_BAR; PG8_MMA(1, 1, At, B1); PG8_BAR;
.LBB0_922:
	ds_read_b128 v[146:149], v173
	ds_read_b128 v[154:157], v173 offset:1024
	ds_read_b128 v[158:161], v173 offset:2048
	ds_read_b128 v[162:165], v173 offset:3072
	s_add_u32 s22, s20, 0xfffc0080
	s_addc_u32 s23, s21, -1
	s_cmp_eq_u32 s47, 12
	s_cselect_b32 s25, s13, s23
	s_cselect_b32 s24, s43, s22
	s_cselect_b32 s23, s11, s46
	s_cselect_b32 s22, s44, s45
	v_lshl_add_u64 v[150:151], s[20:21], 0, v[138:139]
	s_add_i32 m0, s19, 0xc000
	ds_read_b128 v[166:169], v174
	ds_read_b128 v[178:181], v174 offset:1024
	ds_read_b128 v[182:185], v174 offset:2048
	ds_read_b128 v[186:189], v174 offset:3072
	ds_read_b128 v[190:193], v174 offset:4096
	ds_read_b128 v[194:197], v174 offset:5120
	ds_read_b128 v[198:201], v174 offset:6144
	ds_read_b128 v[202:205], v174 offset:7168
	global_load_lds_dwordx4 v[150:151], off
	v_lshl_add_u64 v[150:151], s[20:21], 0, v[140:141]
	s_add_i32 m0, s19, 0xe000
	s_nop 0
	global_load_lds_dwordx4 v[150:151], off
	s_waitcnt lgkmcnt(8)
	s_barrier
	s_waitcnt lgkmcnt(0)
	v_mfma_f32_16x16x32_bf16 v[124:127], v[146:149], v[166:169], v[124:127]
	v_mfma_f32_16x16x32_bf16 v[120:123], v[158:161], v[166:169], v[120:123]
	v_mfma_f32_16x16x32_bf16 v[112:115], v[146:149], v[182:185], v[112:115]
	v_mfma_f32_16x16x32_bf16 v[104:107], v[158:161], v[182:185], v[104:107]
	v_mfma_f32_16x16x32_bf16 v[92:95], v[146:149], v[190:193], v[92:95]
	v_mfma_f32_16x16x32_bf16 v[88:91], v[158:161], v[190:193], v[88:91]
	v_mfma_f32_16x16x32_bf16 v[80:83], v[146:149], v[198:201], v[80:83]
	v_mfma_f32_16x16x32_bf16 v[72:75], v[158:161], v[198:201], v[72:75]
	v_mfma_f32_16x16x32_bf16 v[124:127], v[154:157], v[178:181], v[124:127]
	v_mfma_f32_16x16x32_bf16 v[120:123], v[162:165], v[178:181], v[120:123]
	v_mfma_f32_16x16x32_bf16 v[112:115], v[154:157], v[186:189], v[112:115]
	v_mfma_f32_16x16x32_bf16 v[104:107], v[162:165], v[186:189], v[104:107]
	v_mfma_f32_16x16x32_bf16 v[92:95], v[154:157], v[194:197], v[92:95]
	v_mfma_f32_16x16x32_bf16 v[88:91], v[162:165], v[194:197], v[88:91]
	v_mfma_f32_16x16x32_bf16 v[80:83], v[154:157], v[202:205], v[80:83]
	v_mfma_f32_16x16x32_bf16 v[72:75], v[162:165], v[202:205], v[72:75]
	s_barrier
	s_add_i32 s48, s38, s27
	v_lshl_add_u64 v[150:151], s[22:23], 0, v[132:133]
	s_mov_b32 m0, s48
	ds_read_b128 v[206:209], v175
	ds_read_b128 v[210:213], v175 offset:1024
	ds_read_b128 v[214:217], v175 offset:2048
	ds_read_b128 v[218:221], v175 offset:3072
	global_load_lds_dwordx4 v[150:151], off
	v_lshl_add_u64 v[222:223], s[22:23], 0, v[128:129]
	s_add_i32 m0, s48, 0x2000
	s_nop 0
	global_load_lds_dwordx4 v[222:223], off
	s_barrier
	s_waitcnt lgkmcnt(0)
	v_mfma_f32_16x16x32_bf16 v[116:119], v[206:209], v[166:169], v[116:119]
	v_mfma_f32_16x16x32_bf16 v[108:111], v[214:217], v[166:169], v[108:111]
	v_mfma_f32_16x16x32_bf16 v[100:103], v[206:209], v[182:185], v[100:103]
	v_mfma_f32_16x16x32_bf16 v[96:99], v[214:217], v[182:185], v[96:99]
	v_mfma_f32_16x16x32_bf16 v[84:87], v[206:209], v[190:193], v[84:87]
	v_mfma_f32_16x16x32_bf16 v[76:79], v[214:217], v[190:193], v[76:79]
	v_mfma_f32_16x16x32_bf16 v[68:71], v[206:209], v[198:201], v[68:71]
	v_mfma_f32_16x16x32_bf16 v[64:67], v[214:217], v[198:201], v[64:67]
	v_mfma_f32_16x16x32_bf16 v[116:119], v[210:213], v[178:181], v[116:119]
	v_mfma_f32_16x16x32_bf16 v[108:111], v[218:221], v[178:181], v[108:111]
	v_mfma_f32_16x16x32_bf16 v[100:103], v[210:213], v[186:189], v[100:103]
	v_mfma_f32_16x16x32_bf16 v[96:99], v[218:221], v[186:189], v[96:99]
	v_mfma_f32_16x16x32_bf16 v[84:87], v[210:213], v[194:197], v[84:87]
	v_mfma_f32_16x16x32_bf16 v[76:79], v[218:221], v[194:197], v[76:79]
	v_mfma_f32_16x16x32_bf16 v[68:71], v[210:213], v[202:205], v[68:71]
	v_mfma_f32_16x16x32_bf16 v[64:67], v[218:221], v[202:205], v[64:67]
	s_mov_b32 m0, s19
	v_lshl_add_u64 v[224:225], s[24:25], 0, v[134:135]
	s_barrier
	ds_read_b128 v[166:169], v174 offset:16384
	ds_read_b128 v[178:181], v174 offset:17408
	ds_read_b128 v[182:185], v174 offset:18432
	ds_read_b128 v[186:189], v174 offset:19456
	ds_read_b128 v[190:193], v174 offset:20480
	ds_read_b128 v[194:197], v174 offset:21504
	ds_read_b128 v[198:201], v174 offset:22528
	ds_read_b128 v[202:205], v174 offset:23552
	global_load_lds_dwordx4 v[224:225], off
	v_lshl_add_u64 v[226:227], s[24:25], 0, v[130:131]
	s_mov_b32 m0, s30
	s_nop 0
	global_load_lds_dwordx4 v[226:227], off
	s_barrier
	s_waitcnt lgkmcnt(0)
	v_mfma_f32_16x16x32_bf16 v[60:63], v[146:149], v[166:169], v[60:63]
	v_mfma_f32_16x16x32_bf16 v[56:59], v[158:161], v[166:169], v[56:59]
	v_mfma_f32_16x16x32_bf16 v[48:51], v[146:149], v[182:185], v[48:51]
	v_mfma_f32_16x16x32_bf16 v[40:43], v[158:161], v[182:185], v[40:43]
	v_mfma_f32_16x16x32_bf16 v[32:35], v[146:149], v[190:193], v[32:35]
	v_mfma_f32_16x16x32_bf16 v[24:27], v[158:161], v[190:193], v[24:27]
	v_mfma_f32_16x16x32_bf16 v[16:19], v[146:149], v[198:201], v[16:19]
	v_mfma_f32_16x16x32_bf16 v[8:11], v[158:161], v[198:201], v[8:11]
	v_mfma_f32_16x16x32_bf16 v[60:63], v[154:157], v[178:181], v[60:63]
	v_mfma_f32_16x16x32_bf16 v[56:59], v[162:165], v[178:181], v[56:59]
	v_mfma_f32_16x16x32_bf16 v[48:51], v[154:157], v[186:189], v[48:51]
	v_mfma_f32_16x16x32_bf16 v[40:43], v[162:165], v[186:189], v[40:43]
	v_mfma_f32_16x16x32_bf16 v[32:35], v[154:157], v[194:197], v[32:35]
	v_mfma_f32_16x16x32_bf16 v[24:27], v[162:165], v[194:197], v[24:27]
	v_mfma_f32_16x16x32_bf16 v[16:19], v[154:157], v[202:205], v[16:19]
	v_mfma_f32_16x16x32_bf16 v[8:11], v[162:165], v[202:205], v[8:11]
	s_barrier
; #define PG8_STAGE(bufoff, gbase, voff) do { _Pragma("unroll") for (int _i = 0; _i < 2; ++_i) \
;         __builtin_amdgcn_global_load_lds((const unsigned*)((const char*)(gbase) + (voff)[_i]), (LAS unsigned*)(lds + (bufoff) + ldsw + _i * 8192), 16, 0, 0); } while (0)
; #define PG8_LDA(dst, b, h) do { _Pragma("unroll") for (int m = 0; m < 4; ++m) _Pragma("unroll") for (int k = 0; k < 2; ++k) dst[m][k] = *(const LAS bf16x8*)(lds + PG8_SA(b, h) + aoff + m * 2048 + k * 1024); } while (0)
; #define PG8_LDB(dst, b, h) do { _Pragma("unroll") for (int n = 0; n < 2; ++n) _Pragma("unroll") for (int k = 0; k < 2; ++k) dst[n][k] = *(const LAS bf16x8*)(lds + PG8_SB(b, h) + boff + n * 2048 + k * 1024); } while (0)
; #define PG8_MMA(ai, bj, At, Bt) do { __builtin_amdgcn_s_setprio(1); _Pragma("unroll") for (int m = 0; m < 4; ++m) _Pragma("unroll") for (int n = 0; n < 2; ++n) _Pragma("unroll") for (int k = 0; k < 2; ++k) \
;         acc[ai][bj][m][n] = __builtin_amdgcn_mfma_f32_16x16x32_bf16(Bt[n][k], At[m][k], acc[ai][bj][m][n], 0, 0, 0); __builtin_amdgcn_s_setprio(0); } while (0)
; #define PG8_WAIT_V(n) asm volatile("s_waitcnt vmcnt(" #n ")" ::: "memory")
; #define PG8_WAIT_L(n) asm volatile("s_waitcnt lgkmcnt(" #n ")" ::: "memory")
; #define PG8_BAR __builtin_amdgcn_s_barrier()
; #define PG8_SCHED __builtin_amdgcn_sched_barrier(0)
; template <class Epi>
; __device__ __forceinline__ void gemm_phase(LAS unsigned char* lds, const Gemm g, const StaticOrder& S, const Epi& E) {
;     ...
;             PG8_WAIT_V(6); PG8_BAR; PG8_MMA(1, 1, At, B1); PG8_BAR;
;             PG8_LDB(B0, 1, 0); PG8_SCHED; PG8_LDA(At, 1, 0); PG8_STAGE(PG8_SA(0, 1), a2 + hstepA, voffA);
;             PG8_WAIT_L(8); PG8_BAR; PG8_WAIT_L(0); PG8_MMA(0, 0, At, B0); PG8_BAR; PG8_SCHED;
;             PG8_LDB(B1, 1, 1); PG8_STAGE(PG8_SB(1, 0), b3, voffB);
;             PG8_BAR; PG8_WAIT_L(0); PG8_MMA(0, 1, At, B1); PG8_BAR;
;             PG8_LDA(At, 1, 1); PG8_STAGE(PG8_SA(1, 0), a3, voffA);
	s_add_u32 s48, s22, 0x40000
	s_addc_u32 s49, s23, 0
	s_add_i32 s50, s39, s27
	v_lshl_add_u64 v[146:147], s[48:49], 0, v[132:133]
	s_mov_b32 m0, s50
	s_nop 0
	global_load_lds_dwordx4 v[146:147], off
	v_lshl_add_u64 v[146:147], s[48:49], 0, v[128:129]
	s_add_i32 m0, s50, 0x2000
	s_nop 0
	global_load_lds_dwordx4 v[146:147], off
	s_waitcnt vmcnt(6)
	s_barrier
	v_mfma_f32_16x16x32_bf16 v[52:55], v[206:209], v[166:169], v[52:55]
	v_mfma_f32_16x16x32_bf16 v[44:47], v[214:217], v[166:169], v[44:47]
	v_mfma_f32_16x16x32_bf16 v[36:39], v[206:209], v[182:185], v[36:39]
	v_mfma_f32_16x16x32_bf16 v[28:31], v[214:217], v[182:185], v[28:31]
	v_mfma_f32_16x16x32_bf16 v[20:23], v[206:209], v[190:193], v[20:23]
	v_mfma_f32_16x16x32_bf16 v[12:15], v[214:217], v[190:193], v[12:15]
	v_mfma_f32_16x16x32_bf16 v[4:7], v[206:209], v[198:201], v[4:7]
	v_mfma_f32_16x16x32_bf16 v[0:3], v[214:217], v[198:201], v[0:3]
	v_mfma_f32_16x16x32_bf16 v[52:55], v[210:213], v[178:181], v[52:55]
	v_mfma_f32_16x16x32_bf16 v[44:47], v[218:221], v[178:181], v[44:47]
	v_mfma_f32_16x16x32_bf16 v[36:39], v[210:213], v[186:189], v[36:39]
	v_mfma_f32_16x16x32_bf16 v[28:31], v[218:221], v[186:189], v[28:31]
	v_mfma_f32_16x16x32_bf16 v[20:23], v[210:213], v[194:197], v[20:23]
	v_mfma_f32_16x16x32_bf16 v[12:15], v[218:221], v[194:197], v[12:15]
	v_mfma_f32_16x16x32_bf16 v[4:7], v[210:213], v[202:205], v[4:7]
	v_mfma_f32_16x16x32_bf16 v[0:3], v[218:221], v[202:205], v[0:3]
	s_add_i32 s48, 0, 0x18000
	v_add_u32_e32 v162, s48, v171
	s_barrier
	ds_read_b128 v[146:149], v162
	ds_read_b128 v[154:157], v162 offset:1024
	ds_read_b128 v[158:161], v162 offset:2048
	ds_read_b128 v[162:165], v162 offset:3072
	s_add_u32 s24, s24, 0x40000
	s_addc_u32 s25, s25, 0
	s_mov_b32 m0, s31
	v_lshl_add_u64 v[206:207], s[24:25], 0, v[134:135]
	ds_read_b128 v[166:169], v174 offset:32768
	ds_read_b128 v[178:181], v174 offset:33792
	ds_read_b128 v[182:185], v174 offset:34816
	ds_read_b128 v[186:189], v174 offset:35840
	ds_read_b128 v[190:193], v174 offset:36864
	ds_read_b128 v[194:197], v174 offset:37888
	ds_read_b128 v[198:201], v174 offset:38912
	ds_read_b128 v[202:205], v174 offset:39936
	global_load_lds_dwordx4 v[206:207], off
	v_lshl_add_u64 v[206:207], s[24:25], 0, v[130:131]
	s_mov_b32 m0, s33
	s_nop 0
	global_load_lds_dwordx4 v[206:207], off
	s_waitcnt lgkmcnt(8)
	s_barrier
	s_waitcnt lgkmcnt(0)
	v_mfma_f32_16x16x32_bf16 v[124:127], v[146:149], v[166:169], v[124:127]
	v_mfma_f32_16x16x32_bf16 v[120:123], v[158:161], v[166:169], v[120:123]
	v_mfma_f32_16x16x32_bf16 v[112:115], v[146:149], v[182:185], v[112:115]
	v_mfma_f32_16x16x32_bf16 v[104:107], v[158:161], v[182:185], v[104:107]
	v_mfma_f32_16x16x32_bf16 v[92:95], v[146:149], v[190:193], v[92:95]
	v_mfma_f32_16x16x32_bf16 v[88:91], v[158:161], v[190:193], v[88:91]
	v_mfma_f32_16x16x32_bf16 v[80:83], v[146:149], v[198:201], v[80:83]
	v_mfma_f32_16x16x32_bf16 v[72:75], v[158:161], v[198:201], v[72:75]
	v_mfma_f32_16x16x32_bf16 v[124:127], v[154:157], v[178:181], v[124:127]
	v_mfma_f32_16x16x32_bf16 v[120:123], v[162:165], v[178:181], v[120:123]
	v_mfma_f32_16x16x32_bf16 v[112:115], v[154:157], v[186:189], v[112:115]
	v_mfma_f32_16x16x32_bf16 v[104:107], v[162:165], v[186:189], v[104:107]
	v_mfma_f32_16x16x32_bf16 v[92:95], v[154:157], v[194:197], v[92:95]
	v_mfma_f32_16x16x32_bf16 v[88:91], v[162:165], v[194:197], v[88:91]
	v_mfma_f32_16x16x32_bf16 v[80:83], v[154:157], v[202:205], v[80:83]
	v_mfma_f32_16x16x32_bf16 v[72:75], v[162:165], v[202:205], v[72:75]
	s_barrier
	s_add_i32 s24, 0, 0x1c000
	s_add_i32 s25, s48, s27
	v_add_u32_e32 v177, s24, v171
	v_lshl_add_u64 v[150:151], v[150:151], 0, s[4:5]
	s_mov_b32 m0, s25
	ds_read_b128 v[206:209], v177
	ds_read_b128 v[210:213], v177 offset:1024
	ds_read_b128 v[214:217], v177 offset:2048
	ds_read_b128 v[218:221], v177 offset:3072
	global_load_lds_dwordx4 v[150:151], off
	v_lshl_add_u64 v[150:151], v[222:223], 0, s[4:5]
	s_add_i32 m0, s25, 0x2000
	s_nop 0
	global_load_lds_dwordx4 v[150:151], off
	s_barrier
	s_waitcnt lgkmcnt(0)
	v_mfma_f32_16x16x32_bf16 v[116:119], v[206:209], v[166:169], v[116:119]
	v_mfma_f32_16x16x32_bf16 v[108:111], v[214:217], v[166:169], v[108:111]
	v_mfma_f32_16x16x32_bf16 v[100:103], v[206:209], v[182:185], v[100:103]
	v_mfma_f32_16x16x32_bf16 v[96:99], v[214:217], v[182:185], v[96:99]
	v_mfma_f32_16x16x32_bf16 v[84:87], v[206:209], v[190:193], v[84:87]
	v_mfma_f32_16x16x32_bf16 v[76:79], v[214:217], v[190:193], v[76:79]
	v_mfma_f32_16x16x32_bf16 v[68:71], v[206:209], v[198:201], v[68:71]
	v_mfma_f32_16x16x32_bf16 v[64:67], v[214:217], v[198:201], v[64:67]
	v_mfma_f32_16x16x32_bf16 v[116:119], v[210:213], v[178:181], v[116:119]
	v_mfma_f32_16x16x32_bf16 v[108:111], v[218:221], v[178:181], v[108:111]
	v_mfma_f32_16x16x32_bf16 v[100:103], v[210:213], v[186:189], v[100:103]
	v_mfma_f32_16x16x32_bf16 v[96:99], v[218:221], v[186:189], v[96:99]
	v_mfma_f32_16x16x32_bf16 v[84:87], v[210:213], v[194:197], v[84:87]
	v_mfma_f32_16x16x32_bf16 v[76:79], v[218:221], v[194:197], v[76:79]
	v_mfma_f32_16x16x32_bf16 v[68:71], v[210:213], v[202:205], v[68:71]
	v_mfma_f32_16x16x32_bf16 v[64:67], v[218:221], v[202:205], v[64:67]
	s_mov_b32 m0, s35
	v_lshl_add_u64 v[150:151], v[224:225], 0, s[4:5]
	s_barrier
	ds_read_b128 v[166:169], v174 offset:49152
	ds_read_b128 v[178:181], v174 offset:50176
	ds_read_b128 v[182:185], v174 offset:51200
	ds_read_b128 v[186:189], v174 offset:52224
	ds_read_b128 v[190:193], v174 offset:53248
	ds_read_b128 v[194:197], v174 offset:54272
	ds_read_b128 v[198:201], v174 offset:55296
	ds_read_b128 v[202:205], v174 offset:56320
	global_load_lds_dwordx4 v[150:151], off
	v_lshl_add_u64 v[150:151], v[226:227], 0, s[4:5]
	s_mov_b32 m0, s36
	s_nop 0
	global_load_lds_dwordx4 v[150:151], off
	s_barrier
; __device__ __forceinline__ unsigned pk2(float lo, float hi) { const f32x2 v = (f32x2){lo, hi}; const bf16x2_t b = __builtin_convertvector(v, bf16x2_t); return __builtin_bit_cast(unsigned, b); }
; #define PG8_STAGE(bufoff, gbase, voff) do { _Pragma("unroll") for (int _i = 0; _i < 2; ++_i) \
;         __builtin_amdgcn_global_load_lds((const unsigned*)((const char*)(gbase) + (voff)[_i]), (LAS unsigned*)(lds + (bufoff) + ldsw + _i * 8192), 16, 0, 0); } while (0)
; #define PG8_MMA(ai, bj, At, Bt) do { __builtin_amdgcn_s_setprio(1); _Pragma("unroll") for (int m = 0; m < 4; ++m) _Pragma("unroll") for (int n = 0; n < 2; ++n) _Pragma("unroll") for (int k = 0; k < 2; ++k) \
;         acc[ai][bj][m][n] = __builtin_amdgcn_mfma_f32_16x16x32_bf16(Bt[n][k], At[m][k], acc[ai][bj][m][n], 0, 0, 0); __builtin_amdgcn_s_setprio(0); } while (0)
; #define PG8_WAIT_V(n) asm volatile("s_waitcnt vmcnt(" #n ")" ::: "memory")
; #define PG8_WAIT_L(n) asm volatile("s_waitcnt lgkmcnt(" #n ")" ::: "memory")
;     __device__ __forceinline__ void operator()(const f32x4 (&acc)[2][2][4][2], const Unit& u, int wr, int wc, int fr, int fq, const float (&)[8]) const {
;     ...
;         const int col0 = u.pn * BM + wc * 32 + 8 * fq;
; #pragma unroll
;         for (int ai = 0; ai < 2; ++ai)
; #pragma unroll
;             for (int m = 0; m < 4; ++m) { const int row = row0 + ai * HALF + m * 16; const float rs = rsqrtf(ep[ai * 4 + m] * (1.0f / 1024.0f) + EPS);
;                 u16* rowp = O + (size_t)row * ldc + col0;
; #pragma unroll
;                 for (int bj = 0; bj < 2; ++bj) { f32x4 v0 = acc[ai][bj][m][0] * rs, v1 = acc[ai][bj][m][1] * rs;
;                     if (ACT == 1) {
; #pragma unroll
;                         for (int j = 0; j < 4; ++j) { const float a0 = fmaxf(v0[j], 0.f), a1 = fmaxf(v1[j], 0.f); v0[j] = a0 * a0; v1[j] = a1 * a1; } }
;                     u32x4 w; w.x = pk2(v0[0], v0[1]); w.y = pk2(v0[2], v0[3]); w.z = pk2(v1[0], v1[1]); w.w = pk2(v1[2], v1[3]);
;                     *(u32x4*)(rowp + bj * HALF) = w; } }
; template <class Epi>
; __device__ __forceinline__ void gemm_phase(LAS unsigned char* lds, const Gemm g, const StaticOrder& S, const Epi& E) {
;     ...
;             PG8_BAR; PG8_WAIT_L(0); PG8_MMA(1, 0, At, B0); PG8_BAR; PG8_SCHED;
;             PG8_STAGE(PG8_SB(1, 1), b3 + hstepB, voffB);
;             PG8_WAIT_V(6); PG8_BAR; PG8_MMA(1, 1, At, B1); PG8_BAR;
	s_waitcnt lgkmcnt(0)
	v_mfma_f32_16x16x32_bf16 v[60:63], v[146:149], v[166:169], v[60:63]
	v_mfma_f32_16x16x32_bf16 v[56:59], v[158:161], v[166:169], v[56:59]
	v_mfma_f32_16x16x32_bf16 v[48:51], v[146:149], v[182:185], v[48:51]
	v_mfma_f32_16x16x32_bf16 v[40:43], v[158:161], v[182:185], v[40:43]
	v_mfma_f32_16x16x32_bf16 v[32:35], v[146:149], v[190:193], v[32:35]
	v_mfma_f32_16x16x32_bf16 v[24:27], v[158:161], v[190:193], v[24:27]
	v_mfma_f32_16x16x32_bf16 v[16:19], v[146:149], v[198:201], v[16:19]
	v_mfma_f32_16x16x32_bf16 v[8:11], v[158:161], v[198:201], v[8:11]
	v_mfma_f32_16x16x32_bf16 v[60:63], v[154:157], v[178:181], v[60:63]
	v_mfma_f32_16x16x32_bf16 v[56:59], v[162:165], v[178:181], v[56:59]
	v_mfma_f32_16x16x32_bf16 v[48:51], v[154:157], v[186:189], v[48:51]
	v_mfma_f32_16x16x32_bf16 v[40:43], v[162:165], v[186:189], v[40:43]
	v_mfma_f32_16x16x32_bf16 v[32:35], v[154:157], v[194:197], v[32:35]
	v_mfma_f32_16x16x32_bf16 v[24:27], v[162:165], v[194:197], v[24:27]
	v_mfma_f32_16x16x32_bf16 v[16:19], v[154:157], v[202:205], v[16:19]
	v_mfma_f32_16x16x32_bf16 v[8:11], v[162:165], v[202:205], v[8:11]
	s_barrier
	s_add_u32 s22, s22, 0x40080
	s_addc_u32 s23, s23, 0
	s_add_i32 s24, s24, s27
	v_lshl_add_u64 v[146:147], s[22:23], 0, v[132:133]
	s_mov_b32 m0, s24
	s_nop 0
	global_load_lds_dwordx4 v[146:147], off
	v_lshl_add_u64 v[146:147], s[22:23], 0, v[128:129]
	s_add_i32 m0, s24, 0x2000
	s_nop 0
	global_load_lds_dwordx4 v[146:147], off
	s_waitcnt vmcnt(6)
	s_barrier
	v_mfma_f32_16x16x32_bf16 v[52:55], v[206:209], v[166:169], v[52:55]
	v_mfma_f32_16x16x32_bf16 v[44:47], v[214:217], v[166:169], v[44:47]
	v_mfma_f32_16x16x32_bf16 v[36:39], v[206:209], v[182:185], v[36:39]
	v_mfma_f32_16x16x32_bf16 v[28:31], v[214:217], v[182:185], v[28:31]
	v_mfma_f32_16x16x32_bf16 v[20:23], v[206:209], v[190:193], v[20:23]
	v_mfma_f32_16x16x32_bf16 v[12:15], v[214:217], v[190:193], v[12:15]
	v_mfma_f32_16x16x32_bf16 v[4:7], v[206:209], v[198:201], v[4:7]
	v_mfma_f32_16x16x32_bf16 v[0:3], v[214:217], v[198:201], v[0:3]
	v_mfma_f32_16x16x32_bf16 v[52:55], v[210:213], v[178:181], v[52:55]
	v_mfma_f32_16x16x32_bf16 v[44:47], v[218:221], v[178:181], v[44:47]
	v_mfma_f32_16x16x32_bf16 v[36:39], v[210:213], v[186:189], v[36:39]
	v_mfma_f32_16x16x32_bf16 v[28:31], v[218:221], v[186:189], v[28:31]
	v_mfma_f32_16x16x32_bf16 v[20:23], v[210:213], v[194:197], v[20:23]
	v_mfma_f32_16x16x32_bf16 v[12:15], v[218:221], v[194:197], v[12:15]
	v_mfma_f32_16x16x32_bf16 v[4:7], v[210:213], v[202:205], v[4:7]
	v_mfma_f32_16x16x32_bf16 v[0:3], v[218:221], v[202:205], v[0:3]
	s_add_i32 s47, s47, 2
	s_add_u32 s20, s20, 0x100
	s_addc_u32 s21, s21, 0
	s_add_u32 s45, s45, 0x100
	s_addc_u32 s46, s46, 0
	s_cmp_gt_u32 s47, 13
	s_barrier
	s_cbranch_scc0 .LBB0_922
	s_setprio 0
	s_cmp_ge_u32 s98, 0x100
	s_cbranch_scc0 .Lep4_skip
	s_setprio 1
.Lep4_skip:
	s_bfe_u32 vcc_lo, s18, 0x20003
	s_lshl_b32 vcc_lo, vcc_lo, 10
	s_add_i32 vcc_lo, vcc_lo, 0x20010
	v_lshl_add_u32 v236, v170, 2, vcc_lo
	ds_read_b32 v228, v236
	ds_read_b32 v229, v236 offset:64
	ds_read_b32 v230, v236 offset:128
	ds_read_b32 v231, v236 offset:192
	ds_read_b32 v232, v236 offset:512
	ds_read_b32 v233, v236 offset:576
	ds_read_b32 v234, v236 offset:640
	ds_read_b32 v235, v236 offset:704
	s_waitcnt lgkmcnt(0)
	v_lshl_add_u32 v154, s18, 8, v170
	v_or_b32_e32 v206, 16, v154
	v_or_b32_e32 v168, 32, v154
	v_or_b32_e32 v162, 48, v154
	v_add_u32_e32 v160, 0x80, v154
	v_add_u32_e32 v156, 0x90, v154
	v_add_u32_e32 v150, 0xa0, v154
	v_add_u32_e32 v146, 0xb0, v154
	v_lshl_or_b32 v208, s42, 8, v172
	v_mov_b64_e32 v[148:149], s[96:97]
	v_ashrrev_i32_e32 v209, 31, v208
	v_mad_i64_i32 v[210:211], s[20:21], v154, s40, v[148:149]
	s_nop 0
	v_lshlrev_b64 v[154:155], 1, v[208:209]
	v_lshl_add_u64 v[208:209], v[210:211], 0, v[154:155]
	s_mov_b32 s42, s10
	s_mov_b32 s18, s12
	s_mov_b64 s[22:23], s[16:17]
	s_waitcnt vmcnt(8)
	s_waitcnt lgkmcnt(0)
	s_waitcnt lgkmcnt(0)
	v_mov_b32_e32 v178, v228
	v_pk_mul_f32 v[126:127], v[126:127], v[178:179] op_sel_hi:[1,0]
	v_pk_mul_f32 v[124:125], v[124:125], v[178:179] op_sel_hi:[1,0]
	v_pk_mul_f32 v[190:191], v[122:123], v[178:179] op_sel_hi:[1,0]
	v_pk_mul_f32 v[122:123], v[120:121], v[178:179] op_sel_hi:[1,0]
	v_cvt_pk_bf16_f32 v120, v124, v125
	v_cvt_pk_bf16_f32 v121, v126, v127
	v_cvt_pk_bf16_f32 v122, v122, v123
	v_cvt_pk_bf16_f32 v123, v190, v191
	v_pk_mul_f32 v[116:117], v[116:117], v[178:179] op_sel_hi:[1,0]
	global_store_dwordx4 v[208:209], v[120:123], off
	s_nop 0
	v_pk_mul_f32 v[118:119], v[118:119], v[178:179] op_sel_hi:[1,0]
	v_pk_mul_f32 v[120:121], v[110:111], v[178:179] op_sel_hi:[1,0]
	v_pk_mul_f32 v[110:111], v[108:109], v[178:179] op_sel_hi:[1,0]
	v_cvt_pk_bf16_f32 v108, v116, v117
	v_cvt_pk_bf16_f32 v109, v118, v119
	v_cvt_pk_bf16_f32 v110, v110, v111
	v_cvt_pk_bf16_f32 v111, v120, v121
	global_store_dwordx4 v[208:209], v[108:111], off offset:256
	s_nop 1
	v_mov_b32_e32 v108, v229
	v_mad_i64_i32 v[110:111], s[20:21], v206, s40, v[148:149]
	v_pk_mul_f32 v[114:115], v[114:115], v[108:109] op_sel_hi:[1,0]
	v_pk_mul_f32 v[112:113], v[112:113], v[108:109] op_sel_hi:[1,0]
	v_pk_mul_f32 v[116:117], v[106:107], v[108:109] op_sel_hi:[1,0]
	v_pk_mul_f32 v[106:107], v[104:105], v[108:109] op_sel_hi:[1,0]
	v_lshl_add_u64 v[110:111], v[110:111], 0, v[154:155]
	v_cvt_pk_bf16_f32 v104, v112, v113
	v_cvt_pk_bf16_f32 v105, v114, v115
	v_cvt_pk_bf16_f32 v106, v106, v107
	v_cvt_pk_bf16_f32 v107, v116, v117
	global_store_dwordx4 v[110:111], v[104:107], off
	v_pk_mul_f32 v[100:101], v[100:101], v[108:109] op_sel_hi:[1,0]
	v_pk_mul_f32 v[112:113], v[98:99], v[108:109] op_sel_hi:[1,0]
	v_pk_mul_f32 v[98:99], v[96:97], v[108:109] op_sel_hi:[1,0]
	v_cvt_pk_bf16_f32 v96, v100, v101
	v_pk_mul_f32 v[102:103], v[102:103], v[108:109] op_sel_hi:[1,0]
	v_cvt_pk_bf16_f32 v98, v98, v99
	s_waitcnt lgkmcnt(0)
; __device__ __forceinline__ unsigned pk2(float lo, float hi) { const f32x2 v = (f32x2){lo, hi}; const bf16x2_t b = __builtin_convertvector(v, bf16x2_t); return __builtin_bit_cast(unsigned, b); }
; #define PG8_WAIT_V(n) asm volatile("s_waitcnt vmcnt(" #n ")" ::: "memory")
; #define PG8_BAR __builtin_amdgcn_s_barrier()
;     __device__ __forceinline__ void operator()(const f32x4 (&acc)[2][2][4][2], const Unit& u, int wr, int wc, int fr, int fq, const float (&)[8]) const {
;     ...
;             for (int m = 0; m < 4; ++m) { const int row = row0 + ai * HALF + m * 16; const float rs = rsqrtf(ep[ai * 4 + m] * (1.0f / 1024.0f) + EPS);
;                 u16* rowp = O + (size_t)row * ldc + col0;
; #pragma unroll
;                 for (int bj = 0; bj < 2; ++bj) { f32x4 v0 = acc[ai][bj][m][0] * rs, v1 = acc[ai][bj][m][1] * rs;
;                     if (ACT == 1) {
; #pragma unroll
;                         for (int j = 0; j < 4; ++j) { const float a0 = fmaxf(v0[j], 0.f), a1 = fmaxf(v1[j], 0.f); v0[j] = a0 * a0; v1[j] = a1 * a1; } }
;                     u32x4 w; w.x = pk2(v0[0], v0[1]); w.y = pk2(v0[2], v0[3]); w.z = pk2(v1[0], v1[1]); w.w = pk2(v1[2], v1[3]);
;                     *(u32x4*)(rowp + bj * HALF) = w; } }
; template <class Epi>
; __device__ __forceinline__ void gemm_phase(LAS unsigned char* lds, const Gemm g, const StaticOrder& S, const Epi& E) {
;     ...
;         E(acc, cur, wr, wc, fr, fq, epre);
;         if (!has_next) break;
; #pragma unroll
;         for (int a = 0; a < 2; ++a)
; #pragma unroll
;             for (int b = 0; b < 2; ++b)
; #pragma unroll
;                 for (int m = 0; m < 4; ++m)
; #pragma unroll
;                     for (int n = 0; n < 2; ++n) acc[a][b][m][n] = (f32x4){0.f, 0.f, 0.f, 0.f};
;         cur = nxt; cA = nA; cB = nB; ++ui;
;     }
;     PG8_WAIT_V(0);
;     if (wr == 0) PG8_BAR;
;     PG8_BAR;
	v_cvt_pk_bf16_f32 v97, v102, v103
	v_cvt_pk_bf16_f32 v99, v112, v113
	global_store_dwordx4 v[110:111], v[96:99], off offset:256
	s_nop 0
	s_waitcnt lgkmcnt(0)
	v_mad_i64_i32 v[98:99], s[20:21], v168, s40, v[148:149]
	v_lshl_add_u64 v[98:99], v[98:99], 0, v[154:155]
	v_mov_b32_e32 v100, v230
	v_pk_mul_f32 v[94:95], v[94:95], v[100:101] op_sel_hi:[1,0]
	v_pk_mul_f32 v[92:93], v[92:93], v[100:101] op_sel_hi:[1,0]
	v_pk_mul_f32 v[102:103], v[90:91], v[100:101] op_sel_hi:[1,0]
	v_pk_mul_f32 v[90:91], v[88:89], v[100:101] op_sel_hi:[1,0]
	v_cvt_pk_bf16_f32 v88, v92, v93
	v_cvt_pk_bf16_f32 v89, v94, v95
	v_cvt_pk_bf16_f32 v90, v90, v91
	v_cvt_pk_bf16_f32 v91, v102, v103
	v_pk_mul_f32 v[84:85], v[84:85], v[100:101] op_sel_hi:[1,0]
	global_store_dwordx4 v[98:99], v[88:91], off
	s_nop 0
	v_pk_mul_f32 v[86:87], v[86:87], v[100:101] op_sel_hi:[1,0]
	v_pk_mul_f32 v[88:89], v[78:79], v[100:101] op_sel_hi:[1,0]
	v_pk_mul_f32 v[78:79], v[76:77], v[100:101] op_sel_hi:[1,0]
	v_cvt_pk_bf16_f32 v76, v84, v85
	v_cvt_pk_bf16_f32 v77, v86, v87
	v_cvt_pk_bf16_f32 v78, v78, v79
	v_cvt_pk_bf16_f32 v79, v88, v89
	global_store_dwordx4 v[98:99], v[76:79], off offset:256
	s_nop 1
	v_mov_b32_e32 v76, v231
	v_mad_i64_i32 v[78:79], s[20:21], v162, s40, v[148:149]
	v_pk_mul_f32 v[82:83], v[82:83], v[76:77] op_sel_hi:[1,0]
	v_pk_mul_f32 v[80:81], v[80:81], v[76:77] op_sel_hi:[1,0]
	v_pk_mul_f32 v[84:85], v[74:75], v[76:77] op_sel_hi:[1,0]
	v_pk_mul_f32 v[74:75], v[72:73], v[76:77] op_sel_hi:[1,0]
	v_lshl_add_u64 v[78:79], v[78:79], 0, v[154:155]
	v_cvt_pk_bf16_f32 v72, v80, v81
	v_cvt_pk_bf16_f32 v73, v82, v83
	v_cvt_pk_bf16_f32 v74, v74, v75
	v_cvt_pk_bf16_f32 v75, v84, v85
	global_store_dwordx4 v[78:79], v[72:75], off
	v_pk_mul_f32 v[68:69], v[68:69], v[76:77] op_sel_hi:[1,0]
	v_pk_mul_f32 v[80:81], v[66:67], v[76:77] op_sel_hi:[1,0]
	v_pk_mul_f32 v[66:67], v[64:65], v[76:77] op_sel_hi:[1,0]
	v_cvt_pk_bf16_f32 v64, v68, v69
	v_pk_mul_f32 v[70:71], v[70:71], v[76:77] op_sel_hi:[1,0]
	v_cvt_pk_bf16_f32 v66, v66, v67
	s_waitcnt lgkmcnt(0)
	v_cvt_pk_bf16_f32 v65, v70, v71
	v_cvt_pk_bf16_f32 v67, v80, v81
	global_store_dwordx4 v[78:79], v[64:67], off offset:256
	s_waitcnt lgkmcnt(0)
	s_nop 0
	s_nop 0
	s_nop 0
	s_nop 1
	v_mad_i64_i32 v[66:67], s[20:21], v160, s40, v[148:149]
	v_lshl_add_u64 v[66:67], v[66:67], 0, v[154:155]
	v_mov_b32_e32 v68, v232
	v_pk_mul_f32 v[62:63], v[62:63], v[68:69] op_sel_hi:[1,0]
	v_pk_mul_f32 v[60:61], v[60:61], v[68:69] op_sel_hi:[1,0]
	v_pk_mul_f32 v[70:71], v[58:59], v[68:69] op_sel_hi:[1,0]
	v_pk_mul_f32 v[58:59], v[56:57], v[68:69] op_sel_hi:[1,0]
	v_cvt_pk_bf16_f32 v56, v60, v61
	v_cvt_pk_bf16_f32 v57, v62, v63
	v_cvt_pk_bf16_f32 v58, v58, v59
	v_cvt_pk_bf16_f32 v59, v70, v71
	v_pk_mul_f32 v[52:53], v[52:53], v[68:69] op_sel_hi:[1,0]
	global_store_dwordx4 v[66:67], v[56:59], off
	s_nop 0
	v_pk_mul_f32 v[54:55], v[54:55], v[68:69] op_sel_hi:[1,0]
	v_pk_mul_f32 v[56:57], v[46:47], v[68:69] op_sel_hi:[1,0]
	v_pk_mul_f32 v[46:47], v[44:45], v[68:69] op_sel_hi:[1,0]
	v_cvt_pk_bf16_f32 v44, v52, v53
	v_cvt_pk_bf16_f32 v45, v54, v55
	v_cvt_pk_bf16_f32 v46, v46, v47
	v_cvt_pk_bf16_f32 v47, v56, v57
	global_store_dwordx4 v[66:67], v[44:47], off offset:256
	s_nop 1
	v_mov_b32_e32 v44, v233
	v_mad_i64_i32 v[46:47], s[20:21], v156, s40, v[148:149]
	v_pk_mul_f32 v[50:51], v[50:51], v[44:45] op_sel_hi:[1,0]
	v_pk_mul_f32 v[48:49], v[48:49], v[44:45] op_sel_hi:[1,0]
	v_pk_mul_f32 v[52:53], v[42:43], v[44:45] op_sel_hi:[1,0]
	v_pk_mul_f32 v[42:43], v[40:41], v[44:45] op_sel_hi:[1,0]
	v_lshl_add_u64 v[46:47], v[46:47], 0, v[154:155]
	v_cvt_pk_bf16_f32 v40, v48, v49
	v_cvt_pk_bf16_f32 v41, v50, v51
	v_cvt_pk_bf16_f32 v42, v42, v43
	v_cvt_pk_bf16_f32 v43, v52, v53
	global_store_dwordx4 v[46:47], v[40:43], off
	v_pk_mul_f32 v[36:37], v[36:37], v[44:45] op_sel_hi:[1,0]
	v_pk_mul_f32 v[48:49], v[30:31], v[44:45] op_sel_hi:[1,0]
	v_pk_mul_f32 v[30:31], v[28:29], v[44:45] op_sel_hi:[1,0]
	v_cvt_pk_bf16_f32 v28, v36, v37
	v_pk_mul_f32 v[38:39], v[38:39], v[44:45] op_sel_hi:[1,0]
	v_cvt_pk_bf16_f32 v30, v30, v31
	s_waitcnt lgkmcnt(0)
	v_cvt_pk_bf16_f32 v29, v38, v39
	v_cvt_pk_bf16_f32 v31, v48, v49
	global_store_dwordx4 v[46:47], v[28:31], off offset:256
	s_waitcnt lgkmcnt(0)
	s_nop 0
	s_nop 0
	s_nop 0
	s_nop 1
	v_mad_i64_i32 v[30:31], s[20:21], v150, s40, v[148:149]
	v_lshl_add_u64 v[30:31], v[30:31], 0, v[154:155]
	v_mov_b32_e32 v36, v234
	v_pk_mul_f32 v[34:35], v[34:35], v[36:37] op_sel_hi:[1,0]
	v_pk_mul_f32 v[32:33], v[32:33], v[36:37] op_sel_hi:[1,0]
	v_pk_mul_f32 v[38:39], v[26:27], v[36:37] op_sel_hi:[1,0]
	v_pk_mul_f32 v[26:27], v[24:25], v[36:37] op_sel_hi:[1,0]
	v_cvt_pk_bf16_f32 v24, v32, v33
	v_cvt_pk_bf16_f32 v25, v34, v35
	v_cvt_pk_bf16_f32 v26, v26, v27
	v_cvt_pk_bf16_f32 v27, v38, v39
	v_pk_mul_f32 v[20:21], v[20:21], v[36:37] op_sel_hi:[1,0]
	global_store_dwordx4 v[30:31], v[24:27], off
	s_nop 0
	v_pk_mul_f32 v[22:23], v[22:23], v[36:37] op_sel_hi:[1,0]
	v_pk_mul_f32 v[24:25], v[14:15], v[36:37] op_sel_hi:[1,0]
	v_pk_mul_f32 v[14:15], v[12:13], v[36:37] op_sel_hi:[1,0]
	v_cvt_pk_bf16_f32 v12, v20, v21
	v_cvt_pk_bf16_f32 v13, v22, v23
	v_cvt_pk_bf16_f32 v14, v14, v15
	v_cvt_pk_bf16_f32 v15, v24, v25
	global_store_dwordx4 v[30:31], v[12:15], off offset:256
	s_nop 1
	v_mov_b32_e32 v12, v235
	v_mad_i64_i32 v[14:15], s[20:21], v146, s40, v[148:149]
	v_pk_mul_f32 v[18:19], v[18:19], v[12:13] op_sel_hi:[1,0]
	v_pk_mul_f32 v[16:17], v[16:17], v[12:13] op_sel_hi:[1,0]
	v_pk_mul_f32 v[20:21], v[10:11], v[12:13] op_sel_hi:[1,0]
	v_pk_mul_f32 v[10:11], v[8:9], v[12:13] op_sel_hi:[1,0]
	v_lshl_add_u64 v[14:15], v[14:15], 0, v[154:155]
	v_cvt_pk_bf16_f32 v8, v16, v17
	v_cvt_pk_bf16_f32 v9, v18, v19
	v_cvt_pk_bf16_f32 v10, v10, v11
	v_cvt_pk_bf16_f32 v11, v20, v21
	global_store_dwordx4 v[14:15], v[8:11], off
	v_pk_mul_f32 v[6:7], v[6:7], v[12:13] op_sel_hi:[1,0]
	v_pk_mul_f32 v[4:5], v[4:5], v[12:13] op_sel_hi:[1,0]
	v_pk_mul_f32 v[8:9], v[2:3], v[12:13] op_sel_hi:[1,0]
	v_pk_mul_f32 v[2:3], v[0:1], v[12:13] op_sel_hi:[1,0]
	v_cvt_pk_bf16_f32 v0, v4, v5
	v_cvt_pk_bf16_f32 v1, v6, v7
	v_cvt_pk_bf16_f32 v2, v2, v3
	v_cvt_pk_bf16_f32 v3, v8, v9
	s_and_b64 vcc, exec, s[0:1]
	s_mov_b64 s[20:21], s[14:15]
	global_store_dwordx4 v[14:15], v[0:3], off offset:256
	s_cbranch_vccz .LBB0_919
	s_waitcnt vmcnt(0)
	v_readlane_b32 s40, v251, 54
	s_cmpk_gt_u32 s7, 0xff
	v_readlane_b32 s41, v251, 55
	s_cbranch_scc1 .LBB0_926
	s_barrier

; #define PG8_STAGE(bufoff, gbase, voff) do { _Pragma("unroll") for (int _i = 0; _i < 2; ++_i) \
;         __builtin_amdgcn_global_load_lds((const unsigned*)((const char*)(gbase) + (voff)[_i]), (LAS unsigned*)(lds + (bufoff) + ldsw + _i * 8192), 16, 0, 0); } while (0)
; #define PG8_LDA(dst, b, h) do { _Pragma("unroll") for (int m = 0; m < 4; ++m) _Pragma("unroll") for (int k = 0; k < 2; ++k) dst[m][k] = *(const LAS bf16x8*)(lds + PG8_SA(b, h) + aoff + m * 2048 + k * 1024); } while (0)
; #define PG8_LDB(dst, b, h) do { _Pragma("unroll") for (int n = 0; n < 2; ++n) _Pragma("unroll") for (int k = 0; k < 2; ++k) dst[n][k] = *(const LAS bf16x8*)(lds + PG8_SB(b, h) + boff + n * 2048 + k * 1024); } while (0)
; #define PG8_MMA(ai, bj, At, Bt) do { __builtin_amdgcn_s_setprio(1); _Pragma("unroll") for (int m = 0; m < 4; ++m) _Pragma("unroll") for (int n = 0; n < 2; ++n) _Pragma("unroll") for (int k = 0; k < 2; ++k) \
;         acc[ai][bj][m][n] = __builtin_amdgcn_mfma_f32_16x16x32_bf16(Bt[n][k], At[m][k], acc[ai][bj][m][n], 0, 0, 0); __builtin_amdgcn_s_setprio(0); } while (0)
; #define PG8_WAIT_L(n) asm volatile("s_waitcnt lgkmcnt(" #n ")" ::: "memory")
; #define PG8_BAR __builtin_amdgcn_s_barrier()
; #define PG8_SCHED __builtin_amdgcn_sched_barrier(0)
; template <class Epi>
; __device__ __forceinline__ void gemm_phase(LAS unsigned char* lds, const Gemm g, const StaticOrder& S, const Epi& E) {
;     ...
;             PG8_LDB(B0, 0, 0); PG8_SCHED; PG8_LDA(At, 0, 0); PG8_STAGE(PG8_SA(1, 1), a1 + hstepA, voffA);
;             PG8_WAIT_L(8); PG8_BAR; PG8_WAIT_L(0); PG8_MMA(0, 0, At, B0); PG8_BAR; PG8_SCHED;
;             PG8_LDB(B1, 0, 1); PG8_STAGE(PG8_SB(0, 0), b2, voffB);
;             PG8_BAR; PG8_WAIT_L(0); PG8_MMA(0, 1, At, B1); PG8_BAR;
;             PG8_LDA(At, 0, 1); PG8_STAGE(PG8_SA(0, 0), a2, voffA);
;             PG8_BAR; PG8_WAIT_L(0); PG8_MMA(1, 0, At, B0); PG8_BAR; PG8_SCHED;
.LBB0_1118:
	ds_read_b128 v[128:131], v190
	ds_read_b128 v[132:135], v190 offset:1024
	ds_read_b128 v[136:139], v190 offset:2048
	ds_read_b128 v[140:143], v190 offset:3072
	s_add_u32 s22, s4, 0xffec0080
	s_addc_u32 s23, s5, -1
	s_cmp_eq_u32 s46, 12
	s_cselect_b32 s25, s19, s23
	s_cselect_b32 s24, s18, s22
	s_cselect_b32 s23, s17, s45
	s_cselect_b32 s22, s43, s44
	v_lshl_add_u64 v[186:187], s[4:5], 0, v[162:163]
	s_add_i32 m0, s9, 0xc000
	ds_read_b128 v[144:147], v191
	ds_read_b128 v[148:151], v191 offset:1024
	ds_read_b128 v[170:173], v191 offset:2048
	ds_read_b128 v[174:177], v191 offset:3072
	ds_read_b128 v[178:181], v191 offset:4096
	ds_read_b128 v[182:185], v191 offset:5120
	ds_read_b128 v[194:197], v191 offset:6144
	ds_read_b128 v[198:201], v191 offset:7168
	global_load_lds_dwordx4 v[186:187], off
	v_lshl_add_u64 v[186:187], s[4:5], 0, v[164:165]
	s_add_i32 m0, s9, 0xe000
	s_nop 0
	global_load_lds_dwordx4 v[186:187], off
	s_waitcnt lgkmcnt(8)
	s_barrier
	s_waitcnt lgkmcnt(0)
	v_mfma_f32_16x16x32_bf16 v[124:127], v[128:131], v[144:147], v[124:127]
	v_mfma_f32_16x16x32_bf16 v[120:123], v[136:139], v[144:147], v[120:123]
	v_mfma_f32_16x16x32_bf16 v[108:111], v[128:131], v[170:173], v[108:111]
	v_mfma_f32_16x16x32_bf16 v[104:107], v[136:139], v[170:173], v[104:107]
	v_mfma_f32_16x16x32_bf16 v[92:95], v[128:131], v[178:181], v[92:95]
	v_mfma_f32_16x16x32_bf16 v[88:91], v[136:139], v[178:181], v[88:91]
	v_mfma_f32_16x16x32_bf16 v[76:79], v[128:131], v[194:197], v[76:79]
	v_mfma_f32_16x16x32_bf16 v[72:75], v[136:139], v[194:197], v[72:75]
	v_mfma_f32_16x16x32_bf16 v[124:127], v[132:135], v[148:151], v[124:127]
	v_mfma_f32_16x16x32_bf16 v[120:123], v[140:143], v[148:151], v[120:123]
	v_mfma_f32_16x16x32_bf16 v[108:111], v[132:135], v[174:177], v[108:111]
	v_mfma_f32_16x16x32_bf16 v[104:107], v[140:143], v[174:177], v[104:107]
	v_mfma_f32_16x16x32_bf16 v[92:95], v[132:135], v[182:185], v[92:95]
	v_mfma_f32_16x16x32_bf16 v[88:91], v[140:143], v[182:185], v[88:91]
	v_mfma_f32_16x16x32_bf16 v[76:79], v[132:135], v[198:201], v[76:79]
	v_mfma_f32_16x16x32_bf16 v[72:75], v[140:143], v[198:201], v[72:75]
	s_barrier
	s_add_i32 s47, s40, s29
	v_lshl_add_u64 v[186:187], s[22:23], 0, v[156:157]
	s_mov_b32 m0, s47
	ds_read_b128 v[202:205], v192
	ds_read_b128 v[206:209], v192 offset:1024
	ds_read_b128 v[210:213], v192 offset:2048
	ds_read_b128 v[214:217], v192 offset:3072
	global_load_lds_dwordx4 v[186:187], off
	v_lshl_add_u64 v[218:219], s[22:23], 0, v[160:161]
	s_add_i32 m0, s47, 0x2000
	s_nop 0
	global_load_lds_dwordx4 v[218:219], off
	s_barrier
	s_waitcnt lgkmcnt(0)
	v_mfma_f32_16x16x32_bf16 v[116:119], v[202:205], v[144:147], v[116:119]
	v_mfma_f32_16x16x32_bf16 v[112:115], v[210:213], v[144:147], v[112:115]
	v_mfma_f32_16x16x32_bf16 v[100:103], v[202:205], v[170:173], v[100:103]
	v_mfma_f32_16x16x32_bf16 v[96:99], v[210:213], v[170:173], v[96:99]
	v_mfma_f32_16x16x32_bf16 v[84:87], v[202:205], v[178:181], v[84:87]
	v_mfma_f32_16x16x32_bf16 v[80:83], v[210:213], v[178:181], v[80:83]
	v_mfma_f32_16x16x32_bf16 v[68:71], v[202:205], v[194:197], v[68:71]
	v_mfma_f32_16x16x32_bf16 v[64:67], v[210:213], v[194:197], v[64:67]
	v_mfma_f32_16x16x32_bf16 v[116:119], v[206:209], v[148:151], v[116:119]
	v_mfma_f32_16x16x32_bf16 v[112:115], v[214:217], v[148:151], v[112:115]
	v_mfma_f32_16x16x32_bf16 v[100:103], v[206:209], v[174:177], v[100:103]
	v_mfma_f32_16x16x32_bf16 v[96:99], v[214:217], v[174:177], v[96:99]
	v_mfma_f32_16x16x32_bf16 v[84:87], v[206:209], v[182:185], v[84:87]
	v_mfma_f32_16x16x32_bf16 v[80:83], v[214:217], v[182:185], v[80:83]
	v_mfma_f32_16x16x32_bf16 v[68:71], v[206:209], v[198:201], v[68:71]
	v_mfma_f32_16x16x32_bf16 v[64:67], v[214:217], v[198:201], v[64:67]
	s_mov_b32 m0, s9
	v_lshl_add_u64 v[220:221], s[24:25], 0, v[154:155]
	s_barrier
	ds_read_b128 v[144:147], v191 offset:16384
	ds_read_b128 v[148:151], v191 offset:17408
	ds_read_b128 v[170:173], v191 offset:18432
	ds_read_b128 v[174:177], v191 offset:19456
	ds_read_b128 v[178:181], v191 offset:20480
	ds_read_b128 v[182:185], v191 offset:21504
	ds_read_b128 v[194:197], v191 offset:22528
	ds_read_b128 v[198:201], v191 offset:23552
	global_load_lds_dwordx4 v[220:221], off
	v_lshl_add_u64 v[222:223], s[24:25], 0, v[158:159]
	s_mov_b32 m0, s30
	s_nop 0
	global_load_lds_dwordx4 v[222:223], off
	s_barrier
	s_waitcnt lgkmcnt(0)
	v_mfma_f32_16x16x32_bf16 v[60:63], v[128:131], v[144:147], v[60:63]
	v_mfma_f32_16x16x32_bf16 v[56:59], v[136:139], v[144:147], v[56:59]
	v_mfma_f32_16x16x32_bf16 v[44:47], v[128:131], v[170:173], v[44:47]
	v_mfma_f32_16x16x32_bf16 v[40:43], v[136:139], v[170:173], v[40:43]
	v_mfma_f32_16x16x32_bf16 v[28:31], v[128:131], v[178:181], v[28:31]
	v_mfma_f32_16x16x32_bf16 v[24:27], v[136:139], v[178:181], v[24:27]
	v_mfma_f32_16x16x32_bf16 v[12:15], v[128:131], v[194:197], v[12:15]
	v_mfma_f32_16x16x32_bf16 v[8:11], v[136:139], v[194:197], v[8:11]
	v_mfma_f32_16x16x32_bf16 v[60:63], v[132:135], v[148:151], v[60:63]
	v_mfma_f32_16x16x32_bf16 v[56:59], v[140:143], v[148:151], v[56:59]
	v_mfma_f32_16x16x32_bf16 v[44:47], v[132:135], v[174:177], v[44:47]
	v_mfma_f32_16x16x32_bf16 v[40:43], v[140:143], v[174:177], v[40:43]
	v_mfma_f32_16x16x32_bf16 v[28:31], v[132:135], v[182:185], v[28:31]
	v_mfma_f32_16x16x32_bf16 v[24:27], v[140:143], v[182:185], v[24:27]
	v_mfma_f32_16x16x32_bf16 v[12:15], v[132:135], v[198:201], v[12:15]
	v_mfma_f32_16x16x32_bf16 v[8:11], v[140:143], v[198:201], v[8:11]
	s_barrier
; #define PG8_STAGE(bufoff, gbase, voff) do { _Pragma("unroll") for (int _i = 0; _i < 2; ++_i) \
;         __builtin_amdgcn_global_load_lds((const unsigned*)((const char*)(gbase) + (voff)[_i]), (LAS unsigned*)(lds + (bufoff) + ldsw + _i * 8192), 16, 0, 0); } while (0)
; #define PG8_LDA(dst, b, h) do { _Pragma("unroll") for (int m = 0; m < 4; ++m) _Pragma("unroll") for (int k = 0; k < 2; ++k) dst[m][k] = *(const LAS bf16x8*)(lds + PG8_SA(b, h) + aoff + m * 2048 + k * 1024); } while (0)
; #define PG8_LDB(dst, b, h) do { _Pragma("unroll") for (int n = 0; n < 2; ++n) _Pragma("unroll") for (int k = 0; k < 2; ++k) dst[n][k] = *(const LAS bf16x8*)(lds + PG8_SB(b, h) + boff + n * 2048 + k * 1024); } while (0)
; #define PG8_MMA(ai, bj, At, Bt) do { __builtin_amdgcn_s_setprio(1); _Pragma("unroll") for (int m = 0; m < 4; ++m) _Pragma("unroll") for (int n = 0; n < 2; ++n) _Pragma("unroll") for (int k = 0; k < 2; ++k) \
;         acc[ai][bj][m][n] = __builtin_amdgcn_mfma_f32_16x16x32_bf16(Bt[n][k], At[m][k], acc[ai][bj][m][n], 0, 0, 0); __builtin_amdgcn_s_setprio(0); } while (0)
; #define PG8_WAIT_V(n) asm volatile("s_waitcnt vmcnt(" #n ")" ::: "memory")
; #define PG8_WAIT_L(n) asm volatile("s_waitcnt lgkmcnt(" #n ")" ::: "memory")
; #define PG8_BAR __builtin_amdgcn_s_barrier()
; #define PG8_SCHED __builtin_amdgcn_sched_barrier(0)
; template <class Epi>
; __device__ __forceinline__ void gemm_phase(LAS unsigned char* lds, const Gemm g, const StaticOrder& S, const Epi& E) {
;     ...
;             PG8_STAGE(PG8_SB(0, 1), b2 + hstepB, voffB);
;             PG8_WAIT_V(6); PG8_BAR; PG8_MMA(1, 1, At, B1); PG8_BAR;
;             PG8_LDB(B0, 1, 0); PG8_SCHED; PG8_LDA(At, 1, 0); PG8_STAGE(PG8_SA(0, 1), a2 + hstepA, voffA);
;             PG8_WAIT_L(8); PG8_BAR; PG8_WAIT_L(0); PG8_MMA(0, 0, At, B0); PG8_BAR; PG8_SCHED;
;             PG8_LDB(B1, 1, 1); PG8_STAGE(PG8_SB(1, 0), b3, voffB);
;             PG8_BAR; PG8_WAIT_L(0); PG8_MMA(0, 1, At, B1); PG8_BAR;
;             PG8_LDA(At, 1, 1); PG8_STAGE(PG8_SA(1, 0), a3, voffA);
;             PG8_BAR; PG8_WAIT_L(0); PG8_MMA(1, 0, At, B0); PG8_BAR; PG8_SCHED;
	s_add_u32 s48, s22, 0x40000
	s_addc_u32 s49, s23, 0
	s_add_i32 s47, s41, s29
	v_lshl_add_u64 v[128:129], s[48:49], 0, v[156:157]
	s_mov_b32 m0, s47
	s_nop 0
	global_load_lds_dwordx4 v[128:129], off
	v_lshl_add_u64 v[128:129], s[48:49], 0, v[160:161]
	s_add_i32 m0, s47, 0x2000
	s_nop 0
	global_load_lds_dwordx4 v[128:129], off
	s_waitcnt vmcnt(6)
	s_barrier
	v_mfma_f32_16x16x32_bf16 v[52:55], v[202:205], v[144:147], v[52:55]
	v_mfma_f32_16x16x32_bf16 v[48:51], v[210:213], v[144:147], v[48:51]
	v_mfma_f32_16x16x32_bf16 v[36:39], v[202:205], v[170:173], v[36:39]
	v_mfma_f32_16x16x32_bf16 v[32:35], v[210:213], v[170:173], v[32:35]
	v_mfma_f32_16x16x32_bf16 v[20:23], v[202:205], v[178:181], v[20:23]
	v_mfma_f32_16x16x32_bf16 v[16:19], v[210:213], v[178:181], v[16:19]
	v_mfma_f32_16x16x32_bf16 v[4:7], v[202:205], v[194:197], v[4:7]
	v_mfma_f32_16x16x32_bf16 v[0:3], v[210:213], v[194:197], v[0:3]
	v_mfma_f32_16x16x32_bf16 v[52:55], v[206:209], v[148:151], v[52:55]
	v_mfma_f32_16x16x32_bf16 v[48:51], v[214:217], v[148:151], v[48:51]
	v_mfma_f32_16x16x32_bf16 v[36:39], v[206:209], v[174:177], v[36:39]
	v_mfma_f32_16x16x32_bf16 v[32:35], v[214:217], v[174:177], v[32:35]
	v_mfma_f32_16x16x32_bf16 v[20:23], v[206:209], v[182:185], v[20:23]
	v_mfma_f32_16x16x32_bf16 v[16:19], v[214:217], v[182:185], v[16:19]
	v_mfma_f32_16x16x32_bf16 v[4:7], v[206:209], v[198:201], v[4:7]
	v_mfma_f32_16x16x32_bf16 v[0:3], v[214:217], v[198:201], v[0:3]
	s_add_i32 s47, 0, 0x18000
	v_add_u32_e32 v140, s47, v188
	s_barrier
	ds_read_b128 v[128:131], v140
	ds_read_b128 v[132:135], v140 offset:1024
	ds_read_b128 v[136:139], v140 offset:2048
	ds_read_b128 v[140:143], v140 offset:3072
	s_add_u32 s24, s24, 0x140000
	s_addc_u32 s25, s25, 0
	s_mov_b32 m0, s31
	v_lshl_add_u64 v[202:203], s[24:25], 0, v[154:155]
	ds_read_b128 v[144:147], v191 offset:32768
	ds_read_b128 v[148:151], v191 offset:33792
	ds_read_b128 v[170:173], v191 offset:34816
	ds_read_b128 v[174:177], v191 offset:35840
	ds_read_b128 v[178:181], v191 offset:36864
	ds_read_b128 v[182:185], v191 offset:37888
	ds_read_b128 v[194:197], v191 offset:38912
	ds_read_b128 v[198:201], v191 offset:39936
	global_load_lds_dwordx4 v[202:203], off
	v_lshl_add_u64 v[202:203], s[24:25], 0, v[158:159]
	s_mov_b32 m0, s34
	s_nop 0
	global_load_lds_dwordx4 v[202:203], off
	s_waitcnt lgkmcnt(8)
	s_barrier
	s_waitcnt lgkmcnt(0)
	v_mfma_f32_16x16x32_bf16 v[124:127], v[128:131], v[144:147], v[124:127]
	v_mfma_f32_16x16x32_bf16 v[120:123], v[136:139], v[144:147], v[120:123]
	v_mfma_f32_16x16x32_bf16 v[108:111], v[128:131], v[170:173], v[108:111]
	v_mfma_f32_16x16x32_bf16 v[104:107], v[136:139], v[170:173], v[104:107]
	v_mfma_f32_16x16x32_bf16 v[92:95], v[128:131], v[178:181], v[92:95]
	v_mfma_f32_16x16x32_bf16 v[88:91], v[136:139], v[178:181], v[88:91]
	v_mfma_f32_16x16x32_bf16 v[76:79], v[128:131], v[194:197], v[76:79]
	v_mfma_f32_16x16x32_bf16 v[72:75], v[136:139], v[194:197], v[72:75]
	v_mfma_f32_16x16x32_bf16 v[124:127], v[132:135], v[148:151], v[124:127]
	v_mfma_f32_16x16x32_bf16 v[120:123], v[140:143], v[148:151], v[120:123]
	v_mfma_f32_16x16x32_bf16 v[108:111], v[132:135], v[174:177], v[108:111]
	v_mfma_f32_16x16x32_bf16 v[104:107], v[140:143], v[174:177], v[104:107]
	v_mfma_f32_16x16x32_bf16 v[92:95], v[132:135], v[182:185], v[92:95]
	v_mfma_f32_16x16x32_bf16 v[88:91], v[140:143], v[182:185], v[88:91]
	v_mfma_f32_16x16x32_bf16 v[76:79], v[132:135], v[198:201], v[76:79]
	v_mfma_f32_16x16x32_bf16 v[72:75], v[140:143], v[198:201], v[72:75]
	s_barrier
	s_add_i32 s24, 0, 0x1c000
	s_add_i32 s25, s47, s29
	v_add_u32_e32 v214, s24, v188
	v_lshl_add_u64 v[186:187], v[186:187], 0, s[14:15]
	s_mov_b32 m0, s25
	ds_read_b128 v[202:205], v214
	ds_read_b128 v[206:209], v214 offset:1024
	ds_read_b128 v[210:213], v214 offset:2048
	ds_read_b128 v[214:217], v214 offset:3072
	global_load_lds_dwordx4 v[186:187], off
	v_lshl_add_u64 v[186:187], v[218:219], 0, s[14:15]
	s_add_i32 m0, s25, 0x2000
	s_nop 0
	global_load_lds_dwordx4 v[186:187], off
	s_barrier
	s_waitcnt lgkmcnt(0)
	v_mfma_f32_16x16x32_bf16 v[116:119], v[202:205], v[144:147], v[116:119]
	v_mfma_f32_16x16x32_bf16 v[112:115], v[210:213], v[144:147], v[112:115]
	v_mfma_f32_16x16x32_bf16 v[100:103], v[202:205], v[170:173], v[100:103]
	v_mfma_f32_16x16x32_bf16 v[96:99], v[210:213], v[170:173], v[96:99]
	v_mfma_f32_16x16x32_bf16 v[84:87], v[202:205], v[178:181], v[84:87]
	v_mfma_f32_16x16x32_bf16 v[80:83], v[210:213], v[178:181], v[80:83]
	v_mfma_f32_16x16x32_bf16 v[68:71], v[202:205], v[194:197], v[68:71]
	v_mfma_f32_16x16x32_bf16 v[64:67], v[210:213], v[194:197], v[64:67]
	v_mfma_f32_16x16x32_bf16 v[116:119], v[206:209], v[148:151], v[116:119]
	v_mfma_f32_16x16x32_bf16 v[112:115], v[214:217], v[148:151], v[112:115]
	v_mfma_f32_16x16x32_bf16 v[100:103], v[206:209], v[174:177], v[100:103]
	v_mfma_f32_16x16x32_bf16 v[96:99], v[214:217], v[174:177], v[96:99]
	v_mfma_f32_16x16x32_bf16 v[84:87], v[206:209], v[182:185], v[84:87]
	v_mfma_f32_16x16x32_bf16 v[80:83], v[214:217], v[182:185], v[80:83]
	v_mfma_f32_16x16x32_bf16 v[68:71], v[206:209], v[198:201], v[68:71]
	v_mfma_f32_16x16x32_bf16 v[64:67], v[214:217], v[198:201], v[64:67]
	s_mov_b32 m0, s36
	v_lshl_add_u64 v[186:187], v[220:221], 0, s[14:15]
	s_barrier
	ds_read_b128 v[144:147], v191 offset:49152
	ds_read_b128 v[148:151], v191 offset:50176
	ds_read_b128 v[170:173], v191 offset:51200
	ds_read_b128 v[174:177], v191 offset:52224
	ds_read_b128 v[178:181], v191 offset:53248
	ds_read_b128 v[182:185], v191 offset:54272
	ds_read_b128 v[194:197], v191 offset:55296
	ds_read_b128 v[198:201], v191 offset:56320
	global_load_lds_dwordx4 v[186:187], off
	v_lshl_add_u64 v[186:187], v[222:223], 0, s[14:15]
	s_mov_b32 m0, s37
	s_nop 0
	global_load_lds_dwordx4 v[186:187], off
	s_barrier
; #define PG8_STAGE(bufoff, gbase, voff) do { _Pragma("unroll") for (int _i = 0; _i < 2; ++_i) \
;         __builtin_amdgcn_global_load_lds((const unsigned*)((const char*)(gbase) + (voff)[_i]), (LAS unsigned*)(lds + (bufoff) + ldsw + _i * 8192), 16, 0, 0); } while (0)
; #define PG8_MMA(ai, bj, At, Bt) do { __builtin_amdgcn_s_setprio(1); _Pragma("unroll") for (int m = 0; m < 4; ++m) _Pragma("unroll") for (int n = 0; n < 2; ++n) _Pragma("unroll") for (int k = 0; k < 2; ++k) \
;         acc[ai][bj][m][n] = __builtin_amdgcn_mfma_f32_16x16x32_bf16(Bt[n][k], At[m][k], acc[ai][bj][m][n], 0, 0, 0); __builtin_amdgcn_s_setprio(0); } while (0)
; #define PG8_WAIT_V(n) asm volatile("s_waitcnt vmcnt(" #n ")" ::: "memory")
; #define PG8_WAIT_L(n) asm volatile("s_waitcnt lgkmcnt(" #n ")" ::: "memory")
; #define PG8_BAR __builtin_amdgcn_s_barrier()
; #define PG8_SCHED __builtin_amdgcn_sched_barrier(0)
; template <class Epi>
; __device__ __forceinline__ void gemm_phase(LAS unsigned char* lds, const Gemm g, const StaticOrder& S, const Epi& E) {
;     ...
;             PG8_BAR; PG8_WAIT_L(0); PG8_MMA(1, 0, At, B0); PG8_BAR; PG8_SCHED;
;             PG8_STAGE(PG8_SB(1, 1), b3 + hstepB, voffB);
;             PG8_WAIT_V(6); PG8_BAR; PG8_MMA(1, 1, At, B1); PG8_BAR;
;         }
;         E(acc, cur, wr, wc, fr, fq, epre);
	s_waitcnt lgkmcnt(0)
	v_mfma_f32_16x16x32_bf16 v[60:63], v[128:131], v[144:147], v[60:63]
	v_mfma_f32_16x16x32_bf16 v[56:59], v[136:139], v[144:147], v[56:59]
	v_mfma_f32_16x16x32_bf16 v[44:47], v[128:131], v[170:173], v[44:47]
	v_mfma_f32_16x16x32_bf16 v[40:43], v[136:139], v[170:173], v[40:43]
	v_mfma_f32_16x16x32_bf16 v[28:31], v[128:131], v[178:181], v[28:31]
	v_mfma_f32_16x16x32_bf16 v[24:27], v[136:139], v[178:181], v[24:27]
	v_mfma_f32_16x16x32_bf16 v[12:15], v[128:131], v[194:197], v[12:15]
	v_mfma_f32_16x16x32_bf16 v[8:11], v[136:139], v[194:197], v[8:11]
	v_mfma_f32_16x16x32_bf16 v[60:63], v[132:135], v[148:151], v[60:63]
	v_mfma_f32_16x16x32_bf16 v[56:59], v[140:143], v[148:151], v[56:59]
	v_mfma_f32_16x16x32_bf16 v[44:47], v[132:135], v[174:177], v[44:47]
	v_mfma_f32_16x16x32_bf16 v[40:43], v[140:143], v[174:177], v[40:43]
	v_mfma_f32_16x16x32_bf16 v[28:31], v[132:135], v[182:185], v[28:31]
	v_mfma_f32_16x16x32_bf16 v[24:27], v[140:143], v[182:185], v[24:27]
	v_mfma_f32_16x16x32_bf16 v[12:15], v[132:135], v[198:201], v[12:15]
	v_mfma_f32_16x16x32_bf16 v[8:11], v[140:143], v[198:201], v[8:11]
	s_barrier
	s_add_u32 s22, s22, 0x40080
	s_addc_u32 s23, s23, 0
	s_add_i32 s24, s24, s29
	v_lshl_add_u64 v[128:129], s[22:23], 0, v[156:157]
	s_mov_b32 m0, s24
	s_nop 0
	global_load_lds_dwordx4 v[128:129], off
	v_lshl_add_u64 v[128:129], s[22:23], 0, v[160:161]
	s_add_i32 m0, s24, 0x2000
	s_nop 0
	global_load_lds_dwordx4 v[128:129], off
	s_waitcnt vmcnt(6)
	s_barrier
	v_mfma_f32_16x16x32_bf16 v[52:55], v[202:205], v[144:147], v[52:55]
	v_mfma_f32_16x16x32_bf16 v[48:51], v[210:213], v[144:147], v[48:51]
	v_mfma_f32_16x16x32_bf16 v[36:39], v[202:205], v[170:173], v[36:39]
	v_mfma_f32_16x16x32_bf16 v[32:35], v[210:213], v[170:173], v[32:35]
	v_mfma_f32_16x16x32_bf16 v[20:23], v[202:205], v[178:181], v[20:23]
	v_mfma_f32_16x16x32_bf16 v[16:19], v[210:213], v[178:181], v[16:19]
	v_mfma_f32_16x16x32_bf16 v[4:7], v[202:205], v[194:197], v[4:7]
	v_mfma_f32_16x16x32_bf16 v[0:3], v[210:213], v[194:197], v[0:3]
	v_mfma_f32_16x16x32_bf16 v[52:55], v[206:209], v[148:151], v[52:55]
	v_mfma_f32_16x16x32_bf16 v[48:51], v[214:217], v[148:151], v[48:51]
	v_mfma_f32_16x16x32_bf16 v[36:39], v[206:209], v[174:177], v[36:39]
	v_mfma_f32_16x16x32_bf16 v[32:35], v[214:217], v[174:177], v[32:35]
	v_mfma_f32_16x16x32_bf16 v[20:23], v[206:209], v[182:185], v[20:23]
	v_mfma_f32_16x16x32_bf16 v[16:19], v[214:217], v[182:185], v[16:19]
	v_mfma_f32_16x16x32_bf16 v[4:7], v[206:209], v[198:201], v[4:7]
	v_mfma_f32_16x16x32_bf16 v[0:3], v[214:217], v[198:201], v[0:3]
	s_add_i32 s46, s46, 2
	s_add_u32 s4, s4, 0x100
	s_addc_u32 s5, s5, 0
	s_add_u32 s44, s44, 0x100
	s_addc_u32 s45, s45, 0
	s_cmp_gt_u32 s46, 13
	s_barrier
	s_cbranch_scc0 .LBB0_1118
	s_setprio 0
	s_cmp_ge_u32 s98, 0x100
	s_cbranch_scc0 .Lep5_skip
	s_setprio 1
; __device__ __forceinline__ unsigned pk2(float lo, float hi) { const f32x2 v = (f32x2){lo, hi}; const bf16x2_t b = __builtin_convertvector(v, bf16x2_t); return __builtin_bit_cast(unsigned, b); }
; __device__ __forceinline__ void unpack8(const u32x4 v, float* f) { f[0] = bf_lo(v.x); f[1] = bf_hi(v.x); f[2] = bf_lo(v.y); f[3] = bf_hi(v.y); f[4] = bf_lo(v.z); f[5] = bf_hi(v.z); f[6] = bf_lo(v.w); f[7] = bf_hi(v.w); }
;     __device__ __forceinline__ void operator()(const f32x4 (&acc)[2][2][4][2], const Unit& u, int wr, int wc, int fr, int fq, const float (&)[8]) const {
;         const int row0 = u.pm * BM + wr * 64 + fr, col0 = u.pn * BM + wc * 32 + 8 * fq;
; #pragma unroll
;         for (int ai = 0; ai < 2; ++ai) {
;             u32x4 bv[4][2];
; #pragma unroll
;             for (int m = 0; m < 4; ++m)
; #pragma unroll
;                 for (int bj = 0; bj < 2; ++bj) bv[m][bj] = *(const u32x4*)(xb + (size_t)(row0 + ai * HALF + m * 16) * DM + col0 + bj * HALF);
; #pragma unroll
;             for (int m = 0; m < 4; ++m) { const int row = row0 + ai * HALF + m * 16; const size_t ro = (size_t)row * DM + col0; float s = 0.f;
; #pragma unroll
;                 for (int bj = 0; bj < 2; ++bj) { float b8[8]; unpack8(bv[m][bj], b8);
;                     const f32x4 v0 = (f32x4){b8[0], b8[1], b8[2], b8[3]} + acc[ai][bj][m][0], v1 = (f32x4){b8[4], b8[5], b8[6], b8[7]} + acc[ai][bj][m][1];
;                     s += v0[0] * v0[0] + v0[1] * v0[1] + v0[2] * v0[2] + v0[3] * v0[3] + v1[0] * v1[0] + v1[1] * v1[1] + v1[2] * v1[2] + v1[3] * v1[3];
;                     if (LAST) { *(f32x4*)(out + ro + bj * HALF) = v0; *(f32x4*)(out + ro + bj * HALF + 4) = v1; }
;                     else { u32x4 w; w.x = pk2(v0[0], v0[1]); w.y = pk2(v0[2], v0[3]); w.z = pk2(v1[0], v1[1]); w.w = pk2(v1[2], v1[3]); *(u32x4*)(xb + ro + bj * HALF) = w; } }
;                 s += __shfl_xor(s, 16); s += __shfl_xor(s, 32);
;                 if (fq == 0) ss[(size_t)row * 16 + u.pn * 4 + wc] = s; }
.Lep5_skip:
	v_lshl_or_b32 v170, s8, 8, v189
	v_lshl_add_u32 v172, s10, 8, v153
	v_ashrrev_i32_e32 v171, 31, v170
	v_lshlrev_b64 v[204:205], 1, v[170:171]
	v_ashrrev_i32_e32 v173, 31, v172
	v_lshl_add_u64 v[174:175], s[76:77], 0, v[204:205]
	v_lshlrev_b64 v[206:207], 11, v[172:173]
	v_lshl_add_u64 v[128:129], v[174:175], 0, v[206:207]
	global_load_dwordx4 v[196:199], v[128:129], off
	global_load_dwordx4 v[200:203], v[128:129], off offset:256
	v_or_b32_e32 v184, 16, v172
	v_or_b32_e32 v180, 32, v172
	v_or_b32_e32 v176, 48, v172
	v_ashrrev_i32_e32 v185, 31, v184
	v_ashrrev_i32_e32 v181, 31, v180
	v_ashrrev_i32_e32 v177, 31, v176
	v_lshlrev_b64 v[186:187], 11, v[184:185]
	v_lshlrev_b64 v[182:183], 11, v[180:181]
	v_lshlrev_b64 v[178:179], 11, v[176:177]
	v_lshl_add_u64 v[128:129], v[174:175], 0, v[186:187]
	v_lshl_add_u64 v[130:131], v[174:175], 0, v[182:183]
	v_lshl_add_u64 v[194:195], v[174:175], 0, v[178:179]
	global_load_dwordx4 v[148:151], v[128:129], off
	global_load_dwordx4 v[144:147], v[128:129], off offset:256
	global_load_dwordx4 v[140:143], v[130:131], off
	global_load_dwordx4 v[136:139], v[130:131], off offset:256
	global_load_dwordx4 v[132:135], v[194:195], off
	s_nop 0
	global_load_dwordx4 v[128:131], v[194:195], off offset:256
	v_add_u32_e32 v226, 0x80, v172
	v_ashrrev_i32_e32 v227, 31, v226
	v_lshlrev_b64 v[226:227], 11, v[226:227]
	v_lshl_add_u64 v[226:227], v[174:175], 0, v[226:227]
	global_load_dwordx4 v[216:219], v[226:227], off
	global_load_dwordx4 v[220:223], v[226:227], off offset:256
	v_add_u32_e32 v226, 0x90, v172
	v_ashrrev_i32_e32 v227, 31, v226
	v_lshlrev_b64 v[226:227], 11, v[226:227]
	v_lshl_add_u64 v[226:227], v[174:175], 0, v[226:227]
	global_load_dwordx4 v[228:231], v[226:227], off
	global_load_dwordx4 v[232:235], v[226:227], off offset:256
	v_add_u32_e32 v226, 0xa0, v172
	v_ashrrev_i32_e32 v227, 31, v226
	v_lshlrev_b64 v[226:227], 11, v[226:227]
	v_lshl_add_u64 v[226:227], v[174:175], 0, v[226:227]
	global_load_dwordx4 v[236:239], v[226:227], off
	global_load_dwordx4 v[240:243], v[226:227], off offset:256
	v_add_u32_e32 v226, 0xb0, v172
	v_ashrrev_i32_e32 v227, 31, v226
	v_lshlrev_b64 v[226:227], 11, v[226:227]
	v_lshl_add_u64 v[226:227], v[174:175], 0, v[226:227]
	global_load_dwordx4 v[244:247], v[226:227], off
	global_load_dwordx4 v[252:255], v[226:227], off offset:256
	v_and_b32_e32 v195, 64, v193
	v_xor_b32_e32 v194, 16, v193
	v_add_u32_e32 v195, 64, v195
	v_xor_b32_e32 v208, 32, v193
	v_cmp_lt_i32_e32 vcc, v194, v195
	s_waitcnt vmcnt(15)
	v_and_b32_e32 v209, 0xffff0000, v196
	v_cndmask_b32_e32 v194, v193, v194, vcc
	v_cmp_lt_i32_e32 vcc, v208, v195
	v_lshlrev_b32_e32 v195, 2, v194
	s_waitcnt vmcnt(14)
	v_lshlrev_b32_e32 v212, 16, v200
	v_cndmask_b32_e32 v208, v193, v208, vcc
	v_lshlrev_b32_e32 v194, 2, v208
	v_lshlrev_b32_e32 v208, 16, v196
	v_and_b32_e32 v213, 0xffff0000, v200
	v_lshlrev_b32_e32 v210, 16, v198
	v_and_b32_e32 v211, 0xffff0000, v198
	v_lshlrev_b32_e32 v198, 16, v199
	v_and_b32_e32 v199, 0xffff0000, v199
	v_lshlrev_b32_e32 v200, 16, v201
	v_and_b32_e32 v201, 0xffff0000, v201
	v_lshlrev_b32_e32 v214, 16, v202
	v_and_b32_e32 v215, 0xffff0000, v202
	v_pk_add_f32 v[124:125], v[124:125], v[208:209]
	v_pk_add_f32 v[116:117], v[116:117], v[212:213]
	v_lshlrev_b32_e32 v196, 16, v197
	v_and_b32_e32 v197, 0xffff0000, v197
	v_pk_add_f32 v[122:123], v[122:123], v[198:199]
	v_pk_add_f32 v[118:119], v[118:119], v[200:201]
	v_pk_add_f32 v[198:199], v[112:113], v[214:215]
	v_mul_f32_e32 v200, v125, v125
	v_cvt_pk_bf16_f32 v112, v124, v125
	v_mul_f32_e32 v125, v117, v117
	v_pk_add_f32 v[126:127], v[126:127], v[196:197]
	v_fmac_f32_e32 v200, v124, v124
	v_fmac_f32_e32 v125, v116, v116
	v_fmac_f32_e32 v200, v126, v126
	v_fmac_f32_e32 v125, v118, v118
	v_pk_add_f32 v[120:121], v[120:121], v[210:211]
	v_fmac_f32_e32 v200, v127, v127
	v_fmac_f32_e32 v125, v119, v119
	v_lshlrev_b32_e32 v202, 16, v203
	v_and_b32_e32 v203, 0xffff0000, v203
	v_fmac_f32_e32 v200, v120, v120
	v_fmac_f32_e32 v125, v198, v198
	v_pk_add_f32 v[196:197], v[114:115], v[202:203]
	v_fmac_f32_e32 v200, v121, v121
	v_fmac_f32_e32 v125, v199, v199
	v_fmac_f32_e32 v200, v122, v122
	v_fmac_f32_e32 v125, v196, v196
	v_fmac_f32_e32 v200, v123, v123
	v_fmac_f32_e32 v125, v197, v197
	v_cvt_pk_bf16_f32 v115, v122, v123
	v_add_f32_e32 v122, v200, v125
	ds_bpermute_b32 v123, v195, v122
	v_cvt_pk_bf16_f32 v114, v120, v121
	v_lshl_add_u64 v[120:121], s[76:77], 0, v[206:207]
	v_cvt_pk_bf16_f32 v113, v126, v127
	v_lshl_add_u64 v[120:121], v[120:121], 0, v[204:205]
	global_store_dwordx4 v[120:121], v[112:115], off
	s_waitcnt lgkmcnt(0)
	s_nop 0
	v_add_f32_e32 v112, v122, v123
	ds_bpermute_b32 v113, v194, v112
	v_cvt_pk_bf16_f32 v114, v116, v117
	v_cvt_pk_bf16_f32 v115, v118, v119
	v_cvt_pk_bf16_f32 v116, v198, v199
	v_cvt_pk_bf16_f32 v117, v196, v197
	global_store_dwordx4 v[120:121], v[114:117], off offset:256
	s_and_saveexec_b64 s[4:5], s[0:1]
	s_cbranch_execz .LBB0_1121
	s_waitcnt lgkmcnt(0)
	v_add_f32_e32 v114, v112, v113
	s_lshl_b32 s22, s8, 2
	v_lshlrev_b64 v[112:113], 6, v[172:173]
	s_ashr_i32 s23, s22, 31
	v_lshl_add_u64 v[112:113], s[12:13], 0, v[112:113]
	v_lshl_add_u64 v[112:113], s[22:23], 2, v[112:113]
	s_lshl_b32 s10, s35, 2
	v_lshl_add_u64 v[112:113], v[112:113], 0, s[10:11]
	global_store_dword v[112:113], v114, off

; #define PG8_STAGE(bufoff, gbase, voff) do { _Pragma("unroll") for (int _i = 0; _i < 2; ++_i) \
;         __builtin_amdgcn_global_load_lds((const unsigned*)((const char*)(gbase) + (voff)[_i]), (LAS unsigned*)(lds + (bufoff) + ldsw + _i * 8192), 16, 0, 0); } while (0)
; #define PG8_LDA(dst, b, h) do { _Pragma("unroll") for (int m = 0; m < 4; ++m) _Pragma("unroll") for (int k = 0; k < 2; ++k) dst[m][k] = *(const LAS bf16x8*)(lds + PG8_SA(b, h) + aoff + m * 2048 + k * 1024); } while (0)
; #define PG8_LDB(dst, b, h) do { _Pragma("unroll") for (int n = 0; n < 2; ++n) _Pragma("unroll") for (int k = 0; k < 2; ++k) dst[n][k] = *(const LAS bf16x8*)(lds + PG8_SB(b, h) + boff + n * 2048 + k * 1024); } while (0)
; #define PG8_MMA(ai, bj, At, Bt) do { __builtin_amdgcn_s_setprio(1); _Pragma("unroll") for (int m = 0; m < 4; ++m) _Pragma("unroll") for (int n = 0; n < 2; ++n) _Pragma("unroll") for (int k = 0; k < 2; ++k) \
;         acc[ai][bj][m][n] = __builtin_amdgcn_mfma_f32_16x16x32_bf16(Bt[n][k], At[m][k], acc[ai][bj][m][n], 0, 0, 0); __builtin_amdgcn_s_setprio(0); } while (0)
; #define PG8_WAIT_L(n) asm volatile("s_waitcnt lgkmcnt(" #n ")" ::: "memory")
; #define PG8_BAR __builtin_amdgcn_s_barrier()
; #define PG8_SCHED __builtin_amdgcn_sched_barrier(0)
; template <class Epi>
; __device__ __forceinline__ void gemm_phase(LAS unsigned char* lds, const Gemm g, const StaticOrder& S, const Epi& E) {
;     ...
;             PG8_LDB(B0, 0, 0); PG8_SCHED; PG8_LDA(At, 0, 0); PG8_STAGE(PG8_SA(1, 1), a1 + hstepA, voffA);
;             PG8_WAIT_L(8); PG8_BAR; PG8_WAIT_L(0); PG8_MMA(0, 0, At, B0); PG8_BAR; PG8_SCHED;
;             PG8_LDB(B1, 0, 1); PG8_STAGE(PG8_SB(0, 0), b2, voffB);
;             PG8_BAR; PG8_WAIT_L(0); PG8_MMA(0, 1, At, B1); PG8_BAR;
;             PG8_LDA(At, 0, 1); PG8_STAGE(PG8_SA(0, 0), a2, voffA);
;             PG8_BAR; PG8_WAIT_L(0); PG8_MMA(1, 0, At, B0); PG8_BAR; PG8_SCHED;
.LBB0_1204:
	ds_read_b128 v[146:149], v176
	ds_read_b128 v[154:157], v176 offset:1024
	ds_read_b128 v[158:161], v176 offset:2048
	ds_read_b128 v[162:165], v176 offset:3072
	s_add_u32 s22, s20, 0xfffc0080
	s_addc_u32 s23, s21, -1
	s_cmp_eq_u32 s45, 12
	s_cselect_b32 s25, s13, s23
	s_cselect_b32 s24, s41, s22
	s_cselect_b32 s23, s11, s44
	s_cselect_b32 s22, s42, s43
	v_lshl_add_u64 v[150:151], s[20:21], 0, v[138:139]
	s_add_i32 m0, s19, 0xc000
	ds_read_b128 v[166:169], v177
	ds_read_b128 v[170:173], v177 offset:1024
	ds_read_b128 v[180:183], v177 offset:2048
	ds_read_b128 v[184:187], v177 offset:3072
	ds_read_b128 v[188:191], v177 offset:4096
	ds_read_b128 v[192:195], v177 offset:5120
	ds_read_b128 v[196:199], v177 offset:6144
	ds_read_b128 v[200:203], v177 offset:7168
	global_load_lds_dwordx4 v[150:151], off
	v_lshl_add_u64 v[150:151], s[20:21], 0, v[140:141]
	s_add_i32 m0, s19, 0xe000
	s_nop 0
	global_load_lds_dwordx4 v[150:151], off
	s_waitcnt lgkmcnt(8)
	s_barrier
	s_waitcnt lgkmcnt(0)
	v_mfma_f32_16x16x32_bf16 v[124:127], v[146:149], v[166:169], v[124:127]
	v_mfma_f32_16x16x32_bf16 v[120:123], v[158:161], v[166:169], v[120:123]
	v_mfma_f32_16x16x32_bf16 v[108:111], v[146:149], v[180:183], v[108:111]
	v_mfma_f32_16x16x32_bf16 v[104:107], v[158:161], v[180:183], v[104:107]
	v_mfma_f32_16x16x32_bf16 v[92:95], v[146:149], v[188:191], v[92:95]
	v_mfma_f32_16x16x32_bf16 v[88:91], v[158:161], v[188:191], v[88:91]
	v_mfma_f32_16x16x32_bf16 v[76:79], v[146:149], v[196:199], v[76:79]
	v_mfma_f32_16x16x32_bf16 v[72:75], v[158:161], v[196:199], v[72:75]
	v_mfma_f32_16x16x32_bf16 v[124:127], v[154:157], v[170:173], v[124:127]
	v_mfma_f32_16x16x32_bf16 v[120:123], v[162:165], v[170:173], v[120:123]
	v_mfma_f32_16x16x32_bf16 v[108:111], v[154:157], v[184:187], v[108:111]
	v_mfma_f32_16x16x32_bf16 v[104:107], v[162:165], v[184:187], v[104:107]
	v_mfma_f32_16x16x32_bf16 v[92:95], v[154:157], v[192:195], v[92:95]
	v_mfma_f32_16x16x32_bf16 v[88:91], v[162:165], v[192:195], v[88:91]
	v_mfma_f32_16x16x32_bf16 v[76:79], v[154:157], v[200:203], v[76:79]
	v_mfma_f32_16x16x32_bf16 v[72:75], v[162:165], v[200:203], v[72:75]
	s_barrier
	s_add_i32 s46, s37, s28
	v_lshl_add_u64 v[150:151], s[22:23], 0, v[130:131]
	s_mov_b32 m0, s46
	ds_read_b128 v[204:207], v178
	ds_read_b128 v[208:211], v178 offset:1024
	ds_read_b128 v[212:215], v178 offset:2048
	ds_read_b128 v[216:219], v178 offset:3072
	global_load_lds_dwordx4 v[150:151], off
	v_lshl_add_u64 v[220:221], s[22:23], 0, v[134:135]
	s_add_i32 m0, s46, 0x2000
	s_nop 0
	global_load_lds_dwordx4 v[220:221], off
	s_barrier
	s_waitcnt lgkmcnt(0)
	v_mfma_f32_16x16x32_bf16 v[116:119], v[204:207], v[166:169], v[116:119]
	v_mfma_f32_16x16x32_bf16 v[112:115], v[212:215], v[166:169], v[112:115]
	v_mfma_f32_16x16x32_bf16 v[100:103], v[204:207], v[180:183], v[100:103]
	v_mfma_f32_16x16x32_bf16 v[96:99], v[212:215], v[180:183], v[96:99]
	v_mfma_f32_16x16x32_bf16 v[84:87], v[204:207], v[188:191], v[84:87]
	v_mfma_f32_16x16x32_bf16 v[80:83], v[212:215], v[188:191], v[80:83]
	v_mfma_f32_16x16x32_bf16 v[68:71], v[204:207], v[196:199], v[68:71]
	v_mfma_f32_16x16x32_bf16 v[64:67], v[212:215], v[196:199], v[64:67]
	v_mfma_f32_16x16x32_bf16 v[116:119], v[208:211], v[170:173], v[116:119]
	v_mfma_f32_16x16x32_bf16 v[112:115], v[216:219], v[170:173], v[112:115]
	v_mfma_f32_16x16x32_bf16 v[100:103], v[208:211], v[184:187], v[100:103]
	v_mfma_f32_16x16x32_bf16 v[96:99], v[216:219], v[184:187], v[96:99]
	v_mfma_f32_16x16x32_bf16 v[84:87], v[208:211], v[192:195], v[84:87]
	v_mfma_f32_16x16x32_bf16 v[80:83], v[216:219], v[192:195], v[80:83]
	v_mfma_f32_16x16x32_bf16 v[68:71], v[208:211], v[200:203], v[68:71]
	v_mfma_f32_16x16x32_bf16 v[64:67], v[216:219], v[200:203], v[64:67]
	s_mov_b32 m0, s19
	v_lshl_add_u64 v[222:223], s[24:25], 0, v[128:129]
	s_barrier
	ds_read_b128 v[166:169], v177 offset:16384
	ds_read_b128 v[170:173], v177 offset:17408
	ds_read_b128 v[180:183], v177 offset:18432
	ds_read_b128 v[184:187], v177 offset:19456
	ds_read_b128 v[188:191], v177 offset:20480
	ds_read_b128 v[192:195], v177 offset:21504
	ds_read_b128 v[196:199], v177 offset:22528
	ds_read_b128 v[200:203], v177 offset:23552
	global_load_lds_dwordx4 v[222:223], off
	v_lshl_add_u64 v[224:225], s[24:25], 0, v[132:133]
	s_mov_b32 m0, s29
	s_nop 0
	global_load_lds_dwordx4 v[224:225], off
	s_barrier
	s_waitcnt lgkmcnt(0)
	v_mfma_f32_16x16x32_bf16 v[60:63], v[146:149], v[166:169], v[60:63]
	v_mfma_f32_16x16x32_bf16 v[56:59], v[158:161], v[166:169], v[56:59]
	v_mfma_f32_16x16x32_bf16 v[44:47], v[146:149], v[180:183], v[44:47]
	v_mfma_f32_16x16x32_bf16 v[40:43], v[158:161], v[180:183], v[40:43]
	v_mfma_f32_16x16x32_bf16 v[28:31], v[146:149], v[188:191], v[28:31]
	v_mfma_f32_16x16x32_bf16 v[24:27], v[158:161], v[188:191], v[24:27]
	v_mfma_f32_16x16x32_bf16 v[12:15], v[146:149], v[196:199], v[12:15]
	v_mfma_f32_16x16x32_bf16 v[8:11], v[158:161], v[196:199], v[8:11]
	v_mfma_f32_16x16x32_bf16 v[60:63], v[154:157], v[170:173], v[60:63]
	v_mfma_f32_16x16x32_bf16 v[56:59], v[162:165], v[170:173], v[56:59]
	v_mfma_f32_16x16x32_bf16 v[44:47], v[154:157], v[184:187], v[44:47]
	v_mfma_f32_16x16x32_bf16 v[40:43], v[162:165], v[184:187], v[40:43]
	v_mfma_f32_16x16x32_bf16 v[28:31], v[154:157], v[192:195], v[28:31]
	v_mfma_f32_16x16x32_bf16 v[24:27], v[162:165], v[192:195], v[24:27]
	v_mfma_f32_16x16x32_bf16 v[12:15], v[154:157], v[200:203], v[12:15]
	v_mfma_f32_16x16x32_bf16 v[8:11], v[162:165], v[200:203], v[8:11]
	s_barrier
; #define PG8_STAGE(bufoff, gbase, voff) do { _Pragma("unroll") for (int _i = 0; _i < 2; ++_i) \
;         __builtin_amdgcn_global_load_lds((const unsigned*)((const char*)(gbase) + (voff)[_i]), (LAS unsigned*)(lds + (bufoff) + ldsw + _i * 8192), 16, 0, 0); } while (0)
; #define PG8_LDA(dst, b, h) do { _Pragma("unroll") for (int m = 0; m < 4; ++m) _Pragma("unroll") for (int k = 0; k < 2; ++k) dst[m][k] = *(const LAS bf16x8*)(lds + PG8_SA(b, h) + aoff + m * 2048 + k * 1024); } while (0)
; #define PG8_LDB(dst, b, h) do { _Pragma("unroll") for (int n = 0; n < 2; ++n) _Pragma("unroll") for (int k = 0; k < 2; ++k) dst[n][k] = *(const LAS bf16x8*)(lds + PG8_SB(b, h) + boff + n * 2048 + k * 1024); } while (0)
; #define PG8_MMA(ai, bj, At, Bt) do { __builtin_amdgcn_s_setprio(1); _Pragma("unroll") for (int m = 0; m < 4; ++m) _Pragma("unroll") for (int n = 0; n < 2; ++n) _Pragma("unroll") for (int k = 0; k < 2; ++k) \
;         acc[ai][bj][m][n] = __builtin_amdgcn_mfma_f32_16x16x32_bf16(Bt[n][k], At[m][k], acc[ai][bj][m][n], 0, 0, 0); __builtin_amdgcn_s_setprio(0); } while (0)
; #define PG8_WAIT_V(n) asm volatile("s_waitcnt vmcnt(" #n ")" ::: "memory")
; #define PG8_WAIT_L(n) asm volatile("s_waitcnt lgkmcnt(" #n ")" ::: "memory")
; #define PG8_BAR __builtin_amdgcn_s_barrier()
; #define PG8_SCHED __builtin_amdgcn_sched_barrier(0)
; template <class Epi>
; __device__ __forceinline__ void gemm_phase(LAS unsigned char* lds, const Gemm g, const StaticOrder& S, const Epi& E) {
;     ...
;             PG8_STAGE(PG8_SB(0, 1), b2 + hstepB, voffB);
;             PG8_WAIT_V(6); PG8_BAR; PG8_MMA(1, 1, At, B1); PG8_BAR;
;             PG8_LDB(B0, 1, 0); PG8_SCHED; PG8_LDA(At, 1, 0); PG8_STAGE(PG8_SA(0, 1), a2 + hstepA, voffA);
;             PG8_WAIT_L(8); PG8_BAR; PG8_WAIT_L(0); PG8_MMA(0, 0, At, B0); PG8_BAR; PG8_SCHED;
;             PG8_LDB(B1, 1, 1); PG8_STAGE(PG8_SB(1, 0), b3, voffB);
;             PG8_BAR; PG8_WAIT_L(0); PG8_MMA(0, 1, At, B1); PG8_BAR;
;             PG8_LDA(At, 1, 1); PG8_STAGE(PG8_SA(1, 0), a3, voffA);
;             PG8_BAR; PG8_WAIT_L(0); PG8_MMA(1, 0, At, B0); PG8_BAR; PG8_SCHED;
	s_add_u32 s46, s22, 0x40000
	s_addc_u32 s47, s23, 0
	s_add_i32 s48, s38, s28
	v_lshl_add_u64 v[146:147], s[46:47], 0, v[130:131]
	s_mov_b32 m0, s48
	s_nop 0
	global_load_lds_dwordx4 v[146:147], off
	v_lshl_add_u64 v[146:147], s[46:47], 0, v[134:135]
	s_add_i32 m0, s48, 0x2000
	s_nop 0
	global_load_lds_dwordx4 v[146:147], off
	s_waitcnt vmcnt(6)
	s_barrier
	v_mfma_f32_16x16x32_bf16 v[52:55], v[204:207], v[166:169], v[52:55]
	v_mfma_f32_16x16x32_bf16 v[48:51], v[212:215], v[166:169], v[48:51]
	v_mfma_f32_16x16x32_bf16 v[36:39], v[204:207], v[180:183], v[36:39]
	v_mfma_f32_16x16x32_bf16 v[32:35], v[212:215], v[180:183], v[32:35]
	v_mfma_f32_16x16x32_bf16 v[20:23], v[204:207], v[188:191], v[20:23]
	v_mfma_f32_16x16x32_bf16 v[16:19], v[212:215], v[188:191], v[16:19]
	v_mfma_f32_16x16x32_bf16 v[4:7], v[204:207], v[196:199], v[4:7]
	v_mfma_f32_16x16x32_bf16 v[0:3], v[212:215], v[196:199], v[0:3]
	v_mfma_f32_16x16x32_bf16 v[52:55], v[208:211], v[170:173], v[52:55]
	v_mfma_f32_16x16x32_bf16 v[48:51], v[216:219], v[170:173], v[48:51]
	v_mfma_f32_16x16x32_bf16 v[36:39], v[208:211], v[184:187], v[36:39]
	v_mfma_f32_16x16x32_bf16 v[32:35], v[216:219], v[184:187], v[32:35]
	v_mfma_f32_16x16x32_bf16 v[20:23], v[208:211], v[192:195], v[20:23]
	v_mfma_f32_16x16x32_bf16 v[16:19], v[216:219], v[192:195], v[16:19]
	v_mfma_f32_16x16x32_bf16 v[4:7], v[208:211], v[200:203], v[4:7]
	v_mfma_f32_16x16x32_bf16 v[0:3], v[216:219], v[200:203], v[0:3]
	s_add_i32 s46, 0, 0x18000
	v_add_u32_e32 v162, s46, v174
	s_barrier
	ds_read_b128 v[146:149], v162
	ds_read_b128 v[154:157], v162 offset:1024
	ds_read_b128 v[158:161], v162 offset:2048
	ds_read_b128 v[162:165], v162 offset:3072
	s_add_u32 s24, s24, 0x40000
	s_addc_u32 s25, s25, 0
	s_mov_b32 m0, s30
	v_lshl_add_u64 v[204:205], s[24:25], 0, v[128:129]
	ds_read_b128 v[166:169], v177 offset:32768
	ds_read_b128 v[170:173], v177 offset:33792
	ds_read_b128 v[180:183], v177 offset:34816
	ds_read_b128 v[184:187], v177 offset:35840
	ds_read_b128 v[188:191], v177 offset:36864
	ds_read_b128 v[192:195], v177 offset:37888
	ds_read_b128 v[196:199], v177 offset:38912
	ds_read_b128 v[200:203], v177 offset:39936
	global_load_lds_dwordx4 v[204:205], off
	v_lshl_add_u64 v[204:205], s[24:25], 0, v[132:133]
	s_mov_b32 m0, s31
	s_nop 0
	global_load_lds_dwordx4 v[204:205], off
	s_waitcnt lgkmcnt(8)
	s_barrier
	s_waitcnt lgkmcnt(0)
	v_mfma_f32_16x16x32_bf16 v[124:127], v[146:149], v[166:169], v[124:127]
	v_mfma_f32_16x16x32_bf16 v[120:123], v[158:161], v[166:169], v[120:123]
	v_mfma_f32_16x16x32_bf16 v[108:111], v[146:149], v[180:183], v[108:111]
	v_mfma_f32_16x16x32_bf16 v[104:107], v[158:161], v[180:183], v[104:107]
	v_mfma_f32_16x16x32_bf16 v[92:95], v[146:149], v[188:191], v[92:95]
	v_mfma_f32_16x16x32_bf16 v[88:91], v[158:161], v[188:191], v[88:91]
	v_mfma_f32_16x16x32_bf16 v[76:79], v[146:149], v[196:199], v[76:79]
	v_mfma_f32_16x16x32_bf16 v[72:75], v[158:161], v[196:199], v[72:75]
	v_mfma_f32_16x16x32_bf16 v[124:127], v[154:157], v[170:173], v[124:127]
	v_mfma_f32_16x16x32_bf16 v[120:123], v[162:165], v[170:173], v[120:123]
	v_mfma_f32_16x16x32_bf16 v[108:111], v[154:157], v[184:187], v[108:111]
	v_mfma_f32_16x16x32_bf16 v[104:107], v[162:165], v[184:187], v[104:107]
	v_mfma_f32_16x16x32_bf16 v[92:95], v[154:157], v[192:195], v[92:95]
	v_mfma_f32_16x16x32_bf16 v[88:91], v[162:165], v[192:195], v[88:91]
	v_mfma_f32_16x16x32_bf16 v[76:79], v[154:157], v[200:203], v[76:79]
	v_mfma_f32_16x16x32_bf16 v[72:75], v[162:165], v[200:203], v[72:75]
	s_barrier
	s_add_i32 s24, 0, 0x1c000
	s_add_i32 s25, s46, s28
	v_add_u32_e32 v216, s24, v174
	v_lshl_add_u64 v[150:151], v[150:151], 0, s[4:5]
	s_mov_b32 m0, s25
	ds_read_b128 v[204:207], v216
	ds_read_b128 v[208:211], v216 offset:1024
	ds_read_b128 v[212:215], v216 offset:2048
	ds_read_b128 v[216:219], v216 offset:3072
	global_load_lds_dwordx4 v[150:151], off
	v_lshl_add_u64 v[150:151], v[220:221], 0, s[4:5]
	s_add_i32 m0, s25, 0x2000
	s_nop 0
	global_load_lds_dwordx4 v[150:151], off
	s_barrier
	s_waitcnt lgkmcnt(0)
	v_mfma_f32_16x16x32_bf16 v[116:119], v[204:207], v[166:169], v[116:119]
	v_mfma_f32_16x16x32_bf16 v[112:115], v[212:215], v[166:169], v[112:115]
	v_mfma_f32_16x16x32_bf16 v[100:103], v[204:207], v[180:183], v[100:103]
	v_mfma_f32_16x16x32_bf16 v[96:99], v[212:215], v[180:183], v[96:99]
	v_mfma_f32_16x16x32_bf16 v[84:87], v[204:207], v[188:191], v[84:87]
	v_mfma_f32_16x16x32_bf16 v[80:83], v[212:215], v[188:191], v[80:83]
	v_mfma_f32_16x16x32_bf16 v[68:71], v[204:207], v[196:199], v[68:71]
	v_mfma_f32_16x16x32_bf16 v[64:67], v[212:215], v[196:199], v[64:67]
	v_mfma_f32_16x16x32_bf16 v[116:119], v[208:211], v[170:173], v[116:119]
	v_mfma_f32_16x16x32_bf16 v[112:115], v[216:219], v[170:173], v[112:115]
	v_mfma_f32_16x16x32_bf16 v[100:103], v[208:211], v[184:187], v[100:103]
	v_mfma_f32_16x16x32_bf16 v[96:99], v[216:219], v[184:187], v[96:99]
	v_mfma_f32_16x16x32_bf16 v[84:87], v[208:211], v[192:195], v[84:87]
	v_mfma_f32_16x16x32_bf16 v[80:83], v[216:219], v[192:195], v[80:83]
	v_mfma_f32_16x16x32_bf16 v[68:71], v[208:211], v[200:203], v[68:71]
	v_mfma_f32_16x16x32_bf16 v[64:67], v[216:219], v[200:203], v[64:67]
	s_mov_b32 m0, s34
	v_lshl_add_u64 v[150:151], v[222:223], 0, s[4:5]
	s_barrier
	ds_read_b128 v[166:169], v177 offset:49152
	ds_read_b128 v[170:173], v177 offset:50176
	ds_read_b128 v[180:183], v177 offset:51200
	ds_read_b128 v[184:187], v177 offset:52224
	ds_read_b128 v[188:191], v177 offset:53248
	ds_read_b128 v[192:195], v177 offset:54272
	ds_read_b128 v[196:199], v177 offset:55296
	ds_read_b128 v[200:203], v177 offset:56320
	global_load_lds_dwordx4 v[150:151], off
	v_lshl_add_u64 v[150:151], v[224:225], 0, s[4:5]
	s_mov_b32 m0, s35
	s_nop 0
	global_load_lds_dwordx4 v[150:151], off
	s_barrier
; #define PG8_STAGE(bufoff, gbase, voff) do { _Pragma("unroll") for (int _i = 0; _i < 2; ++_i) \
;         __builtin_amdgcn_global_load_lds((const unsigned*)((const char*)(gbase) + (voff)[_i]), (LAS unsigned*)(lds + (bufoff) + ldsw + _i * 8192), 16, 0, 0); } while (0)
; #define PG8_MMA(ai, bj, At, Bt) do { __builtin_amdgcn_s_setprio(1); _Pragma("unroll") for (int m = 0; m < 4; ++m) _Pragma("unroll") for (int n = 0; n < 2; ++n) _Pragma("unroll") for (int k = 0; k < 2; ++k) \
;         acc[ai][bj][m][n] = __builtin_amdgcn_mfma_f32_16x16x32_bf16(Bt[n][k], At[m][k], acc[ai][bj][m][n], 0, 0, 0); __builtin_amdgcn_s_setprio(0); } while (0)
; #define PG8_WAIT_V(n) asm volatile("s_waitcnt vmcnt(" #n ")" ::: "memory")
; #define PG8_WAIT_L(n) asm volatile("s_waitcnt lgkmcnt(" #n ")" ::: "memory")
; #define PG8_BAR __builtin_amdgcn_s_barrier()
; #define PG8_SCHED __builtin_amdgcn_sched_barrier(0)
;     __device__ __forceinline__ void operator()(const f32x4 (&acc)[2][2][4][2], const Unit& u, int wr, int wc, int fr, int fq, const float (&)[8]) const {
;     ...
;         const int col0 = u.pn * BM + wc * 32 + 8 * fq;
; #pragma unroll
;         for (int ai = 0; ai < 2; ++ai)
; #pragma unroll
;             for (int m = 0; m < 4; ++m) { const int row = row0 + ai * HALF + m * 16; const float rs = rsqrtf(ep[ai * 4 + m] * (1.0f / 1024.0f) + EPS);
;                 u16* rowp = O + (size_t)row * ldc + col0;
; #pragma unroll
;                 for (int bj = 0; bj < 2; ++bj) { f32x4 v0 = acc[ai][bj][m][0] * rs, v1 = acc[ai][bj][m][1] * rs;
;                     if (ACT == 1) {
; #pragma unroll
;                         for (int j = 0; j < 4; ++j) { const float a0 = fmaxf(v0[j], 0.f), a1 = fmaxf(v1[j], 0.f); v0[j] = a0 * a0; v1[j] = a1 * a1; } }
; template <class Epi>
; __device__ __forceinline__ void gemm_phase(LAS unsigned char* lds, const Gemm g, const StaticOrder& S, const Epi& E) {
;     ...
;             PG8_BAR; PG8_WAIT_L(0); PG8_MMA(1, 0, At, B0); PG8_BAR; PG8_SCHED;
;             PG8_STAGE(PG8_SB(1, 1), b3 + hstepB, voffB);
;             PG8_WAIT_V(6); PG8_BAR; PG8_MMA(1, 1, At, B1); PG8_BAR;
;         }
;         E(acc, cur, wr, wc, fr, fq, epre);
	s_waitcnt lgkmcnt(0)
	v_mfma_f32_16x16x32_bf16 v[60:63], v[146:149], v[166:169], v[60:63]
	v_mfma_f32_16x16x32_bf16 v[56:59], v[158:161], v[166:169], v[56:59]
	v_mfma_f32_16x16x32_bf16 v[44:47], v[146:149], v[180:183], v[44:47]
	v_mfma_f32_16x16x32_bf16 v[40:43], v[158:161], v[180:183], v[40:43]
	v_mfma_f32_16x16x32_bf16 v[28:31], v[146:149], v[188:191], v[28:31]
	v_mfma_f32_16x16x32_bf16 v[24:27], v[158:161], v[188:191], v[24:27]
	v_mfma_f32_16x16x32_bf16 v[12:15], v[146:149], v[196:199], v[12:15]
	v_mfma_f32_16x16x32_bf16 v[8:11], v[158:161], v[196:199], v[8:11]
	v_mfma_f32_16x16x32_bf16 v[60:63], v[154:157], v[170:173], v[60:63]
	v_mfma_f32_16x16x32_bf16 v[56:59], v[162:165], v[170:173], v[56:59]
	v_mfma_f32_16x16x32_bf16 v[44:47], v[154:157], v[184:187], v[44:47]
	v_mfma_f32_16x16x32_bf16 v[40:43], v[162:165], v[184:187], v[40:43]
	v_mfma_f32_16x16x32_bf16 v[28:31], v[154:157], v[192:195], v[28:31]
	v_mfma_f32_16x16x32_bf16 v[24:27], v[162:165], v[192:195], v[24:27]
	v_mfma_f32_16x16x32_bf16 v[12:15], v[154:157], v[200:203], v[12:15]
	v_mfma_f32_16x16x32_bf16 v[8:11], v[162:165], v[200:203], v[8:11]
	s_barrier
	s_add_u32 s22, s22, 0x40080
	s_addc_u32 s23, s23, 0
	s_add_i32 s24, s24, s28
	v_lshl_add_u64 v[146:147], s[22:23], 0, v[130:131]
	s_mov_b32 m0, s24
	s_nop 0
	global_load_lds_dwordx4 v[146:147], off
	v_lshl_add_u64 v[146:147], s[22:23], 0, v[134:135]
	s_add_i32 m0, s24, 0x2000
	s_nop 0
	global_load_lds_dwordx4 v[146:147], off
	s_waitcnt vmcnt(6)
	s_barrier
	v_mfma_f32_16x16x32_bf16 v[52:55], v[204:207], v[166:169], v[52:55]
	v_mfma_f32_16x16x32_bf16 v[48:51], v[212:215], v[166:169], v[48:51]
	v_mfma_f32_16x16x32_bf16 v[36:39], v[204:207], v[180:183], v[36:39]
	v_mfma_f32_16x16x32_bf16 v[32:35], v[212:215], v[180:183], v[32:35]
	v_mfma_f32_16x16x32_bf16 v[20:23], v[204:207], v[188:191], v[20:23]
	v_mfma_f32_16x16x32_bf16 v[16:19], v[212:215], v[188:191], v[16:19]
	v_mfma_f32_16x16x32_bf16 v[4:7], v[204:207], v[196:199], v[4:7]
	v_mfma_f32_16x16x32_bf16 v[0:3], v[212:215], v[196:199], v[0:3]
	v_mfma_f32_16x16x32_bf16 v[52:55], v[208:211], v[170:173], v[52:55]
	v_mfma_f32_16x16x32_bf16 v[48:51], v[216:219], v[170:173], v[48:51]
	v_mfma_f32_16x16x32_bf16 v[36:39], v[208:211], v[184:187], v[36:39]
	v_mfma_f32_16x16x32_bf16 v[32:35], v[216:219], v[184:187], v[32:35]
	v_mfma_f32_16x16x32_bf16 v[20:23], v[208:211], v[192:195], v[20:23]
	v_mfma_f32_16x16x32_bf16 v[16:19], v[216:219], v[192:195], v[16:19]
	v_mfma_f32_16x16x32_bf16 v[4:7], v[208:211], v[200:203], v[4:7]
	v_mfma_f32_16x16x32_bf16 v[0:3], v[216:219], v[200:203], v[0:3]
	s_add_i32 s45, s45, 2
	s_add_u32 s20, s20, 0x100
	s_addc_u32 s21, s21, 0
	s_add_u32 s43, s43, 0x100
	s_addc_u32 s44, s44, 0
	s_cmp_gt_u32 s45, 13
	s_barrier
	s_cbranch_scc0 .LBB0_1204
	s_setprio 0
	s_cmp_ge_u32 s98, 0x100
	s_cbranch_scc0 .Lep6_skip
	s_setprio 1
.Lep6_skip:
	s_bfe_u32 vcc_lo, s18, 0x20003
	s_lshl_b32 vcc_lo, vcc_lo, 10
	s_add_i32 vcc_lo, vcc_lo, 0x20010
	v_lshl_add_u32 v236, v153, 2, vcc_lo
	ds_read_b32 v228, v236
	ds_read_b32 v229, v236 offset:64
	ds_read_b32 v230, v236 offset:128
	ds_read_b32 v231, v236 offset:192
	ds_read_b32 v232, v236 offset:512
	ds_read_b32 v233, v236 offset:576
	ds_read_b32 v234, v236 offset:640
	ds_read_b32 v235, v236 offset:704
	s_waitcnt lgkmcnt(0)
	v_lshl_add_u32 v148, s18, 8, v153
	v_ashrrev_i32_e32 v149, 31, v148
	v_or_b32_e32 v172, 16, v148
	v_ashrrev_i32_e32 v173, 31, v172
	v_or_b32_e32 v168, 32, v148
	v_or_b32_e32 v164, 48, v148
	v_ashrrev_i32_e32 v169, 31, v168
	v_ashrrev_i32_e32 v165, 31, v164
	v_add_u32_e32 v162, 0x80, v148
	v_add_u32_e32 v156, 0x90, v148
	v_ashrrev_i32_e32 v163, 31, v162
	v_ashrrev_i32_e32 v157, 31, v156
	v_add_u32_e32 v150, 0xa0, v148
	v_ashrrev_i32_e32 v151, 31, v150
	v_add_u32_e32 v146, 0xb0, v148
	v_ashrrev_i32_e32 v147, 31, v146
	v_lshl_or_b32 v166, s40, 8, v175
	v_ashrrev_i32_e32 v167, 31, v166
	v_lshlrev_b64 v[170:171], 13, v[148:149]
	v_lshlrev_b64 v[148:149], 1, v[166:167]
	v_lshl_add_u64 v[166:167], s[96:97], 0, v[170:171]
	v_lshl_add_u64 v[210:211], v[166:167], 0, v[148:149]
	s_mov_b32 s40, s10
	s_mov_b32 s18, s12
	s_mov_b64 s[22:23], s[16:17]
	s_mov_b64 s[20:21], s[14:15]
	s_waitcnt vmcnt(8)
	s_waitcnt lgkmcnt(0)
	s_waitcnt lgkmcnt(0)
	v_mov_b32_e32 v182, v228
	v_pk_mul_f32 v[120:121], v[120:121], v[182:183] op_sel_hi:[1,0]
	v_pk_mul_f32 v[126:127], v[126:127], v[182:183] op_sel_hi:[1,0]
	v_pk_mul_f32 v[124:125], v[124:125], v[182:183] op_sel_hi:[1,0]
	v_pk_mul_f32 v[122:123], v[122:123], v[182:183] op_sel_hi:[1,0]
	v_max_f32_e32 v120, 0, v120
	v_max_f32_e32 v121, 0, v121
	v_max_f32_e32 v124, 0, v124
	v_max_f32_e32 v125, 0, v125
	v_pk_mul_f32 v[188:189], v[120:121], v[120:121]
	v_max_f32_e32 v120, 0, v126
	v_max_f32_e32 v122, 0, v122
	v_max_f32_e32 v121, 0, v127
	v_max_f32_e32 v123, 0, v123
	v_pk_mul_f32 v[124:125], v[124:125], v[124:125]
	v_pk_mul_f32 v[126:127], v[120:121], v[120:121]
	v_pk_mul_f32 v[192:193], v[122:123], v[122:123]
	v_pk_mul_f32 v[114:115], v[114:115], v[182:183] op_sel_hi:[1,0]
	v_cvt_pk_bf16_f32 v120, v124, v125
	v_cvt_pk_bf16_f32 v121, v126, v127
	v_cvt_pk_bf16_f32 v122, v188, v189
	v_cvt_pk_bf16_f32 v123, v192, v193
	v_pk_mul_f32 v[116:117], v[116:117], v[182:183] op_sel_hi:[1,0]
	v_pk_mul_f32 v[112:113], v[112:113], v[182:183] op_sel_hi:[1,0]
	v_max_f32_e32 v114, 0, v114
	v_max_f32_e32 v115, 0, v115
	global_store_dwordx4 v[210:211], v[120:123], off
	v_pk_mul_f32 v[118:119], v[118:119], v[182:183] op_sel_hi:[1,0]
	v_max_f32_e32 v116, 0, v116
	v_max_f32_e32 v112, 0, v112
	v_max_f32_e32 v117, 0, v117
	v_max_f32_e32 v113, 0, v113
	v_pk_mul_f32 v[122:123], v[114:115], v[114:115]
	v_pk_mul_f32 v[116:117], v[116:117], v[116:117]
; __device__ __forceinline__ unsigned pk2(float lo, float hi) { const f32x2 v = (f32x2){lo, hi}; const bf16x2_t b = __builtin_convertvector(v, bf16x2_t); return __builtin_bit_cast(unsigned, b); }
;     __device__ __forceinline__ void operator()(const f32x4 (&acc)[2][2][4][2], const Unit& u, int wr, int wc, int fr, int fq, const float (&)[8]) const {
;     ...
;             for (int m = 0; m < 4; ++m) { const int row = row0 + ai * HALF + m * 16; const float rs = rsqrtf(ep[ai * 4 + m] * (1.0f / 1024.0f) + EPS);
;                 u16* rowp = O + (size_t)row * ldc + col0;
; #pragma unroll
;                 for (int bj = 0; bj < 2; ++bj) { f32x4 v0 = acc[ai][bj][m][0] * rs, v1 = acc[ai][bj][m][1] * rs;
;                     if (ACT == 1) {
; #pragma unroll
;                         for (int j = 0; j < 4; ++j) { const float a0 = fmaxf(v0[j], 0.f), a1 = fmaxf(v1[j], 0.f); v0[j] = a0 * a0; v1[j] = a1 * a1; } }
;                     u32x4 w; w.x = pk2(v0[0], v0[1]); w.y = pk2(v0[2], v0[3]); w.z = pk2(v1[0], v1[1]); w.w = pk2(v1[2], v1[3]);
;                     *(u32x4*)(rowp + bj * HALF) = w; } }
	v_pk_mul_f32 v[120:121], v[112:113], v[112:113]
	v_max_f32_e32 v112, 0, v118
	v_max_f32_e32 v113, 0, v119
	v_pk_mul_f32 v[118:119], v[112:113], v[112:113]
	v_cvt_pk_bf16_f32 v112, v116, v117
	v_cvt_pk_bf16_f32 v113, v118, v119
	v_cvt_pk_bf16_f32 v114, v120, v121
	v_cvt_pk_bf16_f32 v115, v122, v123
	global_store_dwordx4 v[210:211], v[112:115], off offset:256
	s_nop 1
	v_mov_b32_e32 v112, v229
	v_pk_mul_f32 v[104:105], v[104:105], v[112:113] op_sel_hi:[1,0]
	v_pk_mul_f32 v[110:111], v[110:111], v[112:113] op_sel_hi:[1,0]
	v_pk_mul_f32 v[108:109], v[108:109], v[112:113] op_sel_hi:[1,0]
	v_pk_mul_f32 v[106:107], v[106:107], v[112:113] op_sel_hi:[1,0]
	v_max_f32_e32 v104, 0, v104
	v_max_f32_e32 v105, 0, v105
	v_lshlrev_b64 v[114:115], 13, v[172:173]
	v_max_f32_e32 v108, 0, v108
	v_max_f32_e32 v109, 0, v109
	v_pk_mul_f32 v[116:117], v[104:105], v[104:105]
	v_max_f32_e32 v104, 0, v110
	v_max_f32_e32 v106, 0, v106
	v_max_f32_e32 v105, 0, v111
	v_max_f32_e32 v107, 0, v107
	v_lshl_add_u64 v[114:115], s[96:97], 0, v[114:115]
	v_pk_mul_f32 v[108:109], v[108:109], v[108:109]
	v_pk_mul_f32 v[110:111], v[104:105], v[104:105]
	v_pk_mul_f32 v[118:119], v[106:107], v[106:107]
	v_pk_mul_f32 v[96:97], v[96:97], v[112:113] op_sel_hi:[1,0]
	v_lshl_add_u64 v[114:115], v[114:115], 0, v[148:149]
	v_cvt_pk_bf16_f32 v104, v108, v109
	v_cvt_pk_bf16_f32 v105, v110, v111
	v_cvt_pk_bf16_f32 v106, v116, v117
	v_cvt_pk_bf16_f32 v107, v118, v119
	v_pk_mul_f32 v[102:103], v[102:103], v[112:113] op_sel_hi:[1,0]
	v_max_f32_e32 v96, 0, v96
	v_max_f32_e32 v97, 0, v97
	global_store_dwordx4 v[114:115], v[104:107], off
	v_pk_mul_f32 v[100:101], v[100:101], v[112:113] op_sel_hi:[1,0]
	v_pk_mul_f32 v[98:99], v[98:99], v[112:113] op_sel_hi:[1,0]
	v_pk_mul_f32 v[104:105], v[96:97], v[96:97]
	v_max_f32_e32 v96, 0, v102
	v_max_f32_e32 v97, 0, v103
	v_max_f32_e32 v100, 0, v100
	v_max_f32_e32 v101, 0, v101
	v_pk_mul_f32 v[100:101], v[100:101], v[100:101]
	v_pk_mul_f32 v[108:109], v[96:97], v[96:97]
	v_cvt_pk_bf16_f32 v96, v100, v101
	s_waitcnt lgkmcnt(0)
	v_max_f32_e32 v98, 0, v98
	v_max_f32_e32 v99, 0, v99
	v_pk_mul_f32 v[110:111], v[98:99], v[98:99]
	v_cvt_pk_bf16_f32 v97, v108, v109
	v_cvt_pk_bf16_f32 v98, v104, v105
	v_cvt_pk_bf16_f32 v99, v110, v111
	global_store_dwordx4 v[114:115], v[96:99], off offset:256
	s_waitcnt lgkmcnt(0)
	s_nop 0
	s_nop 0
	s_nop 0
	s_nop 1
	v_lshlrev_b64 v[98:99], 13, v[168:169]
	v_lshl_add_u64 v[98:99], s[96:97], 0, v[98:99]
	v_lshl_add_u64 v[98:99], v[98:99], 0, v[148:149]
	v_mov_b32_e32 v100, v230
	v_pk_mul_f32 v[88:89], v[88:89], v[100:101] op_sel_hi:[1,0]
	v_pk_mul_f32 v[94:95], v[94:95], v[100:101] op_sel_hi:[1,0]
	v_pk_mul_f32 v[92:93], v[92:93], v[100:101] op_sel_hi:[1,0]
	v_pk_mul_f32 v[90:91], v[90:91], v[100:101] op_sel_hi:[1,0]
	v_max_f32_e32 v88, 0, v88
	v_max_f32_e32 v89, 0, v89
	v_max_f32_e32 v92, 0, v92
	v_max_f32_e32 v93, 0, v93
	v_pk_mul_f32 v[102:103], v[88:89], v[88:89]
	v_max_f32_e32 v88, 0, v94
	v_max_f32_e32 v90, 0, v90
	v_max_f32_e32 v89, 0, v95
	v_max_f32_e32 v91, 0, v91
	v_pk_mul_f32 v[92:93], v[92:93], v[92:93]
	v_pk_mul_f32 v[94:95], v[88:89], v[88:89]
	v_pk_mul_f32 v[104:105], v[90:91], v[90:91]
	v_pk_mul_f32 v[82:83], v[82:83], v[100:101] op_sel_hi:[1,0]
	v_cvt_pk_bf16_f32 v88, v92, v93
	v_cvt_pk_bf16_f32 v89, v94, v95
	v_cvt_pk_bf16_f32 v90, v102, v103
	v_cvt_pk_bf16_f32 v91, v104, v105
	v_pk_mul_f32 v[84:85], v[84:85], v[100:101] op_sel_hi:[1,0]
	v_pk_mul_f32 v[80:81], v[80:81], v[100:101] op_sel_hi:[1,0]
	v_max_f32_e32 v82, 0, v82
	v_max_f32_e32 v83, 0, v83
	global_store_dwordx4 v[98:99], v[88:91], off
	v_pk_mul_f32 v[86:87], v[86:87], v[100:101] op_sel_hi:[1,0]
	v_max_f32_e32 v84, 0, v84
	v_max_f32_e32 v80, 0, v80
	v_max_f32_e32 v85, 0, v85
	v_max_f32_e32 v81, 0, v81
	v_pk_mul_f32 v[90:91], v[82:83], v[82:83]
	v_pk_mul_f32 v[84:85], v[84:85], v[84:85]
	v_pk_mul_f32 v[88:89], v[80:81], v[80:81]
	v_max_f32_e32 v80, 0, v86
	v_max_f32_e32 v81, 0, v87
	v_pk_mul_f32 v[86:87], v[80:81], v[80:81]
	v_cvt_pk_bf16_f32 v80, v84, v85
	v_cvt_pk_bf16_f32 v81, v86, v87
	v_cvt_pk_bf16_f32 v82, v88, v89
	v_cvt_pk_bf16_f32 v83, v90, v91
	global_store_dwordx4 v[98:99], v[80:83], off offset:256
	s_nop 1
	v_mov_b32_e32 v80, v231
	v_pk_mul_f32 v[72:73], v[72:73], v[80:81] op_sel_hi:[1,0]
	v_pk_mul_f32 v[78:79], v[78:79], v[80:81] op_sel_hi:[1,0]
	v_pk_mul_f32 v[76:77], v[76:77], v[80:81] op_sel_hi:[1,0]
	v_pk_mul_f32 v[74:75], v[74:75], v[80:81] op_sel_hi:[1,0]
	v_max_f32_e32 v72, 0, v72
	v_max_f32_e32 v73, 0, v73
	v_lshlrev_b64 v[82:83], 13, v[164:165]
	v_max_f32_e32 v76, 0, v76
	v_max_f32_e32 v77, 0, v77
	v_pk_mul_f32 v[84:85], v[72:73], v[72:73]
	v_max_f32_e32 v72, 0, v78
	v_max_f32_e32 v74, 0, v74
	v_max_f32_e32 v73, 0, v79
	v_max_f32_e32 v75, 0, v75
	v_lshl_add_u64 v[82:83], s[96:97], 0, v[82:83]
	v_pk_mul_f32 v[76:77], v[76:77], v[76:77]
	v_pk_mul_f32 v[78:79], v[72:73], v[72:73]
	v_pk_mul_f32 v[86:87], v[74:75], v[74:75]
	v_pk_mul_f32 v[64:65], v[64:65], v[80:81] op_sel_hi:[1,0]
	v_lshl_add_u64 v[82:83], v[82:83], 0, v[148:149]
	v_cvt_pk_bf16_f32 v72, v76, v77
	v_cvt_pk_bf16_f32 v73, v78, v79
	v_cvt_pk_bf16_f32 v74, v84, v85
	v_cvt_pk_bf16_f32 v75, v86, v87
	v_pk_mul_f32 v[70:71], v[70:71], v[80:81] op_sel_hi:[1,0]
	v_max_f32_e32 v64, 0, v64
	v_max_f32_e32 v65, 0, v65
	global_store_dwordx4 v[82:83], v[72:75], off
	v_pk_mul_f32 v[68:69], v[68:69], v[80:81] op_sel_hi:[1,0]
	v_pk_mul_f32 v[66:67], v[66:67], v[80:81] op_sel_hi:[1,0]
	v_pk_mul_f32 v[72:73], v[64:65], v[64:65]
	v_max_f32_e32 v64, 0, v70
	v_max_f32_e32 v65, 0, v71
	v_max_f32_e32 v68, 0, v68
	v_max_f32_e32 v69, 0, v69
	v_pk_mul_f32 v[68:69], v[68:69], v[68:69]
	v_pk_mul_f32 v[76:77], v[64:65], v[64:65]
	v_cvt_pk_bf16_f32 v64, v68, v69
	s_waitcnt lgkmcnt(0)
; __device__ __forceinline__ unsigned pk2(float lo, float hi) { const f32x2 v = (f32x2){lo, hi}; const bf16x2_t b = __builtin_convertvector(v, bf16x2_t); return __builtin_bit_cast(unsigned, b); }
;     __device__ __forceinline__ void operator()(const f32x4 (&acc)[2][2][4][2], const Unit& u, int wr, int wc, int fr, int fq, const float (&)[8]) const {
;     ...
;             for (int m = 0; m < 4; ++m) { const int row = row0 + ai * HALF + m * 16; const float rs = rsqrtf(ep[ai * 4 + m] * (1.0f / 1024.0f) + EPS);
;                 u16* rowp = O + (size_t)row * ldc + col0;
; #pragma unroll
;                 for (int bj = 0; bj < 2; ++bj) { f32x4 v0 = acc[ai][bj][m][0] * rs, v1 = acc[ai][bj][m][1] * rs;
;                     if (ACT == 1) {
; #pragma unroll
;                         for (int j = 0; j < 4; ++j) { const float a0 = fmaxf(v0[j], 0.f), a1 = fmaxf(v1[j], 0.f); v0[j] = a0 * a0; v1[j] = a1 * a1; } }
;                     u32x4 w; w.x = pk2(v0[0], v0[1]); w.y = pk2(v0[2], v0[3]); w.z = pk2(v1[0], v1[1]); w.w = pk2(v1[2], v1[3]);
;                     *(u32x4*)(rowp + bj * HALF) = w; } }
	v_max_f32_e32 v66, 0, v66
	v_max_f32_e32 v67, 0, v67
	v_pk_mul_f32 v[78:79], v[66:67], v[66:67]
	v_cvt_pk_bf16_f32 v65, v76, v77
	v_cvt_pk_bf16_f32 v66, v72, v73
	v_cvt_pk_bf16_f32 v67, v78, v79
	global_store_dwordx4 v[82:83], v[64:67], off offset:256
	s_waitcnt lgkmcnt(0)
	s_nop 0
	s_nop 0
	s_nop 0
	s_nop 1
	v_lshlrev_b64 v[66:67], 13, v[162:163]
	v_lshl_add_u64 v[66:67], s[96:97], 0, v[66:67]
	v_lshl_add_u64 v[66:67], v[66:67], 0, v[148:149]
	v_mov_b32_e32 v68, v232
	v_pk_mul_f32 v[56:57], v[56:57], v[68:69] op_sel_hi:[1,0]
	v_pk_mul_f32 v[62:63], v[62:63], v[68:69] op_sel_hi:[1,0]
	v_pk_mul_f32 v[60:61], v[60:61], v[68:69] op_sel_hi:[1,0]
	v_pk_mul_f32 v[58:59], v[58:59], v[68:69] op_sel_hi:[1,0]
	v_max_f32_e32 v56, 0, v56
	v_max_f32_e32 v57, 0, v57
	v_max_f32_e32 v60, 0, v60
	v_max_f32_e32 v61, 0, v61
	v_pk_mul_f32 v[70:71], v[56:57], v[56:57]
	v_max_f32_e32 v56, 0, v62
	v_max_f32_e32 v58, 0, v58
	v_max_f32_e32 v57, 0, v63
	v_max_f32_e32 v59, 0, v59
	v_pk_mul_f32 v[60:61], v[60:61], v[60:61]
	v_pk_mul_f32 v[62:63], v[56:57], v[56:57]
	v_pk_mul_f32 v[72:73], v[58:59], v[58:59]
	v_pk_mul_f32 v[50:51], v[50:51], v[68:69] op_sel_hi:[1,0]
	v_cvt_pk_bf16_f32 v56, v60, v61
	v_cvt_pk_bf16_f32 v57, v62, v63
	v_cvt_pk_bf16_f32 v58, v70, v71
	v_cvt_pk_bf16_f32 v59, v72, v73
	v_pk_mul_f32 v[52:53], v[52:53], v[68:69] op_sel_hi:[1,0]
	v_pk_mul_f32 v[48:49], v[48:49], v[68:69] op_sel_hi:[1,0]
	v_max_f32_e32 v50, 0, v50
	v_max_f32_e32 v51, 0, v51
	global_store_dwordx4 v[66:67], v[56:59], off
	v_pk_mul_f32 v[54:55], v[54:55], v[68:69] op_sel_hi:[1,0]
	v_max_f32_e32 v52, 0, v52
	v_max_f32_e32 v48, 0, v48
	v_max_f32_e32 v53, 0, v53
	v_max_f32_e32 v49, 0, v49
	v_pk_mul_f32 v[58:59], v[50:51], v[50:51]
	v_pk_mul_f32 v[52:53], v[52:53], v[52:53]
	v_pk_mul_f32 v[56:57], v[48:49], v[48:49]
	v_max_f32_e32 v48, 0, v54
	v_max_f32_e32 v49, 0, v55
	v_pk_mul_f32 v[54:55], v[48:49], v[48:49]
	v_cvt_pk_bf16_f32 v48, v52, v53
	v_cvt_pk_bf16_f32 v49, v54, v55
	v_cvt_pk_bf16_f32 v50, v56, v57
	v_cvt_pk_bf16_f32 v51, v58, v59
	global_store_dwordx4 v[66:67], v[48:51], off offset:256
	s_nop 1
	v_mov_b32_e32 v48, v233
	v_pk_mul_f32 v[40:41], v[40:41], v[48:49] op_sel_hi:[1,0]
	v_pk_mul_f32 v[46:47], v[46:47], v[48:49] op_sel_hi:[1,0]
	v_pk_mul_f32 v[44:45], v[44:45], v[48:49] op_sel_hi:[1,0]
	v_pk_mul_f32 v[42:43], v[42:43], v[48:49] op_sel_hi:[1,0]
	v_max_f32_e32 v40, 0, v40
	v_max_f32_e32 v41, 0, v41
	v_lshlrev_b64 v[50:51], 13, v[156:157]
	v_max_f32_e32 v44, 0, v44
	v_max_f32_e32 v45, 0, v45
	v_pk_mul_f32 v[52:53], v[40:41], v[40:41]
	v_max_f32_e32 v40, 0, v46
	v_max_f32_e32 v42, 0, v42
	v_max_f32_e32 v41, 0, v47
	v_max_f32_e32 v43, 0, v43
	v_lshl_add_u64 v[50:51], s[96:97], 0, v[50:51]
	v_pk_mul_f32 v[44:45], v[44:45], v[44:45]
	v_pk_mul_f32 v[46:47], v[40:41], v[40:41]
	v_pk_mul_f32 v[54:55], v[42:43], v[42:43]
	v_pk_mul_f32 v[32:33], v[32:33], v[48:49] op_sel_hi:[1,0]
	v_lshl_add_u64 v[50:51], v[50:51], 0, v[148:149]
	v_cvt_pk_bf16_f32 v40, v44, v45
	v_cvt_pk_bf16_f32 v41, v46, v47
	v_cvt_pk_bf16_f32 v42, v52, v53
	v_cvt_pk_bf16_f32 v43, v54, v55
	v_pk_mul_f32 v[38:39], v[38:39], v[48:49] op_sel_hi:[1,0]
	v_max_f32_e32 v32, 0, v32
	v_max_f32_e32 v33, 0, v33
	global_store_dwordx4 v[50:51], v[40:43], off
	v_pk_mul_f32 v[36:37], v[36:37], v[48:49] op_sel_hi:[1,0]
	v_pk_mul_f32 v[34:35], v[34:35], v[48:49] op_sel_hi:[1,0]
	v_pk_mul_f32 v[40:41], v[32:33], v[32:33]
	v_max_f32_e32 v32, 0, v38
	v_max_f32_e32 v33, 0, v39
	v_max_f32_e32 v36, 0, v36
	v_max_f32_e32 v37, 0, v37
	v_pk_mul_f32 v[36:37], v[36:37], v[36:37]
	v_pk_mul_f32 v[44:45], v[32:33], v[32:33]
	v_cvt_pk_bf16_f32 v32, v36, v37
	s_waitcnt lgkmcnt(0)
	v_max_f32_e32 v34, 0, v34
	v_max_f32_e32 v35, 0, v35
	v_pk_mul_f32 v[46:47], v[34:35], v[34:35]
	v_cvt_pk_bf16_f32 v33, v44, v45
	v_cvt_pk_bf16_f32 v34, v40, v41
	v_cvt_pk_bf16_f32 v35, v46, v47
	global_store_dwordx4 v[50:51], v[32:35], off offset:256
	s_waitcnt lgkmcnt(0)
; __device__ __forceinline__ unsigned pk2(float lo, float hi) { const f32x2 v = (f32x2){lo, hi}; const bf16x2_t b = __builtin_convertvector(v, bf16x2_t); return __builtin_bit_cast(unsigned, b); }
; #define PG8_WAIT_V(n) asm volatile("s_waitcnt vmcnt(" #n ")" ::: "memory")
; #define PG8_BAR __builtin_amdgcn_s_barrier()
;     __device__ __forceinline__ void operator()(const f32x4 (&acc)[2][2][4][2], const Unit& u, int wr, int wc, int fr, int fq, const float (&)[8]) const {
;     ...
;             for (int m = 0; m < 4; ++m) { const int row = row0 + ai * HALF + m * 16; const float rs = rsqrtf(ep[ai * 4 + m] * (1.0f / 1024.0f) + EPS);
;                 u16* rowp = O + (size_t)row * ldc + col0;
; #pragma unroll
;                 for (int bj = 0; bj < 2; ++bj) { f32x4 v0 = acc[ai][bj][m][0] * rs, v1 = acc[ai][bj][m][1] * rs;
;                     if (ACT == 1) {
; #pragma unroll
;                         for (int j = 0; j < 4; ++j) { const float a0 = fmaxf(v0[j], 0.f), a1 = fmaxf(v1[j], 0.f); v0[j] = a0 * a0; v1[j] = a1 * a1; } }
;                     u32x4 w; w.x = pk2(v0[0], v0[1]); w.y = pk2(v0[2], v0[3]); w.z = pk2(v1[0], v1[1]); w.w = pk2(v1[2], v1[3]);
;                     *(u32x4*)(rowp + bj * HALF) = w; } }
; template <class Epi>
; __device__ __forceinline__ void gemm_phase(LAS unsigned char* lds, const Gemm g, const StaticOrder& S, const Epi& E) {
;     ...
;         E(acc, cur, wr, wc, fr, fq, epre);
;         if (!has_next) break;
; #pragma unroll
;         for (int a = 0; a < 2; ++a)
; #pragma unroll
;             for (int b = 0; b < 2; ++b)
; #pragma unroll
;                 for (int m = 0; m < 4; ++m)
; #pragma unroll
;                     for (int n = 0; n < 2; ++n) acc[a][b][m][n] = (f32x4){0.f, 0.f, 0.f, 0.f};
;         cur = nxt; cA = nA; cB = nB; ++ui;
;     }
;     PG8_WAIT_V(0);
;     if (wr == 0) PG8_BAR;
;     PG8_BAR;
	s_nop 0
	s_nop 0
	s_nop 0
	s_nop 1
	v_lshlrev_b64 v[34:35], 13, v[150:151]
	v_lshl_add_u64 v[34:35], s[96:97], 0, v[34:35]
	v_lshl_add_u64 v[34:35], v[34:35], 0, v[148:149]
	v_mov_b32_e32 v36, v234
	v_pk_mul_f32 v[24:25], v[24:25], v[36:37] op_sel_hi:[1,0]
	v_pk_mul_f32 v[30:31], v[30:31], v[36:37] op_sel_hi:[1,0]
	v_pk_mul_f32 v[28:29], v[28:29], v[36:37] op_sel_hi:[1,0]
	v_pk_mul_f32 v[26:27], v[26:27], v[36:37] op_sel_hi:[1,0]
	v_max_f32_e32 v24, 0, v24
	v_max_f32_e32 v25, 0, v25
	v_max_f32_e32 v28, 0, v28
	v_max_f32_e32 v29, 0, v29
	v_pk_mul_f32 v[38:39], v[24:25], v[24:25]
	v_max_f32_e32 v24, 0, v30
	v_max_f32_e32 v26, 0, v26
	v_max_f32_e32 v25, 0, v31
	v_max_f32_e32 v27, 0, v27
	v_pk_mul_f32 v[28:29], v[28:29], v[28:29]
	v_pk_mul_f32 v[30:31], v[24:25], v[24:25]
	v_pk_mul_f32 v[40:41], v[26:27], v[26:27]
	v_pk_mul_f32 v[18:19], v[18:19], v[36:37] op_sel_hi:[1,0]
	v_cvt_pk_bf16_f32 v24, v28, v29
	v_cvt_pk_bf16_f32 v25, v30, v31
	v_cvt_pk_bf16_f32 v26, v38, v39
	v_cvt_pk_bf16_f32 v27, v40, v41
	v_pk_mul_f32 v[20:21], v[20:21], v[36:37] op_sel_hi:[1,0]
	v_pk_mul_f32 v[16:17], v[16:17], v[36:37] op_sel_hi:[1,0]
	v_max_f32_e32 v18, 0, v18
	v_max_f32_e32 v19, 0, v19
	global_store_dwordx4 v[34:35], v[24:27], off
	v_pk_mul_f32 v[22:23], v[22:23], v[36:37] op_sel_hi:[1,0]
	v_max_f32_e32 v20, 0, v20
	v_max_f32_e32 v16, 0, v16
	v_max_f32_e32 v21, 0, v21
	v_max_f32_e32 v17, 0, v17
	v_pk_mul_f32 v[26:27], v[18:19], v[18:19]
	v_pk_mul_f32 v[20:21], v[20:21], v[20:21]
	v_pk_mul_f32 v[24:25], v[16:17], v[16:17]
	v_max_f32_e32 v16, 0, v22
	v_max_f32_e32 v17, 0, v23
	v_pk_mul_f32 v[22:23], v[16:17], v[16:17]
	v_cvt_pk_bf16_f32 v16, v20, v21
	v_cvt_pk_bf16_f32 v17, v22, v23
	v_cvt_pk_bf16_f32 v18, v24, v25
	v_cvt_pk_bf16_f32 v19, v26, v27
	global_store_dwordx4 v[34:35], v[16:19], off offset:256
	s_nop 1
	v_mov_b32_e32 v16, v235
	v_pk_mul_f32 v[8:9], v[8:9], v[16:17] op_sel_hi:[1,0]
	v_pk_mul_f32 v[14:15], v[14:15], v[16:17] op_sel_hi:[1,0]
	v_pk_mul_f32 v[12:13], v[12:13], v[16:17] op_sel_hi:[1,0]
	v_pk_mul_f32 v[10:11], v[10:11], v[16:17] op_sel_hi:[1,0]
	v_max_f32_e32 v8, 0, v8
	v_max_f32_e32 v9, 0, v9
	v_lshlrev_b64 v[18:19], 13, v[146:147]
	v_max_f32_e32 v12, 0, v12
	v_max_f32_e32 v13, 0, v13
	v_pk_mul_f32 v[20:21], v[8:9], v[8:9]
	v_max_f32_e32 v8, 0, v14
	v_max_f32_e32 v10, 0, v10
	v_max_f32_e32 v9, 0, v15
	v_max_f32_e32 v11, 0, v11
	v_lshl_add_u64 v[18:19], s[96:97], 0, v[18:19]
	v_pk_mul_f32 v[12:13], v[12:13], v[12:13]
	v_pk_mul_f32 v[14:15], v[8:9], v[8:9]
	v_pk_mul_f32 v[22:23], v[10:11], v[10:11]
	v_pk_mul_f32 v[0:1], v[0:1], v[16:17] op_sel_hi:[1,0]
	v_lshl_add_u64 v[18:19], v[18:19], 0, v[148:149]
	v_cvt_pk_bf16_f32 v8, v12, v13
	v_cvt_pk_bf16_f32 v9, v14, v15
	v_cvt_pk_bf16_f32 v10, v20, v21
	v_cvt_pk_bf16_f32 v11, v22, v23
	v_pk_mul_f32 v[6:7], v[6:7], v[16:17] op_sel_hi:[1,0]
	v_pk_mul_f32 v[4:5], v[4:5], v[16:17] op_sel_hi:[1,0]
	v_pk_mul_f32 v[2:3], v[2:3], v[16:17] op_sel_hi:[1,0]
	v_max_f32_e32 v0, 0, v0
	v_max_f32_e32 v1, 0, v1
	global_store_dwordx4 v[18:19], v[8:11], off
	v_max_f32_e32 v4, 0, v4
	v_max_f32_e32 v5, 0, v5
	v_pk_mul_f32 v[8:9], v[0:1], v[0:1]
	v_max_f32_e32 v0, 0, v6
	v_max_f32_e32 v2, 0, v2
	v_max_f32_e32 v1, 0, v7
	v_max_f32_e32 v3, 0, v3
	v_pk_mul_f32 v[4:5], v[4:5], v[4:5]
	v_pk_mul_f32 v[6:7], v[0:1], v[0:1]
	v_pk_mul_f32 v[10:11], v[2:3], v[2:3]
	v_cvt_pk_bf16_f32 v0, v4, v5
	v_cvt_pk_bf16_f32 v1, v6, v7
	v_cvt_pk_bf16_f32 v2, v8, v9
	v_cvt_pk_bf16_f32 v3, v10, v11
	s_and_b64 vcc, exec, s[0:1]
	global_store_dwordx4 v[18:19], v[0:3], off offset:256
	s_cbranch_vccz .LBB0_1197
	s_waitcnt vmcnt(0)
	s_cmpk_gt_u32 s7, 0xff
	s_cbranch_scc1 .LBB0_1208
	s_barrier

; #define PG8_STAGE(bufoff, gbase, voff) do { _Pragma("unroll") for (int _i = 0; _i < 2; ++_i) \
;         __builtin_amdgcn_global_load_lds((const unsigned*)((const char*)(gbase) + (voff)[_i]), (LAS unsigned*)(lds + (bufoff) + ldsw + _i * 8192), 16, 0, 0); } while (0)
; #define PG8_LDA(dst, b, h) do { _Pragma("unroll") for (int m = 0; m < 4; ++m) _Pragma("unroll") for (int k = 0; k < 2; ++k) dst[m][k] = *(const LAS bf16x8*)(lds + PG8_SA(b, h) + aoff + m * 2048 + k * 1024); } while (0)
; #define PG8_LDB(dst, b, h) do { _Pragma("unroll") for (int n = 0; n < 2; ++n) _Pragma("unroll") for (int k = 0; k < 2; ++k) dst[n][k] = *(const LAS bf16x8*)(lds + PG8_SB(b, h) + boff + n * 2048 + k * 1024); } while (0)
; #define PG8_MMA(ai, bj, At, Bt) do { __builtin_amdgcn_s_setprio(1); _Pragma("unroll") for (int m = 0; m < 4; ++m) _Pragma("unroll") for (int n = 0; n < 2; ++n) _Pragma("unroll") for (int k = 0; k < 2; ++k) \
;         acc[ai][bj][m][n] = __builtin_amdgcn_mfma_f32_16x16x32_bf16(Bt[n][k], At[m][k], acc[ai][bj][m][n], 0, 0, 0); __builtin_amdgcn_s_setprio(0); } while (0)
; #define PG8_WAIT_L(n) asm volatile("s_waitcnt lgkmcnt(" #n ")" ::: "memory")
; #define PG8_BAR __builtin_amdgcn_s_barrier()
; #define PG8_SCHED __builtin_amdgcn_sched_barrier(0)
; template <class Epi>
; __device__ __forceinline__ void gemm_phase(LAS unsigned char* lds, const Gemm g, const StaticOrder& S, const Epi& E) {
;     ...
;             PG8_LDB(B0, 0, 0); PG8_SCHED; PG8_LDA(At, 0, 0); PG8_STAGE(PG8_SA(1, 1), a1 + hstepA, voffA);
;             PG8_WAIT_L(8); PG8_BAR; PG8_WAIT_L(0); PG8_MMA(0, 0, At, B0); PG8_BAR; PG8_SCHED;
;             PG8_LDB(B1, 0, 1); PG8_STAGE(PG8_SB(0, 0), b2, voffB);
;             PG8_BAR; PG8_WAIT_L(0); PG8_MMA(0, 1, At, B1); PG8_BAR;
;             PG8_LDA(At, 0, 1); PG8_STAGE(PG8_SA(0, 0), a2, voffA);
;             PG8_BAR; PG8_WAIT_L(0); PG8_MMA(1, 0, At, B0); PG8_BAR; PG8_SCHED;
.LBB0_1278:
	ds_read_b128 v[128:131], v190
	ds_read_b128 v[132:135], v190 offset:1024
	ds_read_b128 v[136:139], v190 offset:2048
	ds_read_b128 v[140:143], v190 offset:3072
	s_add_u32 s24, s22, 0xfff00080
	s_addc_u32 s25, s23, -1
	s_cmp_eq_u32 s48, 60
	s_cselect_b32 s27, s17, s25
	s_cselect_b32 s26, s44, s24
	s_cselect_b32 s25, s15, s47
	s_cselect_b32 s24, s45, s46
	v_lshl_add_u64 v[186:187], s[22:23], 0, v[162:163]
	s_add_i32 m0, s7, 0xc000
	ds_read_b128 v[144:147], v191
	ds_read_b128 v[148:151], v191 offset:1024
	ds_read_b128 v[170:173], v191 offset:2048
	ds_read_b128 v[174:177], v191 offset:3072
	ds_read_b128 v[178:181], v191 offset:4096
	ds_read_b128 v[182:185], v191 offset:5120
	ds_read_b128 v[194:197], v191 offset:6144
	ds_read_b128 v[198:201], v191 offset:7168
	global_load_lds_dwordx4 v[186:187], off
	v_lshl_add_u64 v[186:187], s[22:23], 0, v[164:165]
	s_add_i32 m0, s7, 0xe000
	s_nop 0
	global_load_lds_dwordx4 v[186:187], off
	s_waitcnt lgkmcnt(8)
	s_barrier
	s_waitcnt lgkmcnt(0)
	v_mfma_f32_16x16x32_bf16 v[124:127], v[128:131], v[144:147], v[124:127]
	v_mfma_f32_16x16x32_bf16 v[120:123], v[136:139], v[144:147], v[120:123]
	v_mfma_f32_16x16x32_bf16 v[108:111], v[128:131], v[170:173], v[108:111]
	v_mfma_f32_16x16x32_bf16 v[104:107], v[136:139], v[170:173], v[104:107]
	v_mfma_f32_16x16x32_bf16 v[92:95], v[128:131], v[178:181], v[92:95]
	v_mfma_f32_16x16x32_bf16 v[88:91], v[136:139], v[178:181], v[88:91]
	v_mfma_f32_16x16x32_bf16 v[76:79], v[128:131], v[194:197], v[76:79]
	v_mfma_f32_16x16x32_bf16 v[72:75], v[136:139], v[194:197], v[72:75]
	v_mfma_f32_16x16x32_bf16 v[124:127], v[132:135], v[148:151], v[124:127]
	v_mfma_f32_16x16x32_bf16 v[120:123], v[140:143], v[148:151], v[120:123]
	v_mfma_f32_16x16x32_bf16 v[108:111], v[132:135], v[174:177], v[108:111]
	v_mfma_f32_16x16x32_bf16 v[104:107], v[140:143], v[174:177], v[104:107]
	v_mfma_f32_16x16x32_bf16 v[92:95], v[132:135], v[182:185], v[92:95]
	v_mfma_f32_16x16x32_bf16 v[88:91], v[140:143], v[182:185], v[88:91]
	v_mfma_f32_16x16x32_bf16 v[76:79], v[132:135], v[198:201], v[76:79]
	v_mfma_f32_16x16x32_bf16 v[72:75], v[140:143], v[198:201], v[72:75]
	s_barrier
	s_add_i32 s49, s42, s31
	v_lshl_add_u64 v[186:187], s[24:25], 0, v[156:157]
	s_mov_b32 m0, s49
	ds_read_b128 v[202:205], v192
	ds_read_b128 v[206:209], v192 offset:1024
	ds_read_b128 v[210:213], v192 offset:2048
	ds_read_b128 v[214:217], v192 offset:3072
	global_load_lds_dwordx4 v[186:187], off
	v_lshl_add_u64 v[218:219], s[24:25], 0, v[160:161]
	s_add_i32 m0, s49, 0x2000
	s_nop 0
	global_load_lds_dwordx4 v[218:219], off
	s_barrier
	s_waitcnt lgkmcnt(0)
	v_mfma_f32_16x16x32_bf16 v[116:119], v[202:205], v[144:147], v[116:119]
	v_mfma_f32_16x16x32_bf16 v[112:115], v[210:213], v[144:147], v[112:115]
	v_mfma_f32_16x16x32_bf16 v[100:103], v[202:205], v[170:173], v[100:103]
	v_mfma_f32_16x16x32_bf16 v[96:99], v[210:213], v[170:173], v[96:99]
	v_mfma_f32_16x16x32_bf16 v[84:87], v[202:205], v[178:181], v[84:87]
	v_mfma_f32_16x16x32_bf16 v[80:83], v[210:213], v[178:181], v[80:83]
	v_mfma_f32_16x16x32_bf16 v[68:71], v[202:205], v[194:197], v[68:71]
	v_mfma_f32_16x16x32_bf16 v[64:67], v[210:213], v[194:197], v[64:67]
	v_mfma_f32_16x16x32_bf16 v[116:119], v[206:209], v[148:151], v[116:119]
	v_mfma_f32_16x16x32_bf16 v[112:115], v[214:217], v[148:151], v[112:115]
	v_mfma_f32_16x16x32_bf16 v[100:103], v[206:209], v[174:177], v[100:103]
	v_mfma_f32_16x16x32_bf16 v[96:99], v[214:217], v[174:177], v[96:99]
	v_mfma_f32_16x16x32_bf16 v[84:87], v[206:209], v[182:185], v[84:87]
	v_mfma_f32_16x16x32_bf16 v[80:83], v[214:217], v[182:185], v[80:83]
	v_mfma_f32_16x16x32_bf16 v[68:71], v[206:209], v[198:201], v[68:71]
	v_mfma_f32_16x16x32_bf16 v[64:67], v[214:217], v[198:201], v[64:67]
	s_mov_b32 m0, s7
	v_lshl_add_u64 v[220:221], s[26:27], 0, v[154:155]
	s_barrier
	ds_read_b128 v[144:147], v191 offset:16384
	ds_read_b128 v[148:151], v191 offset:17408
	ds_read_b128 v[170:173], v191 offset:18432
	ds_read_b128 v[174:177], v191 offset:19456
	ds_read_b128 v[178:181], v191 offset:20480
	ds_read_b128 v[182:185], v191 offset:21504
	ds_read_b128 v[194:197], v191 offset:22528
	ds_read_b128 v[198:201], v191 offset:23552
	global_load_lds_dwordx4 v[220:221], off
	v_lshl_add_u64 v[222:223], s[26:27], 0, v[158:159]
	s_mov_b32 m0, s34
	s_nop 0
	global_load_lds_dwordx4 v[222:223], off
	s_barrier
	s_waitcnt lgkmcnt(0)
	v_mfma_f32_16x16x32_bf16 v[60:63], v[128:131], v[144:147], v[60:63]
	v_mfma_f32_16x16x32_bf16 v[56:59], v[136:139], v[144:147], v[56:59]
	v_mfma_f32_16x16x32_bf16 v[44:47], v[128:131], v[170:173], v[44:47]
	v_mfma_f32_16x16x32_bf16 v[40:43], v[136:139], v[170:173], v[40:43]
	v_mfma_f32_16x16x32_bf16 v[28:31], v[128:131], v[178:181], v[28:31]
	v_mfma_f32_16x16x32_bf16 v[24:27], v[136:139], v[178:181], v[24:27]
	v_mfma_f32_16x16x32_bf16 v[12:15], v[128:131], v[194:197], v[12:15]
	v_mfma_f32_16x16x32_bf16 v[8:11], v[136:139], v[194:197], v[8:11]
	v_mfma_f32_16x16x32_bf16 v[60:63], v[132:135], v[148:151], v[60:63]
	v_mfma_f32_16x16x32_bf16 v[56:59], v[140:143], v[148:151], v[56:59]
	v_mfma_f32_16x16x32_bf16 v[44:47], v[132:135], v[174:177], v[44:47]
	v_mfma_f32_16x16x32_bf16 v[40:43], v[140:143], v[174:177], v[40:43]
	v_mfma_f32_16x16x32_bf16 v[28:31], v[132:135], v[182:185], v[28:31]
	v_mfma_f32_16x16x32_bf16 v[24:27], v[140:143], v[182:185], v[24:27]
	v_mfma_f32_16x16x32_bf16 v[12:15], v[132:135], v[198:201], v[12:15]
	v_mfma_f32_16x16x32_bf16 v[8:11], v[140:143], v[198:201], v[8:11]
	s_barrier
; #define PG8_STAGE(bufoff, gbase, voff) do { _Pragma("unroll") for (int _i = 0; _i < 2; ++_i) \
;         __builtin_amdgcn_global_load_lds((const unsigned*)((const char*)(gbase) + (voff)[_i]), (LAS unsigned*)(lds + (bufoff) + ldsw + _i * 8192), 16, 0, 0); } while (0)
; #define PG8_LDA(dst, b, h) do { _Pragma("unroll") for (int m = 0; m < 4; ++m) _Pragma("unroll") for (int k = 0; k < 2; ++k) dst[m][k] = *(const LAS bf16x8*)(lds + PG8_SA(b, h) + aoff + m * 2048 + k * 1024); } while (0)
; #define PG8_LDB(dst, b, h) do { _Pragma("unroll") for (int n = 0; n < 2; ++n) _Pragma("unroll") for (int k = 0; k < 2; ++k) dst[n][k] = *(const LAS bf16x8*)(lds + PG8_SB(b, h) + boff + n * 2048 + k * 1024); } while (0)
; #define PG8_MMA(ai, bj, At, Bt) do { __builtin_amdgcn_s_setprio(1); _Pragma("unroll") for (int m = 0; m < 4; ++m) _Pragma("unroll") for (int n = 0; n < 2; ++n) _Pragma("unroll") for (int k = 0; k < 2; ++k) \
;         acc[ai][bj][m][n] = __builtin_amdgcn_mfma_f32_16x16x32_bf16(Bt[n][k], At[m][k], acc[ai][bj][m][n], 0, 0, 0); __builtin_amdgcn_s_setprio(0); } while (0)
; #define PG8_WAIT_V(n) asm volatile("s_waitcnt vmcnt(" #n ")" ::: "memory")
; #define PG8_WAIT_L(n) asm volatile("s_waitcnt lgkmcnt(" #n ")" ::: "memory")
; #define PG8_BAR __builtin_amdgcn_s_barrier()
; #define PG8_SCHED __builtin_amdgcn_sched_barrier(0)
; template <class Epi>
; __device__ __forceinline__ void gemm_phase(LAS unsigned char* lds, const Gemm g, const StaticOrder& S, const Epi& E) {
;     ...
;             PG8_STAGE(PG8_SB(0, 1), b2 + hstepB, voffB);
;             PG8_WAIT_V(6); PG8_BAR; PG8_MMA(1, 1, At, B1); PG8_BAR;
;             PG8_LDB(B0, 1, 0); PG8_SCHED; PG8_LDA(At, 1, 0); PG8_STAGE(PG8_SA(0, 1), a2 + hstepA, voffA);
;             PG8_WAIT_L(8); PG8_BAR; PG8_WAIT_L(0); PG8_MMA(0, 0, At, B0); PG8_BAR; PG8_SCHED;
;             PG8_LDB(B1, 1, 1); PG8_STAGE(PG8_SB(1, 0), b3, voffB);
;             PG8_BAR; PG8_WAIT_L(0); PG8_MMA(0, 1, At, B1); PG8_BAR;
;             PG8_LDA(At, 1, 1); PG8_STAGE(PG8_SA(1, 0), a3, voffA);
;             PG8_BAR; PG8_WAIT_L(0); PG8_MMA(1, 0, At, B0); PG8_BAR; PG8_SCHED;
	s_add_u32 s50, s24, 0x100000
	s_addc_u32 s51, s25, 0
	s_add_i32 s49, s43, s31
	v_lshl_add_u64 v[128:129], s[50:51], 0, v[156:157]
	s_mov_b32 m0, s49
	s_nop 0
	global_load_lds_dwordx4 v[128:129], off
	v_lshl_add_u64 v[128:129], s[50:51], 0, v[160:161]
	s_add_i32 m0, s49, 0x2000
	s_nop 0
	global_load_lds_dwordx4 v[128:129], off
	s_waitcnt vmcnt(6)
	s_barrier
	v_mfma_f32_16x16x32_bf16 v[52:55], v[202:205], v[144:147], v[52:55]
	v_mfma_f32_16x16x32_bf16 v[48:51], v[210:213], v[144:147], v[48:51]
	v_mfma_f32_16x16x32_bf16 v[36:39], v[202:205], v[170:173], v[36:39]
	v_mfma_f32_16x16x32_bf16 v[32:35], v[210:213], v[170:173], v[32:35]
	v_mfma_f32_16x16x32_bf16 v[20:23], v[202:205], v[178:181], v[20:23]
	v_mfma_f32_16x16x32_bf16 v[16:19], v[210:213], v[178:181], v[16:19]
	v_mfma_f32_16x16x32_bf16 v[4:7], v[202:205], v[194:197], v[4:7]
	v_mfma_f32_16x16x32_bf16 v[0:3], v[210:213], v[194:197], v[0:3]
	v_mfma_f32_16x16x32_bf16 v[52:55], v[206:209], v[148:151], v[52:55]
	v_mfma_f32_16x16x32_bf16 v[48:51], v[214:217], v[148:151], v[48:51]
	v_mfma_f32_16x16x32_bf16 v[36:39], v[206:209], v[174:177], v[36:39]
	v_mfma_f32_16x16x32_bf16 v[32:35], v[214:217], v[174:177], v[32:35]
	v_mfma_f32_16x16x32_bf16 v[20:23], v[206:209], v[182:185], v[20:23]
	v_mfma_f32_16x16x32_bf16 v[16:19], v[214:217], v[182:185], v[16:19]
	v_mfma_f32_16x16x32_bf16 v[4:7], v[206:209], v[198:201], v[4:7]
	v_mfma_f32_16x16x32_bf16 v[0:3], v[214:217], v[198:201], v[0:3]
	s_add_i32 s49, 0, 0x18000
	v_add_u32_e32 v140, s49, v188
	s_barrier
	ds_read_b128 v[128:131], v140
	ds_read_b128 v[132:135], v140 offset:1024
	ds_read_b128 v[136:139], v140 offset:2048
	ds_read_b128 v[140:143], v140 offset:3072
	s_add_u32 s26, s26, 0x100000
	s_addc_u32 s27, s27, 0
	s_mov_b32 m0, s35
	v_lshl_add_u64 v[202:203], s[26:27], 0, v[154:155]
	ds_read_b128 v[144:147], v191 offset:32768
	ds_read_b128 v[148:151], v191 offset:33792
	ds_read_b128 v[170:173], v191 offset:34816
	ds_read_b128 v[174:177], v191 offset:35840
	ds_read_b128 v[178:181], v191 offset:36864
	ds_read_b128 v[182:185], v191 offset:37888
	ds_read_b128 v[194:197], v191 offset:38912
	ds_read_b128 v[198:201], v191 offset:39936
	global_load_lds_dwordx4 v[202:203], off
	v_lshl_add_u64 v[202:203], s[26:27], 0, v[158:159]
	s_mov_b32 m0, s36
	s_nop 0
	global_load_lds_dwordx4 v[202:203], off
	s_waitcnt lgkmcnt(8)
	s_barrier
	s_waitcnt lgkmcnt(0)
	v_mfma_f32_16x16x32_bf16 v[124:127], v[128:131], v[144:147], v[124:127]
	v_mfma_f32_16x16x32_bf16 v[120:123], v[136:139], v[144:147], v[120:123]
	v_mfma_f32_16x16x32_bf16 v[108:111], v[128:131], v[170:173], v[108:111]
	v_mfma_f32_16x16x32_bf16 v[104:107], v[136:139], v[170:173], v[104:107]
	v_mfma_f32_16x16x32_bf16 v[92:95], v[128:131], v[178:181], v[92:95]
	v_mfma_f32_16x16x32_bf16 v[88:91], v[136:139], v[178:181], v[88:91]
	v_mfma_f32_16x16x32_bf16 v[76:79], v[128:131], v[194:197], v[76:79]
	v_mfma_f32_16x16x32_bf16 v[72:75], v[136:139], v[194:197], v[72:75]
	v_mfma_f32_16x16x32_bf16 v[124:127], v[132:135], v[148:151], v[124:127]
	v_mfma_f32_16x16x32_bf16 v[120:123], v[140:143], v[148:151], v[120:123]
	v_mfma_f32_16x16x32_bf16 v[108:111], v[132:135], v[174:177], v[108:111]
	v_mfma_f32_16x16x32_bf16 v[104:107], v[140:143], v[174:177], v[104:107]
	v_mfma_f32_16x16x32_bf16 v[92:95], v[132:135], v[182:185], v[92:95]
	v_mfma_f32_16x16x32_bf16 v[88:91], v[140:143], v[182:185], v[88:91]
	v_mfma_f32_16x16x32_bf16 v[76:79], v[132:135], v[198:201], v[76:79]
	v_mfma_f32_16x16x32_bf16 v[72:75], v[140:143], v[198:201], v[72:75]
	s_barrier
	s_add_i32 s26, 0, 0x1c000
	s_add_i32 s27, s49, s31
	v_add_u32_e32 v214, s26, v188
	v_lshl_add_u64 v[186:187], v[186:187], 0, s[12:13]
	s_mov_b32 m0, s27
	ds_read_b128 v[202:205], v214
	ds_read_b128 v[206:209], v214 offset:1024
	ds_read_b128 v[210:213], v214 offset:2048
	ds_read_b128 v[214:217], v214 offset:3072
	global_load_lds_dwordx4 v[186:187], off
	v_lshl_add_u64 v[186:187], v[218:219], 0, s[12:13]
	s_add_i32 m0, s27, 0x2000
	s_nop 0
	global_load_lds_dwordx4 v[186:187], off
	s_barrier
	s_waitcnt lgkmcnt(0)
	v_mfma_f32_16x16x32_bf16 v[116:119], v[202:205], v[144:147], v[116:119]
	v_mfma_f32_16x16x32_bf16 v[112:115], v[210:213], v[144:147], v[112:115]
	v_mfma_f32_16x16x32_bf16 v[100:103], v[202:205], v[170:173], v[100:103]
	v_mfma_f32_16x16x32_bf16 v[96:99], v[210:213], v[170:173], v[96:99]
	v_mfma_f32_16x16x32_bf16 v[84:87], v[202:205], v[178:181], v[84:87]
	v_mfma_f32_16x16x32_bf16 v[80:83], v[210:213], v[178:181], v[80:83]
	v_mfma_f32_16x16x32_bf16 v[68:71], v[202:205], v[194:197], v[68:71]
	v_mfma_f32_16x16x32_bf16 v[64:67], v[210:213], v[194:197], v[64:67]
	v_mfma_f32_16x16x32_bf16 v[116:119], v[206:209], v[148:151], v[116:119]
	v_mfma_f32_16x16x32_bf16 v[112:115], v[214:217], v[148:151], v[112:115]
	v_mfma_f32_16x16x32_bf16 v[100:103], v[206:209], v[174:177], v[100:103]
	v_mfma_f32_16x16x32_bf16 v[96:99], v[214:217], v[174:177], v[96:99]
	v_mfma_f32_16x16x32_bf16 v[84:87], v[206:209], v[182:185], v[84:87]
	v_mfma_f32_16x16x32_bf16 v[80:83], v[214:217], v[182:185], v[80:83]
	v_mfma_f32_16x16x32_bf16 v[68:71], v[206:209], v[198:201], v[68:71]
	v_mfma_f32_16x16x32_bf16 v[64:67], v[214:217], v[198:201], v[64:67]
	s_mov_b32 m0, s38
	v_lshl_add_u64 v[186:187], v[220:221], 0, s[12:13]
	s_barrier
	ds_read_b128 v[144:147], v191 offset:49152
	ds_read_b128 v[148:151], v191 offset:50176
	ds_read_b128 v[170:173], v191 offset:51200
	ds_read_b128 v[174:177], v191 offset:52224
	ds_read_b128 v[178:181], v191 offset:53248
	ds_read_b128 v[182:185], v191 offset:54272
	ds_read_b128 v[194:197], v191 offset:55296
	ds_read_b128 v[198:201], v191 offset:56320
	global_load_lds_dwordx4 v[186:187], off
	v_lshl_add_u64 v[186:187], v[222:223], 0, s[12:13]
	s_mov_b32 m0, s39
	s_nop 0
	global_load_lds_dwordx4 v[186:187], off
	s_barrier
; #define PG8_STAGE(bufoff, gbase, voff) do { _Pragma("unroll") for (int _i = 0; _i < 2; ++_i) \
;         __builtin_amdgcn_global_load_lds((const unsigned*)((const char*)(gbase) + (voff)[_i]), (LAS unsigned*)(lds + (bufoff) + ldsw + _i * 8192), 16, 0, 0); } while (0)
; #define PG8_MMA(ai, bj, At, Bt) do { __builtin_amdgcn_s_setprio(1); _Pragma("unroll") for (int m = 0; m < 4; ++m) _Pragma("unroll") for (int n = 0; n < 2; ++n) _Pragma("unroll") for (int k = 0; k < 2; ++k) \
;         acc[ai][bj][m][n] = __builtin_amdgcn_mfma_f32_16x16x32_bf16(Bt[n][k], At[m][k], acc[ai][bj][m][n], 0, 0, 0); __builtin_amdgcn_s_setprio(0); } while (0)
; #define PG8_WAIT_V(n) asm volatile("s_waitcnt vmcnt(" #n ")" ::: "memory")
; #define PG8_WAIT_L(n) asm volatile("s_waitcnt lgkmcnt(" #n ")" ::: "memory")
; #define PG8_BAR __builtin_amdgcn_s_barrier()
; #define PG8_SCHED __builtin_amdgcn_sched_barrier(0)
; template <class Epi>
; __device__ __forceinline__ void gemm_phase(LAS unsigned char* lds, const Gemm g, const StaticOrder& S, const Epi& E) {
;     ...
;             PG8_BAR; PG8_WAIT_L(0); PG8_MMA(1, 0, At, B0); PG8_BAR; PG8_SCHED;
;             PG8_STAGE(PG8_SB(1, 1), b3 + hstepB, voffB);
;             PG8_WAIT_V(6); PG8_BAR; PG8_MMA(1, 1, At, B1); PG8_BAR;
;         }
;         E(acc, cur, wr, wc, fr, fq, epre);
	s_waitcnt lgkmcnt(0)
	v_mfma_f32_16x16x32_bf16 v[60:63], v[128:131], v[144:147], v[60:63]
	v_mfma_f32_16x16x32_bf16 v[56:59], v[136:139], v[144:147], v[56:59]
	v_mfma_f32_16x16x32_bf16 v[44:47], v[128:131], v[170:173], v[44:47]
	v_mfma_f32_16x16x32_bf16 v[40:43], v[136:139], v[170:173], v[40:43]
	v_mfma_f32_16x16x32_bf16 v[28:31], v[128:131], v[178:181], v[28:31]
	v_mfma_f32_16x16x32_bf16 v[24:27], v[136:139], v[178:181], v[24:27]
	v_mfma_f32_16x16x32_bf16 v[12:15], v[128:131], v[194:197], v[12:15]
	v_mfma_f32_16x16x32_bf16 v[8:11], v[136:139], v[194:197], v[8:11]
	v_mfma_f32_16x16x32_bf16 v[60:63], v[132:135], v[148:151], v[60:63]
	v_mfma_f32_16x16x32_bf16 v[56:59], v[140:143], v[148:151], v[56:59]
	v_mfma_f32_16x16x32_bf16 v[44:47], v[132:135], v[174:177], v[44:47]
	v_mfma_f32_16x16x32_bf16 v[40:43], v[140:143], v[174:177], v[40:43]
	v_mfma_f32_16x16x32_bf16 v[28:31], v[132:135], v[182:185], v[28:31]
	v_mfma_f32_16x16x32_bf16 v[24:27], v[140:143], v[182:185], v[24:27]
	v_mfma_f32_16x16x32_bf16 v[12:15], v[132:135], v[198:201], v[12:15]
	v_mfma_f32_16x16x32_bf16 v[8:11], v[140:143], v[198:201], v[8:11]
	s_barrier
	s_add_u32 s24, s24, 0x100080
	s_addc_u32 s25, s25, 0
	s_add_i32 s26, s26, s31
	v_lshl_add_u64 v[128:129], s[24:25], 0, v[156:157]
	s_mov_b32 m0, s26
	s_nop 0
	global_load_lds_dwordx4 v[128:129], off
	v_lshl_add_u64 v[128:129], s[24:25], 0, v[160:161]
	s_add_i32 m0, s26, 0x2000
	s_nop 0
	global_load_lds_dwordx4 v[128:129], off
	s_waitcnt vmcnt(6)
	s_barrier
	v_mfma_f32_16x16x32_bf16 v[52:55], v[202:205], v[144:147], v[52:55]
	v_mfma_f32_16x16x32_bf16 v[48:51], v[210:213], v[144:147], v[48:51]
	v_mfma_f32_16x16x32_bf16 v[36:39], v[202:205], v[170:173], v[36:39]
	v_mfma_f32_16x16x32_bf16 v[32:35], v[210:213], v[170:173], v[32:35]
	v_mfma_f32_16x16x32_bf16 v[20:23], v[202:205], v[178:181], v[20:23]
	v_mfma_f32_16x16x32_bf16 v[16:19], v[210:213], v[178:181], v[16:19]
	v_mfma_f32_16x16x32_bf16 v[4:7], v[202:205], v[194:197], v[4:7]
	v_mfma_f32_16x16x32_bf16 v[0:3], v[210:213], v[194:197], v[0:3]
	v_mfma_f32_16x16x32_bf16 v[52:55], v[206:209], v[148:151], v[52:55]
	v_mfma_f32_16x16x32_bf16 v[48:51], v[214:217], v[148:151], v[48:51]
	v_mfma_f32_16x16x32_bf16 v[36:39], v[206:209], v[174:177], v[36:39]
	v_mfma_f32_16x16x32_bf16 v[32:35], v[214:217], v[174:177], v[32:35]
	v_mfma_f32_16x16x32_bf16 v[20:23], v[206:209], v[182:185], v[20:23]
	v_mfma_f32_16x16x32_bf16 v[16:19], v[214:217], v[182:185], v[16:19]
	v_mfma_f32_16x16x32_bf16 v[4:7], v[206:209], v[198:201], v[4:7]
	v_mfma_f32_16x16x32_bf16 v[0:3], v[214:217], v[198:201], v[0:3]
	s_add_i32 s48, s48, 2
	s_add_u32 s22, s22, 0x100
	s_addc_u32 s23, s23, 0
	s_add_u32 s46, s46, 0x100
	s_addc_u32 s47, s47, 0
	s_cmp_gt_u32 s48, 61
	s_barrier
	s_cbranch_scc0 .LBB0_1278
	s_setprio 0
	s_cmp_ge_u32 s98, 0x100
	s_cbranch_scc0 .Lep7_skip
	s_setprio 1
; __device__ __forceinline__ unsigned pk2(float lo, float hi) { const f32x2 v = (f32x2){lo, hi}; const bf16x2_t b = __builtin_convertvector(v, bf16x2_t); return __builtin_bit_cast(unsigned, b); }
; __device__ __forceinline__ void unpack8(const u32x4 v, float* f) { f[0] = bf_lo(v.x); f[1] = bf_hi(v.x); f[2] = bf_lo(v.y); f[3] = bf_hi(v.y); f[4] = bf_lo(v.z); f[5] = bf_hi(v.z); f[6] = bf_lo(v.w); f[7] = bf_hi(v.w); }
;     __device__ __forceinline__ void operator()(const f32x4 (&acc)[2][2][4][2], const Unit& u, int wr, int wc, int fr, int fq, const float (&)[8]) const {
;         const int row0 = u.pm * BM + wr * 64 + fr, col0 = u.pn * BM + wc * 32 + 8 * fq;
; #pragma unroll
;         for (int ai = 0; ai < 2; ++ai) {
;             u32x4 bv[4][2];
; #pragma unroll
;             for (int m = 0; m < 4; ++m)
; #pragma unroll
;                 for (int bj = 0; bj < 2; ++bj) bv[m][bj] = *(const u32x4*)(xb + (size_t)(row0 + ai * HALF + m * 16) * DM + col0 + bj * HALF);
; #pragma unroll
;             for (int m = 0; m < 4; ++m) { const int row = row0 + ai * HALF + m * 16; const size_t ro = (size_t)row * DM + col0; float s = 0.f;
; #pragma unroll
;                 for (int bj = 0; bj < 2; ++bj) { float b8[8]; unpack8(bv[m][bj], b8);
;                     const f32x4 v0 = (f32x4){b8[0], b8[1], b8[2], b8[3]} + acc[ai][bj][m][0], v1 = (f32x4){b8[4], b8[5], b8[6], b8[7]} + acc[ai][bj][m][1];
;                     s += v0[0] * v0[0] + v0[1] * v0[1] + v0[2] * v0[2] + v0[3] * v0[3] + v1[0] * v1[0] + v1[1] * v1[1] + v1[2] * v1[2] + v1[3] * v1[3];
;                     if (LAST) { *(f32x4*)(out + ro + bj * HALF) = v0; *(f32x4*)(out + ro + bj * HALF + 4) = v1; }
;                     else { u32x4 w; w.x = pk2(v0[0], v0[1]); w.y = pk2(v0[2], v0[3]); w.z = pk2(v1[0], v1[1]); w.w = pk2(v1[2], v1[3]); *(u32x4*)(xb + ro + bj * HALF) = w; } }
;                 s += __shfl_xor(s, 16); s += __shfl_xor(s, 32);
;                 if (fq == 0) ss[(size_t)row * 16 + u.pn * 4 + wc] = s; }
.Lep7_skip:
	v_lshl_or_b32 v170, s6, 8, v189
	v_lshl_add_u32 v172, s8, 8, v153
	v_ashrrev_i32_e32 v171, 31, v170
	v_lshlrev_b64 v[204:205], 1, v[170:171]
	v_ashrrev_i32_e32 v173, 31, v172
	v_lshl_add_u64 v[174:175], s[76:77], 0, v[204:205]
	v_lshlrev_b64 v[206:207], 11, v[172:173]
	v_lshl_add_u64 v[128:129], v[174:175], 0, v[206:207]
	global_load_dwordx4 v[196:199], v[128:129], off
	global_load_dwordx4 v[200:203], v[128:129], off offset:256
	v_or_b32_e32 v184, 16, v172
	v_or_b32_e32 v180, 32, v172
	v_or_b32_e32 v176, 48, v172
	v_ashrrev_i32_e32 v185, 31, v184
	v_ashrrev_i32_e32 v181, 31, v180
	v_ashrrev_i32_e32 v177, 31, v176
	v_lshlrev_b64 v[186:187], 11, v[184:185]
	v_lshlrev_b64 v[182:183], 11, v[180:181]
	v_lshlrev_b64 v[178:179], 11, v[176:177]
	v_lshl_add_u64 v[128:129], v[174:175], 0, v[186:187]
	v_lshl_add_u64 v[130:131], v[174:175], 0, v[182:183]
	v_lshl_add_u64 v[194:195], v[174:175], 0, v[178:179]
	global_load_dwordx4 v[148:151], v[128:129], off
	global_load_dwordx4 v[144:147], v[128:129], off offset:256
	global_load_dwordx4 v[140:143], v[130:131], off
	global_load_dwordx4 v[136:139], v[130:131], off offset:256
	global_load_dwordx4 v[132:135], v[194:195], off
	s_nop 0
	global_load_dwordx4 v[128:131], v[194:195], off offset:256
	v_add_u32_e32 v226, 0x80, v172
	v_ashrrev_i32_e32 v227, 31, v226
	v_lshlrev_b64 v[226:227], 11, v[226:227]
	v_lshl_add_u64 v[226:227], v[174:175], 0, v[226:227]
	global_load_dwordx4 v[216:219], v[226:227], off
	global_load_dwordx4 v[220:223], v[226:227], off offset:256
	v_add_u32_e32 v226, 0x90, v172
	v_ashrrev_i32_e32 v227, 31, v226
	v_lshlrev_b64 v[226:227], 11, v[226:227]
	v_lshl_add_u64 v[226:227], v[174:175], 0, v[226:227]
	global_load_dwordx4 v[228:231], v[226:227], off
	global_load_dwordx4 v[232:235], v[226:227], off offset:256
	v_add_u32_e32 v226, 0xa0, v172
	v_ashrrev_i32_e32 v227, 31, v226
	v_lshlrev_b64 v[226:227], 11, v[226:227]
	v_lshl_add_u64 v[226:227], v[174:175], 0, v[226:227]
	global_load_dwordx4 v[236:239], v[226:227], off
	global_load_dwordx4 v[240:243], v[226:227], off offset:256
	v_add_u32_e32 v226, 0xb0, v172
	v_ashrrev_i32_e32 v227, 31, v226
	v_lshlrev_b64 v[226:227], 11, v[226:227]
	v_lshl_add_u64 v[226:227], v[174:175], 0, v[226:227]
	global_load_dwordx4 v[244:247], v[226:227], off
	global_load_dwordx4 v[252:255], v[226:227], off offset:256
	v_and_b32_e32 v195, 64, v193
	v_xor_b32_e32 v194, 16, v193
	v_add_u32_e32 v195, 64, v195
	v_xor_b32_e32 v208, 32, v193
	v_cmp_lt_i32_e32 vcc, v194, v195
	s_waitcnt vmcnt(15)
	v_and_b32_e32 v209, 0xffff0000, v196
	v_cndmask_b32_e32 v194, v193, v194, vcc
	v_cmp_lt_i32_e32 vcc, v208, v195
	v_lshlrev_b32_e32 v195, 2, v194
	s_waitcnt vmcnt(14)
	v_lshlrev_b32_e32 v212, 16, v200
	v_cndmask_b32_e32 v208, v193, v208, vcc
	v_lshlrev_b32_e32 v194, 2, v208
	v_lshlrev_b32_e32 v208, 16, v196
	v_and_b32_e32 v213, 0xffff0000, v200
	v_lshlrev_b32_e32 v210, 16, v198
	v_and_b32_e32 v211, 0xffff0000, v198
	v_lshlrev_b32_e32 v198, 16, v199
	v_and_b32_e32 v199, 0xffff0000, v199
	v_lshlrev_b32_e32 v200, 16, v201
	v_and_b32_e32 v201, 0xffff0000, v201
	v_lshlrev_b32_e32 v214, 16, v202
	v_and_b32_e32 v215, 0xffff0000, v202
	v_pk_add_f32 v[124:125], v[124:125], v[208:209]
	v_pk_add_f32 v[116:117], v[116:117], v[212:213]
	v_lshlrev_b32_e32 v196, 16, v197
	v_and_b32_e32 v197, 0xffff0000, v197
	v_pk_add_f32 v[122:123], v[122:123], v[198:199]
	v_pk_add_f32 v[118:119], v[118:119], v[200:201]
	v_pk_add_f32 v[198:199], v[112:113], v[214:215]
	v_mul_f32_e32 v200, v125, v125
	v_cvt_pk_bf16_f32 v112, v124, v125
	v_mul_f32_e32 v125, v117, v117
	v_pk_add_f32 v[126:127], v[126:127], v[196:197]
	v_fmac_f32_e32 v200, v124, v124
	v_fmac_f32_e32 v125, v116, v116
	v_fmac_f32_e32 v200, v126, v126
	v_fmac_f32_e32 v125, v118, v118
	v_pk_add_f32 v[120:121], v[120:121], v[210:211]
	v_fmac_f32_e32 v200, v127, v127
	v_fmac_f32_e32 v125, v119, v119
	v_lshlrev_b32_e32 v202, 16, v203
	v_and_b32_e32 v203, 0xffff0000, v203
	v_fmac_f32_e32 v200, v120, v120
	v_fmac_f32_e32 v125, v198, v198
	v_pk_add_f32 v[196:197], v[114:115], v[202:203]
	v_fmac_f32_e32 v200, v121, v121
	v_fmac_f32_e32 v125, v199, v199
	v_fmac_f32_e32 v200, v122, v122
	v_fmac_f32_e32 v125, v196, v196
	v_fmac_f32_e32 v200, v123, v123
	v_fmac_f32_e32 v125, v197, v197
	v_cvt_pk_bf16_f32 v115, v122, v123
	v_add_f32_e32 v122, v200, v125
	ds_bpermute_b32 v123, v195, v122
	v_cvt_pk_bf16_f32 v114, v120, v121
	v_lshl_add_u64 v[120:121], s[76:77], 0, v[206:207]
	v_cvt_pk_bf16_f32 v113, v126, v127
	v_lshl_add_u64 v[120:121], v[120:121], 0, v[204:205]
	global_store_dwordx4 v[120:121], v[112:115], off
	s_waitcnt lgkmcnt(0)
	s_nop 0
	v_add_f32_e32 v112, v122, v123
	ds_bpermute_b32 v113, v194, v112
	v_cvt_pk_bf16_f32 v114, v116, v117
	v_cvt_pk_bf16_f32 v115, v118, v119
	v_cvt_pk_bf16_f32 v116, v198, v199
	v_cvt_pk_bf16_f32 v117, v196, v197
	global_store_dwordx4 v[120:121], v[114:117], off offset:256
	s_and_saveexec_b64 s[22:23], s[0:1]
	s_cbranch_execz .LBB0_1281
	s_waitcnt lgkmcnt(0)
	v_add_f32_e32 v114, v112, v113
	s_lshl_b32 s24, s6, 2
	v_lshlrev_b64 v[112:113], 6, v[172:173]
	s_ashr_i32 s25, s24, 31
	v_lshl_add_u64 v[112:113], s[10:11], 0, v[112:113]
	v_lshl_add_u64 v[112:113], s[24:25], 2, v[112:113]
	s_lshl_b32 s8, s37, 2
	v_lshl_add_u64 v[112:113], v[112:113], 0, s[8:9]
	global_store_dword v[112:113], v114, off
